# v24 (rowstat partials via bf16 dot2) + all 7 hot K-loop labels aligned to 64 bytes (.p2align 6)
# speedup vs baseline: 1.0026x; 1.0007x over previous
; #define PG8_STAGE(bufoff, gbase, voff) do { _Pragma("unroll") for (int _i = 0; _i < 2; ++_i) \
;         __builtin_amdgcn_global_load_lds((const unsigned*)((const char*)(gbase) + (voff)[_i]), (LAS unsigned*)(lds + (bufoff) + ldsw + _i * 8192), 16, 0, 0); } while (0)
; #define PG8_LDA(dst, b, h) do { _Pragma("unroll") for (int m = 0; m < 4; ++m) _Pragma("unroll") for (int k = 0; k < 2; ++k) dst[m][k] = *(const LAS bf16x8*)(lds + PG8_SA(b, h) + aoff + m * 2048 + k * 1024); } while (0)
; #define PG8_LDB(dst, b, h) do { _Pragma("unroll") for (int n = 0; n < 2; ++n) _Pragma("unroll") for (int k = 0; k < 2; ++k) dst[n][k] = *(const LAS bf16x8*)(lds + PG8_SB(b, h) + boff + n * 2048 + k * 1024); } while (0)
; #define PG8_MMA(ai, bj, At, Bt) do { __builtin_amdgcn_s_setprio(1); _Pragma("unroll") for (int m = 0; m < 4; ++m) _Pragma("unroll") for (int n = 0; n < 2; ++n) _Pragma("unroll") for (int k = 0; k < 2; ++k) \
;         acc[ai][bj][m][n] = __builtin_amdgcn_mfma_f32_16x16x32_bf16(Bt[n][k], At[m][k], acc[ai][bj][m][n], 0, 0, 0); __builtin_amdgcn_s_setprio(0); } while (0)
; #define PG8_BAR __builtin_amdgcn_s_barrier()
; template <class Epi, class Sched>
; __device__ __forceinline__ void gemm_phase(LAS unsigned char* lds, const Gemm g, const Sched& S, const Epi& E) {
;     ...
;         const bool has_next = S.next(ui + 1, nxt);
;         const char* nA = has_next ? (const char*)g.A + (size_t)nxt.pm * tstepA : cA; const char* nB = has_next ? (const char*)g.Bt + (size_t)nxt.pn * tstepB : cB;
;         for (int t = 0; t < nt; t += 2) {
;             const bool last = (t == nt - 2);
;             const char* a1 = cA + (size_t)(t + 1) * kstep;
;             const char* a2 = last ? nA : cA + (size_t)(t + 2) * kstep; const char* b2 = last ? nB : cB + (size_t)(t + 2) * kstep;
;             const char* a3 = a2 + kstep; const char* b3 = b2 + kstep;
;             if (last && has_next) S.a_ready(nxt);
;             PG8_LDB(B0, 0, 0); PG8_SCHED; PG8_LDA(At, 0, 0); PG8_STAGE(PG8_SA(1, 1), a1 + hstepA, voffA);
;             PG8_WAIT_L(8); PG8_BAR; PG8_WAIT_L(0); PG8_MMA(0, 0, At, B0); PG8_BAR; PG8_SCHED;
;             PG8_LDB(B1, 0, 1); PG8_STAGE(PG8_SB(0, 0), b2, voffB);
;             PG8_BAR; PG8_WAIT_L(0); PG8_MMA(0, 1, At, B1); PG8_BAR;
;             PG8_LDA(At, 0, 1); PG8_STAGE(PG8_SA(0, 0), a2, voffA);
;             PG8_BAR; PG8_WAIT_L(0); PG8_MMA(1, 0, At, B0); PG8_BAR; PG8_SCHED;
.LBB0_351:
	v_mov_b64_e32 v[4:5], 0xd80
	s_ashr_i32 s15, s14, 31
	v_cmp_lt_i64_e32 vcc, s[4:5], v[4:5]
	s_lshl_b64 s[4:5], s[14:15], 20
	s_add_u32 s18, s88, s4
	s_addc_u32 s19, s89, s5
	s_and_b64 s[4:5], vcc, exec
	s_cselect_b32 s15, s19, s7
	s_cselect_b32 s51, s18, s6
	s_ashr_i32 s1, s0, 31
	s_lshl_b64 s[4:5], s[0:1], 20
	s_add_u32 s4, s28, s4
	s_addc_u32 s5, s29, s5
	s_and_b64 s[24:25], vcc, exec
	s_cselect_b32 s1, s5, s21
	s_cselect_b32 s52, s4, s20
	s_add_u32 s6, s6, 0x80080
	s_addc_u32 s7, s7, 0
	s_add_u32 s53, s20, 0x100
	s_addc_u32 s54, s21, 0
	s_mov_b32 s55, -2
	s_waitcnt lgkmcnt(0)
	s_setprio 0
	s_add_u32 s20, s6, 0xfff80080
	s_addc_u32 s21, s7, -1
	s_add_i32 s56, 0, 0x10000
	v_add_u32_e32 v2, s56, v1
	ds_read_b128 v[144:147], v2
	ds_read_b128 v[150:153], v2 offset:1024
	ds_read_b128 v[154:157], v2 offset:2048
	ds_read_b128 v[158:161], v2 offset:3072
	s_cmp_eq_u32 s55, 28
	s_cselect_b32 s25, s15, s21
	s_cselect_b32 s24, s51, s20
	s_cselect_b32 s21, s1, s54
	s_cselect_b32 s20, s52, s53
	ds_read_b128 v[162:165], v149
	ds_read_b128 v[166:169], v149 offset:1024
	ds_read_b128 v[170:173], v149 offset:2048
	ds_read_b128 v[174:177], v149 offset:3072
	ds_read_b128 v[178:181], v149 offset:4096
	ds_read_b128 v[182:185], v149 offset:5120
	ds_read_b128 v[186:189], v149 offset:6144
	ds_read_b128 v[190:193], v149 offset:7168
	s_add_i32 s58, 0, 0x14000
	v_add_u32_e32 v2, s58, v1
	ds_read_b128 v[194:197], v2
	ds_read_b128 v[198:201], v2 offset:1024
	ds_read_b128 v[202:205], v2 offset:2048
	ds_read_b128 v[206:209], v2 offset:3072
	s_add_i32 m0, s31, 0xc000
	s_nop 0
	global_load_lds_dwordx4 v140, s[6:7]
	s_add_i32 m0, s31, 0xe000
	s_nop 0
	global_load_lds_dwordx4 v142, s[6:7]
	s_waitcnt lgkmcnt(0)
	s_setprio 1
	s_barrier
	v_mfma_f32_16x16x32_bf16 v[128:131], v[144:147], v[162:165], 0
	v_mfma_f32_16x16x32_bf16 v[124:127], v[154:157], v[162:165], 0
	v_mfma_f32_16x16x32_bf16 v[112:115], v[144:147], v[170:173], 0
	v_mfma_f32_16x16x32_bf16 v[108:111], v[154:157], v[170:173], 0
	v_mfma_f32_16x16x32_bf16 v[96:99], v[144:147], v[178:181], 0
	v_mfma_f32_16x16x32_bf16 v[92:95], v[154:157], v[178:181], 0
	v_mfma_f32_16x16x32_bf16 v[80:83], v[144:147], v[186:189], 0
	v_mfma_f32_16x16x32_bf16 v[76:79], v[154:157], v[186:189], 0
	v_mfma_f32_16x16x32_bf16 v[128:131], v[150:153], v[166:169], v[128:131]
	v_mfma_f32_16x16x32_bf16 v[124:127], v[158:161], v[166:169], v[124:127]
	v_mfma_f32_16x16x32_bf16 v[112:115], v[150:153], v[174:177], v[112:115]
	v_mfma_f32_16x16x32_bf16 v[108:111], v[158:161], v[174:177], v[108:111]
	v_mfma_f32_16x16x32_bf16 v[96:99], v[150:153], v[182:185], v[96:99]
	v_mfma_f32_16x16x32_bf16 v[92:95], v[158:161], v[182:185], v[92:95]
	v_mfma_f32_16x16x32_bf16 v[80:83], v[150:153], v[190:193], v[80:83]
	v_mfma_f32_16x16x32_bf16 v[76:79], v[158:161], v[190:193], v[76:79]
	v_mfma_f32_16x16x32_bf16 v[120:123], v[194:197], v[162:165], 0
	v_mfma_f32_16x16x32_bf16 v[116:119], v[202:205], v[162:165], 0
	v_mfma_f32_16x16x32_bf16 v[104:107], v[194:197], v[170:173], 0
	v_mfma_f32_16x16x32_bf16 v[100:103], v[202:205], v[170:173], 0
	v_mfma_f32_16x16x32_bf16 v[88:91], v[194:197], v[178:181], 0
	v_mfma_f32_16x16x32_bf16 v[84:87], v[202:205], v[178:181], 0
	v_mfma_f32_16x16x32_bf16 v[72:75], v[194:197], v[186:189], 0
	v_mfma_f32_16x16x32_bf16 v[68:71], v[202:205], v[186:189], 0
	v_mfma_f32_16x16x32_bf16 v[120:123], v[198:201], v[166:169], v[120:123]
	v_mfma_f32_16x16x32_bf16 v[116:119], v[206:209], v[166:169], v[116:119]
	v_mfma_f32_16x16x32_bf16 v[104:107], v[198:201], v[174:177], v[104:107]
	v_mfma_f32_16x16x32_bf16 v[100:103], v[206:209], v[174:177], v[100:103]
	v_mfma_f32_16x16x32_bf16 v[88:91], v[198:201], v[182:185], v[88:91]
	v_mfma_f32_16x16x32_bf16 v[84:87], v[206:209], v[182:185], v[84:87]
	v_mfma_f32_16x16x32_bf16 v[72:75], v[198:201], v[190:193], v[72:75]
	v_mfma_f32_16x16x32_bf16 v[68:71], v[206:209], v[190:193], v[68:71]
	s_barrier
	s_setprio 0
	ds_read_b128 v[162:165], v149 offset:16384
	ds_read_b128 v[166:169], v149 offset:17408
	ds_read_b128 v[170:173], v149 offset:18432
	ds_read_b128 v[174:177], v149 offset:19456
	ds_read_b128 v[178:181], v149 offset:20480
	ds_read_b128 v[182:185], v149 offset:21504
	ds_read_b128 v[186:189], v149 offset:22528
	ds_read_b128 v[190:193], v149 offset:23552
	s_add_i32 s56, s56, s30
	v_lshl_add_u64 v[210:211], s[20:21], 0, v[136:137]
	s_mov_b32 m0, s56
	s_nop 0
	global_load_lds_dwordx4 v[210:211], off
	v_lshl_add_u64 v[212:213], s[20:21], 0, v[132:133]
	s_add_i32 m0, s56, 0x2000
	s_nop 0
	global_load_lds_dwordx4 v[212:213], off
	s_mov_b32 m0, s31
	v_lshl_add_u64 v[216:217], s[24:25], 0, v[138:139]
	global_load_lds_dwordx4 v[216:217], off
	v_lshl_add_u64 v[218:219], s[24:25], 0, v[134:135]
	s_mov_b32 m0, s35
	s_nop 0
	global_load_lds_dwordx4 v[218:219], off
	s_add_u32 s56, s20, 0x80000
	s_addc_u32 s57, s21, 0
	s_add_i32 s58, s58, s30
	s_mov_b32 m0, s58
	s_nop 0
	global_load_lds_dwordx4 v136, s[56:57]
	s_add_i32 m0, s58, 0x2000
	s_nop 0
	global_load_lds_dwordx4 v132, s[56:57]
	s_waitcnt lgkmcnt(0)
	s_waitcnt vmcnt(6)
	s_setprio 1
	s_barrier
; #define PG8_STAGE(bufoff, gbase, voff) do { _Pragma("unroll") for (int _i = 0; _i < 2; ++_i) \
;         __builtin_amdgcn_global_load_lds((const unsigned*)((const char*)(gbase) + (voff)[_i]), (LAS unsigned*)(lds + (bufoff) + ldsw + _i * 8192), 16, 0, 0); } while (0)
; #define PG8_LDA(dst, b, h) do { _Pragma("unroll") for (int m = 0; m < 4; ++m) _Pragma("unroll") for (int k = 0; k < 2; ++k) dst[m][k] = *(const LAS bf16x8*)(lds + PG8_SA(b, h) + aoff + m * 2048 + k * 1024); } while (0)
; #define PG8_LDB(dst, b, h) do { _Pragma("unroll") for (int n = 0; n < 2; ++n) _Pragma("unroll") for (int k = 0; k < 2; ++k) dst[n][k] = *(const LAS bf16x8*)(lds + PG8_SB(b, h) + boff + n * 2048 + k * 1024); } while (0)
; #define PG8_MMA(ai, bj, At, Bt) do { __builtin_amdgcn_s_setprio(1); _Pragma("unroll") for (int m = 0; m < 4; ++m) _Pragma("unroll") for (int n = 0; n < 2; ++n) _Pragma("unroll") for (int k = 0; k < 2; ++k) \
;         acc[ai][bj][m][n] = __builtin_amdgcn_mfma_f32_16x16x32_bf16(Bt[n][k], At[m][k], acc[ai][bj][m][n], 0, 0, 0); __builtin_amdgcn_s_setprio(0); } while (0)
; #define PG8_WAIT_V(n) asm volatile("s_waitcnt vmcnt(" #n ")" ::: "memory")
; #define PG8_WAIT_L(n) asm volatile("s_waitcnt lgkmcnt(" #n ")" ::: "memory")
; #define PG8_BAR __builtin_amdgcn_s_barrier()
; #define PG8_SCHED __builtin_amdgcn_sched_barrier(0)
; template <class Epi, class Sched>
; __device__ __forceinline__ void gemm_phase(LAS unsigned char* lds, const Gemm g, const Sched& S, const Epi& E) {
;     ...
;             PG8_BAR; PG8_WAIT_L(0); PG8_MMA(1, 0, At, B0); PG8_BAR; PG8_SCHED;
;             PG8_STAGE(PG8_SB(0, 1), b2 + hstepB, voffB);
;             PG8_WAIT_V(6); PG8_BAR; PG8_MMA(1, 1, At, B1); PG8_BAR;
;             PG8_LDB(B0, 1, 0); PG8_SCHED; PG8_LDA(At, 1, 0); PG8_STAGE(PG8_SA(0, 1), a2 + hstepA, voffA);
;             PG8_WAIT_L(8); PG8_BAR; PG8_WAIT_L(0); PG8_MMA(0, 0, At, B0); PG8_BAR; PG8_SCHED;
;             PG8_LDB(B1, 1, 1); PG8_STAGE(PG8_SB(1, 0), b3, voffB);
;             PG8_BAR; PG8_WAIT_L(0); PG8_MMA(0, 1, At, B1); PG8_BAR;
	v_mfma_f32_16x16x32_bf16 v[64:67], v[144:147], v[162:165], 0
	v_mfma_f32_16x16x32_bf16 v[60:63], v[154:157], v[162:165], 0
	v_mfma_f32_16x16x32_bf16 v[48:51], v[144:147], v[170:173], 0
	v_mfma_f32_16x16x32_bf16 v[44:47], v[154:157], v[170:173], 0
	v_mfma_f32_16x16x32_bf16 v[32:35], v[144:147], v[178:181], 0
	v_mfma_f32_16x16x32_bf16 v[28:31], v[154:157], v[178:181], 0
	v_mfma_f32_16x16x32_bf16 v[16:19], v[144:147], v[186:189], 0
	v_mfma_f32_16x16x32_bf16 v[12:15], v[154:157], v[186:189], 0
	v_mfma_f32_16x16x32_bf16 v[64:67], v[150:153], v[166:169], v[64:67]
	v_mfma_f32_16x16x32_bf16 v[60:63], v[158:161], v[166:169], v[60:63]
	v_mfma_f32_16x16x32_bf16 v[48:51], v[150:153], v[174:177], v[48:51]
	v_mfma_f32_16x16x32_bf16 v[44:47], v[158:161], v[174:177], v[44:47]
	v_mfma_f32_16x16x32_bf16 v[32:35], v[150:153], v[182:185], v[32:35]
	v_mfma_f32_16x16x32_bf16 v[28:31], v[158:161], v[182:185], v[28:31]
	v_mfma_f32_16x16x32_bf16 v[16:19], v[150:153], v[190:193], v[16:19]
	v_mfma_f32_16x16x32_bf16 v[12:15], v[158:161], v[190:193], v[12:15]
	v_mfma_f32_16x16x32_bf16 v[56:59], v[194:197], v[162:165], 0
	v_mfma_f32_16x16x32_bf16 v[52:55], v[202:205], v[162:165], 0
	v_mfma_f32_16x16x32_bf16 v[40:43], v[194:197], v[170:173], 0
	v_mfma_f32_16x16x32_bf16 v[36:39], v[202:205], v[170:173], 0
	v_mfma_f32_16x16x32_bf16 v[24:27], v[194:197], v[178:181], 0
	v_mfma_f32_16x16x32_bf16 v[20:23], v[202:205], v[178:181], 0
	v_mfma_f32_16x16x32_bf16 v[8:11], v[194:197], v[186:189], 0
	v_mfma_f32_16x16x32_bf16 v[4:7], v[202:205], v[186:189], 0
	v_mfma_f32_16x16x32_bf16 v[56:59], v[198:201], v[166:169], v[56:59]
	v_mfma_f32_16x16x32_bf16 v[52:55], v[206:209], v[166:169], v[52:55]
	v_mfma_f32_16x16x32_bf16 v[40:43], v[198:201], v[174:177], v[40:43]
	v_mfma_f32_16x16x32_bf16 v[36:39], v[206:209], v[174:177], v[36:39]
	v_mfma_f32_16x16x32_bf16 v[24:27], v[198:201], v[182:185], v[24:27]
	v_mfma_f32_16x16x32_bf16 v[20:23], v[206:209], v[182:185], v[20:23]
	v_mfma_f32_16x16x32_bf16 v[8:11], v[198:201], v[190:193], v[8:11]
	v_mfma_f32_16x16x32_bf16 v[4:7], v[206:209], v[190:193], v[4:7]
	s_barrier
	s_setprio 0
	s_add_i32 s56, 0, 0x18000
	v_add_u32_e32 v2, s56, v1
	ds_read_b128 v[144:147], v2
	ds_read_b128 v[150:153], v2 offset:1024
	ds_read_b128 v[154:157], v2 offset:2048
	ds_read_b128 v[158:161], v2 offset:3072
	s_add_u32 s24, s24, 0x80000
	s_addc_u32 s25, s25, 0
	ds_read_b128 v[162:165], v149 offset:32768
	ds_read_b128 v[166:169], v149 offset:33792
	ds_read_b128 v[170:173], v149 offset:34816
	ds_read_b128 v[174:177], v149 offset:35840
	ds_read_b128 v[178:181], v149 offset:36864
	ds_read_b128 v[182:185], v149 offset:37888
	ds_read_b128 v[186:189], v149 offset:38912
	ds_read_b128 v[190:193], v149 offset:39936
	s_mov_b32 m0, s36
	s_nop 0
	global_load_lds_dwordx4 v138, s[24:25]
	s_mov_b32 m0, s37
	s_nop 0
	global_load_lds_dwordx4 v134, s[24:25]
	s_add_i32 s24, 0, 0x1c000
	v_add_u32_e32 v2, s24, v1
	ds_read_b128 v[194:197], v2
	ds_read_b128 v[198:201], v2 offset:1024
	ds_read_b128 v[202:205], v2 offset:2048
	ds_read_b128 v[206:209], v2 offset:3072
	s_waitcnt lgkmcnt(0)
	s_setprio 1
	s_barrier
	v_mfma_f32_16x16x32_bf16 v[128:131], v[144:147], v[162:165], v[128:131]
	v_mfma_f32_16x16x32_bf16 v[124:127], v[154:157], v[162:165], v[124:127]
	v_mfma_f32_16x16x32_bf16 v[112:115], v[144:147], v[170:173], v[112:115]
	v_mfma_f32_16x16x32_bf16 v[108:111], v[154:157], v[170:173], v[108:111]
	v_mfma_f32_16x16x32_bf16 v[96:99], v[144:147], v[178:181], v[96:99]
	v_mfma_f32_16x16x32_bf16 v[92:95], v[154:157], v[178:181], v[92:95]
	v_mfma_f32_16x16x32_bf16 v[80:83], v[144:147], v[186:189], v[80:83]
	v_mfma_f32_16x16x32_bf16 v[76:79], v[154:157], v[186:189], v[76:79]
	v_mfma_f32_16x16x32_bf16 v[128:131], v[150:153], v[166:169], v[128:131]
	v_mfma_f32_16x16x32_bf16 v[124:127], v[158:161], v[166:169], v[124:127]
	v_mfma_f32_16x16x32_bf16 v[112:115], v[150:153], v[174:177], v[112:115]
	v_mfma_f32_16x16x32_bf16 v[108:111], v[158:161], v[174:177], v[108:111]
	v_mfma_f32_16x16x32_bf16 v[96:99], v[150:153], v[182:185], v[96:99]
	v_mfma_f32_16x16x32_bf16 v[92:95], v[158:161], v[182:185], v[92:95]
	v_mfma_f32_16x16x32_bf16 v[80:83], v[150:153], v[190:193], v[80:83]
	v_mfma_f32_16x16x32_bf16 v[76:79], v[158:161], v[190:193], v[76:79]
	v_mfma_f32_16x16x32_bf16 v[120:123], v[194:197], v[162:165], v[120:123]
	v_mfma_f32_16x16x32_bf16 v[116:119], v[202:205], v[162:165], v[116:119]
	v_mfma_f32_16x16x32_bf16 v[104:107], v[194:197], v[170:173], v[104:107]
	v_mfma_f32_16x16x32_bf16 v[100:103], v[202:205], v[170:173], v[100:103]
	v_mfma_f32_16x16x32_bf16 v[88:91], v[194:197], v[178:181], v[88:91]
	v_mfma_f32_16x16x32_bf16 v[84:87], v[202:205], v[178:181], v[84:87]
	v_mfma_f32_16x16x32_bf16 v[72:75], v[194:197], v[186:189], v[72:75]
	v_mfma_f32_16x16x32_bf16 v[68:71], v[202:205], v[186:189], v[68:71]
	v_mfma_f32_16x16x32_bf16 v[120:123], v[198:201], v[166:169], v[120:123]
	v_mfma_f32_16x16x32_bf16 v[116:119], v[206:209], v[166:169], v[116:119]
	v_mfma_f32_16x16x32_bf16 v[104:107], v[198:201], v[174:177], v[104:107]
	v_mfma_f32_16x16x32_bf16 v[100:103], v[206:209], v[174:177], v[100:103]
	v_mfma_f32_16x16x32_bf16 v[88:91], v[198:201], v[182:185], v[88:91]
	v_mfma_f32_16x16x32_bf16 v[84:87], v[206:209], v[182:185], v[84:87]
	v_mfma_f32_16x16x32_bf16 v[72:75], v[198:201], v[190:193], v[72:75]
	v_mfma_f32_16x16x32_bf16 v[68:71], v[206:209], v[190:193], v[68:71]
	s_barrier
; #define PG8_STAGE(bufoff, gbase, voff) do { _Pragma("unroll") for (int _i = 0; _i < 2; ++_i) \
;         __builtin_amdgcn_global_load_lds((const unsigned*)((const char*)(gbase) + (voff)[_i]), (LAS unsigned*)(lds + (bufoff) + ldsw + _i * 8192), 16, 0, 0); } while (0)
; #define PG8_LDA(dst, b, h) do { _Pragma("unroll") for (int m = 0; m < 4; ++m) _Pragma("unroll") for (int k = 0; k < 2; ++k) dst[m][k] = *(const LAS bf16x8*)(lds + PG8_SA(b, h) + aoff + m * 2048 + k * 1024); } while (0)
; #define PG8_MMA(ai, bj, At, Bt) do { __builtin_amdgcn_s_setprio(1); _Pragma("unroll") for (int m = 0; m < 4; ++m) _Pragma("unroll") for (int n = 0; n < 2; ++n) _Pragma("unroll") for (int k = 0; k < 2; ++k) \
;         acc[ai][bj][m][n] = __builtin_amdgcn_mfma_f32_16x16x32_bf16(Bt[n][k], At[m][k], acc[ai][bj][m][n], 0, 0, 0); __builtin_amdgcn_s_setprio(0); } while (0)
; #define PG8_WAIT_V(n) asm volatile("s_waitcnt vmcnt(" #n ")" ::: "memory")
; #define PG8_WAIT_L(n) asm volatile("s_waitcnt lgkmcnt(" #n ")" ::: "memory")
; #define PG8_BAR __builtin_amdgcn_s_barrier()
; #define PG8_SCHED __builtin_amdgcn_sched_barrier(0)
; template <class Epi, class Sched>
; __device__ __forceinline__ void gemm_phase(LAS unsigned char* lds, const Gemm g, const Sched& S, const Epi& E) {
;     ...
;             PG8_BAR; PG8_WAIT_L(0); PG8_MMA(0, 1, At, B1); PG8_BAR;
;             PG8_LDA(At, 1, 1); PG8_STAGE(PG8_SA(1, 0), a3, voffA);
;             PG8_BAR; PG8_WAIT_L(0); PG8_MMA(1, 0, At, B0); PG8_BAR; PG8_SCHED;
;             PG8_STAGE(PG8_SB(1, 1), b3 + hstepB, voffB);
;             PG8_WAIT_V(6); PG8_BAR; PG8_MMA(1, 1, At, B1); PG8_BAR;
	s_setprio 0
	ds_read_b128 v[162:165], v149 offset:49152
	ds_read_b128 v[166:169], v149 offset:50176
	ds_read_b128 v[170:173], v149 offset:51200
	ds_read_b128 v[174:177], v149 offset:52224
	ds_read_b128 v[178:181], v149 offset:53248
	ds_read_b128 v[182:185], v149 offset:54272
	ds_read_b128 v[186:189], v149 offset:55296
	ds_read_b128 v[190:193], v149 offset:56320
	s_add_i32 s25, s56, s30
	v_lshl_add_u64 v[210:211], v[210:211], 0, s[8:9]
	s_mov_b32 m0, s25
	s_nop 0
	global_load_lds_dwordx4 v[210:211], off
	v_lshl_add_u64 v[210:211], v[212:213], 0, s[8:9]
	s_add_i32 m0, s25, 0x2000
	s_nop 0
	global_load_lds_dwordx4 v[210:211], off
	s_mov_b32 m0, s40
	v_lshl_add_u64 v[210:211], v[216:217], 0, s[8:9]
	global_load_lds_dwordx4 v[210:211], off
	v_lshl_add_u64 v[210:211], v[218:219], 0, s[8:9]
	s_mov_b32 m0, s41
	s_nop 0
	global_load_lds_dwordx4 v[210:211], off
	s_add_u32 s20, s20, 0x80080
	s_addc_u32 s21, s21, 0
	s_add_i32 s24, s24, s30
	s_mov_b32 m0, s24
	s_nop 0
	global_load_lds_dwordx4 v136, s[20:21]
	s_add_i32 m0, s24, 0x2000
	s_nop 0
	global_load_lds_dwordx4 v132, s[20:21]
	s_add_i32 s55, s55, 2
	s_add_u32 s6, s6, 0x100
	s_addc_u32 s7, s7, 0
	s_add_u32 s53, s53, 0x100
	s_addc_u32 s54, s54, 0
	s_cmp_gt_u32 s55, 29
	s_waitcnt lgkmcnt(0)
	s_waitcnt vmcnt(6)
	s_setprio 1
	s_barrier
	v_mfma_f32_16x16x32_bf16 v[64:67], v[144:147], v[162:165], v[64:67]
	v_mfma_f32_16x16x32_bf16 v[60:63], v[154:157], v[162:165], v[60:63]
	v_mfma_f32_16x16x32_bf16 v[48:51], v[144:147], v[170:173], v[48:51]
	v_mfma_f32_16x16x32_bf16 v[44:47], v[154:157], v[170:173], v[44:47]
	v_mfma_f32_16x16x32_bf16 v[32:35], v[144:147], v[178:181], v[32:35]
	v_mfma_f32_16x16x32_bf16 v[28:31], v[154:157], v[178:181], v[28:31]
	v_mfma_f32_16x16x32_bf16 v[16:19], v[144:147], v[186:189], v[16:19]
	v_mfma_f32_16x16x32_bf16 v[12:15], v[154:157], v[186:189], v[12:15]
	v_mfma_f32_16x16x32_bf16 v[64:67], v[150:153], v[166:169], v[64:67]
	v_mfma_f32_16x16x32_bf16 v[60:63], v[158:161], v[166:169], v[60:63]
	v_mfma_f32_16x16x32_bf16 v[48:51], v[150:153], v[174:177], v[48:51]
	v_mfma_f32_16x16x32_bf16 v[44:47], v[158:161], v[174:177], v[44:47]
	v_mfma_f32_16x16x32_bf16 v[32:35], v[150:153], v[182:185], v[32:35]
	v_mfma_f32_16x16x32_bf16 v[28:31], v[158:161], v[182:185], v[28:31]
	v_mfma_f32_16x16x32_bf16 v[16:19], v[150:153], v[190:193], v[16:19]
	v_mfma_f32_16x16x32_bf16 v[12:15], v[158:161], v[190:193], v[12:15]
	v_mfma_f32_16x16x32_bf16 v[56:59], v[194:197], v[162:165], v[56:59]
	v_mfma_f32_16x16x32_bf16 v[52:55], v[202:205], v[162:165], v[52:55]
	v_mfma_f32_16x16x32_bf16 v[40:43], v[194:197], v[170:173], v[40:43]
	v_mfma_f32_16x16x32_bf16 v[36:39], v[202:205], v[170:173], v[36:39]
	v_mfma_f32_16x16x32_bf16 v[24:27], v[194:197], v[178:181], v[24:27]
	v_mfma_f32_16x16x32_bf16 v[20:23], v[202:205], v[178:181], v[20:23]
	v_mfma_f32_16x16x32_bf16 v[8:11], v[194:197], v[186:189], v[8:11]
	v_mfma_f32_16x16x32_bf16 v[4:7], v[202:205], v[186:189], v[4:7]
	v_mfma_f32_16x16x32_bf16 v[56:59], v[198:201], v[166:169], v[56:59]
	v_mfma_f32_16x16x32_bf16 v[52:55], v[206:209], v[166:169], v[52:55]
	v_mfma_f32_16x16x32_bf16 v[40:43], v[198:201], v[174:177], v[40:43]
	v_mfma_f32_16x16x32_bf16 v[36:39], v[206:209], v[174:177], v[36:39]
	v_mfma_f32_16x16x32_bf16 v[24:27], v[198:201], v[182:185], v[24:27]
	v_mfma_f32_16x16x32_bf16 v[20:23], v[206:209], v[182:185], v[20:23]
	v_mfma_f32_16x16x32_bf16 v[8:11], v[198:201], v[190:193], v[8:11]
	v_mfma_f32_16x16x32_bf16 v[4:7], v[206:209], v[190:193], v[4:7]
	s_barrier
	s_setprio 0
	.p2align	6

; #define PG8_STAGE(bufoff, gbase, voff) do { _Pragma("unroll") for (int _i = 0; _i < 2; ++_i) \
;         __builtin_amdgcn_global_load_lds((const unsigned*)((const char*)(gbase) + (voff)[_i]), (LAS unsigned*)(lds + (bufoff) + ldsw + _i * 8192), 16, 0, 0); } while (0)
; #define PG8_LDA(dst, b, h) do { _Pragma("unroll") for (int m = 0; m < 4; ++m) _Pragma("unroll") for (int k = 0; k < 2; ++k) dst[m][k] = *(const LAS bf16x8*)(lds + PG8_SA(b, h) + aoff + m * 2048 + k * 1024); } while (0)
; #define PG8_LDB(dst, b, h) do { _Pragma("unroll") for (int n = 0; n < 2; ++n) _Pragma("unroll") for (int k = 0; k < 2; ++k) dst[n][k] = *(const LAS bf16x8*)(lds + PG8_SB(b, h) + boff + n * 2048 + k * 1024); } while (0)
; #define PG8_MMA(ai, bj, At, Bt) do { __builtin_amdgcn_s_setprio(1); _Pragma("unroll") for (int m = 0; m < 4; ++m) _Pragma("unroll") for (int n = 0; n < 2; ++n) _Pragma("unroll") for (int k = 0; k < 2; ++k) \
;         acc[ai][bj][m][n] = __builtin_amdgcn_mfma_f32_16x16x32_bf16(Bt[n][k], At[m][k], acc[ai][bj][m][n], 0, 0, 0); __builtin_amdgcn_s_setprio(0); } while (0)
; #define PG8_BAR __builtin_amdgcn_s_barrier()
; template <class Epi, class Sched>
; __device__ __forceinline__ void gemm_phase(LAS unsigned char* lds, const Gemm g, const Sched& S, const Epi& E) {
;     ...
;         const bool has_next = S.next(ui + 1, nxt);
;         const char* nA = has_next ? (const char*)g.A + (size_t)nxt.pm * tstepA : cA; const char* nB = has_next ? (const char*)g.Bt + (size_t)nxt.pn * tstepB : cB;
;         for (int t = 0; t < nt; t += 2) {
;             const bool last = (t == nt - 2);
;             const char* a1 = cA + (size_t)(t + 1) * kstep;
;             const char* a2 = last ? nA : cA + (size_t)(t + 2) * kstep; const char* b2 = last ? nB : cB + (size_t)(t + 2) * kstep;
;             const char* a3 = a2 + kstep; const char* b3 = b2 + kstep;
;             if (last && has_next) S.a_ready(nxt);
;             PG8_LDB(B0, 0, 0); PG8_SCHED; PG8_LDA(At, 0, 0); PG8_STAGE(PG8_SA(1, 1), a1 + hstepA, voffA);
;             PG8_WAIT_L(8); PG8_BAR; PG8_WAIT_L(0); PG8_MMA(0, 0, At, B0); PG8_BAR; PG8_SCHED;
;             PG8_LDB(B1, 0, 1); PG8_STAGE(PG8_SB(0, 0), b2, voffB);
;             PG8_BAR; PG8_WAIT_L(0); PG8_MMA(0, 1, At, B1); PG8_BAR;
;             PG8_LDA(At, 0, 1); PG8_STAGE(PG8_SA(0, 0), a2, voffA);
;             PG8_BAR; PG8_WAIT_L(0); PG8_MMA(1, 0, At, B0); PG8_BAR; PG8_SCHED;
.LBB0_490:
	s_ashr_i32 s53, s52, 31
	s_lshl_b64 s[18:19], s[52:53], 20
	s_add_u32 s54, s25, s18
	v_cmp_lt_i64_e64 s[14:15], s[14:15], 16
	s_addc_u32 s55, s28, s19
	s_and_b64 s[18:19], s[14:15], exec
	s_cselect_b32 s18, s55, s5
	s_cselect_b32 s19, s54, s4
	s_ashr_i32 s51, s50, 31
	s_lshl_b64 s[56:57], s[50:51], 21
	s_add_u32 s56, s44, s56
	s_addc_u32 s57, s45, s57
	s_and_b64 s[14:15], s[14:15], exec
	s_cselect_b32 s51, s57, s7
	s_cselect_b32 s53, s56, s6
	s_add_u32 s4, s4, 0x80080
	s_addc_u32 s5, s5, 0
	s_add_u32 s65, s6, 0x100
	s_addc_u32 s66, s7, 0
	s_mov_b32 s67, -2
	s_waitcnt lgkmcnt(0)
	s_setprio 0
	s_add_u32 s6, s4, 0xfff80080
	s_addc_u32 s7, s5, -1
	s_add_i32 s68, 0, 0x10000
	v_add_u32_e32 v154, s68, v1
	ds_read_b128 v[142:145], v154
	ds_read_b128 v[146:149], v154 offset:1024
	ds_read_b128 v[150:153], v154 offset:2048
	ds_read_b128 v[158:161], v154 offset:3072
	s_cmp_eq_u32 s67, 60
	s_cselect_b32 s15, s18, s7
	s_cselect_b32 s14, s19, s6
	s_cselect_b32 s7, s51, s66
	s_cselect_b32 s6, s53, s65
	ds_read_b128 v[162:165], v156
	ds_read_b128 v[166:169], v156 offset:1024
	ds_read_b128 v[170:173], v156 offset:2048
	ds_read_b128 v[174:177], v156 offset:3072
	ds_read_b128 v[178:181], v156 offset:4096
	ds_read_b128 v[182:185], v156 offset:5120
	ds_read_b128 v[186:189], v156 offset:6144
	ds_read_b128 v[190:193], v156 offset:7168
	s_add_i32 s70, 0, 0x14000
	v_add_u32_e32 v154, s70, v1
	ds_read_b128 v[194:197], v154
	ds_read_b128 v[198:201], v154 offset:1024
	ds_read_b128 v[202:205], v154 offset:2048
	ds_read_b128 v[206:209], v154 offset:3072
	s_add_i32 m0, s30, 0xc000
	s_nop 0
	global_load_lds_dwordx4 v138, s[4:5]
	s_add_i32 m0, s30, 0xe000
	s_nop 0
	global_load_lds_dwordx4 v140, s[4:5]
	s_waitcnt lgkmcnt(0)
	s_setprio 1
	s_barrier
	v_mfma_f32_16x16x32_bf16 v[128:131], v[142:145], v[162:165], 0
	v_mfma_f32_16x16x32_bf16 v[124:127], v[150:153], v[162:165], 0
	v_mfma_f32_16x16x32_bf16 v[120:123], v[142:145], v[170:173], 0
	v_mfma_f32_16x16x32_bf16 v[116:119], v[150:153], v[170:173], 0
	v_mfma_f32_16x16x32_bf16 v[112:115], v[142:145], v[178:181], 0
	v_mfma_f32_16x16x32_bf16 v[108:111], v[150:153], v[178:181], 0
	v_mfma_f32_16x16x32_bf16 v[104:107], v[142:145], v[186:189], 0
	v_mfma_f32_16x16x32_bf16 v[100:103], v[150:153], v[186:189], 0
	v_mfma_f32_16x16x32_bf16 v[128:131], v[146:149], v[166:169], v[128:131]
	v_mfma_f32_16x16x32_bf16 v[124:127], v[158:161], v[166:169], v[124:127]
	v_mfma_f32_16x16x32_bf16 v[120:123], v[146:149], v[174:177], v[120:123]
	v_mfma_f32_16x16x32_bf16 v[116:119], v[158:161], v[174:177], v[116:119]
	v_mfma_f32_16x16x32_bf16 v[112:115], v[146:149], v[182:185], v[112:115]
	v_mfma_f32_16x16x32_bf16 v[108:111], v[158:161], v[182:185], v[108:111]
	v_mfma_f32_16x16x32_bf16 v[104:107], v[146:149], v[190:193], v[104:107]
	v_mfma_f32_16x16x32_bf16 v[100:103], v[158:161], v[190:193], v[100:103]
	v_mfma_f32_16x16x32_bf16 v[64:67], v[194:197], v[162:165], 0
	v_mfma_f32_16x16x32_bf16 v[60:63], v[202:205], v[162:165], 0
	v_mfma_f32_16x16x32_bf16 v[56:59], v[194:197], v[170:173], 0
	v_mfma_f32_16x16x32_bf16 v[52:55], v[202:205], v[170:173], 0
	v_mfma_f32_16x16x32_bf16 v[48:51], v[194:197], v[178:181], 0
	v_mfma_f32_16x16x32_bf16 v[44:47], v[202:205], v[178:181], 0
	v_mfma_f32_16x16x32_bf16 v[40:43], v[194:197], v[186:189], 0
	v_mfma_f32_16x16x32_bf16 v[36:39], v[202:205], v[186:189], 0
	v_mfma_f32_16x16x32_bf16 v[64:67], v[198:201], v[166:169], v[64:67]
	v_mfma_f32_16x16x32_bf16 v[60:63], v[206:209], v[166:169], v[60:63]
	v_mfma_f32_16x16x32_bf16 v[56:59], v[198:201], v[174:177], v[56:59]
	v_mfma_f32_16x16x32_bf16 v[52:55], v[206:209], v[174:177], v[52:55]
	v_mfma_f32_16x16x32_bf16 v[48:51], v[198:201], v[182:185], v[48:51]
	v_mfma_f32_16x16x32_bf16 v[44:47], v[206:209], v[182:185], v[44:47]
	v_mfma_f32_16x16x32_bf16 v[40:43], v[198:201], v[190:193], v[40:43]
	v_mfma_f32_16x16x32_bf16 v[36:39], v[206:209], v[190:193], v[36:39]
	s_barrier
	s_setprio 0
	ds_read_b128 v[162:165], v156 offset:16384
	ds_read_b128 v[166:169], v156 offset:17408
	ds_read_b128 v[170:173], v156 offset:18432
	ds_read_b128 v[174:177], v156 offset:19456
	ds_read_b128 v[178:181], v156 offset:20480
	ds_read_b128 v[182:185], v156 offset:21504
	ds_read_b128 v[186:189], v156 offset:22528
	ds_read_b128 v[190:193], v156 offset:23552
	s_add_i32 s68, s68, s29
	v_lshl_add_u64 v[154:155], s[6:7], 0, v[2:3]
	s_mov_b32 m0, s68
	v_lshl_add_u64 v[210:211], s[6:7], 0, v[136:137]
	global_load_lds_dwordx4 v[154:155], off
	s_add_i32 m0, s68, 0x2000
	s_nop 0
	global_load_lds_dwordx4 v[210:211], off
	s_mov_b32 m0, s30
	v_lshl_add_u64 v[212:213], s[14:15], 0, v[132:133]
	global_load_lds_dwordx4 v[212:213], off
	v_lshl_add_u64 v[216:217], s[14:15], 0, v[134:135]
	s_mov_b32 m0, s31
	s_nop 0
	global_load_lds_dwordx4 v[216:217], off
	s_add_u32 s68, s6, 0x100000
	s_addc_u32 s69, s7, 0
	s_add_i32 s70, s70, s29
	s_mov_b32 m0, s70
	s_nop 0
	global_load_lds_dwordx4 v2, s[68:69]
	s_add_i32 m0, s70, 0x2000
	s_nop 0
	global_load_lds_dwordx4 v136, s[68:69]
	s_waitcnt lgkmcnt(0)
	s_waitcnt vmcnt(6)
	s_setprio 1
	s_barrier
; #define PG8_STAGE(bufoff, gbase, voff) do { _Pragma("unroll") for (int _i = 0; _i < 2; ++_i) \
;         __builtin_amdgcn_global_load_lds((const unsigned*)((const char*)(gbase) + (voff)[_i]), (LAS unsigned*)(lds + (bufoff) + ldsw + _i * 8192), 16, 0, 0); } while (0)
; #define PG8_LDA(dst, b, h) do { _Pragma("unroll") for (int m = 0; m < 4; ++m) _Pragma("unroll") for (int k = 0; k < 2; ++k) dst[m][k] = *(const LAS bf16x8*)(lds + PG8_SA(b, h) + aoff + m * 2048 + k * 1024); } while (0)
; #define PG8_LDB(dst, b, h) do { _Pragma("unroll") for (int n = 0; n < 2; ++n) _Pragma("unroll") for (int k = 0; k < 2; ++k) dst[n][k] = *(const LAS bf16x8*)(lds + PG8_SB(b, h) + boff + n * 2048 + k * 1024); } while (0)
; #define PG8_WAIT_V(n) asm volatile("s_waitcnt vmcnt(" #n ")" ::: "memory")
; #define PG8_WAIT_L(n) asm volatile("s_waitcnt lgkmcnt(" #n ")" ::: "memory")
; #define PG8_BAR __builtin_amdgcn_s_barrier()
; #define PG8_SCHED __builtin_amdgcn_sched_barrier(0)
; template <class Epi, class Sched>
; __device__ __forceinline__ void gemm_phase(LAS unsigned char* lds, const Gemm g, const Sched& S, const Epi& E) {
;     ...
;             PG8_LDB(B0, 0, 0); PG8_SCHED; PG8_LDA(At, 0, 0); PG8_STAGE(PG8_SA(1, 1), a1 + hstepA, voffA);
;             PG8_WAIT_L(8); PG8_BAR; PG8_WAIT_L(0); PG8_MMA(0, 0, At, B0); PG8_BAR; PG8_SCHED;
;             PG8_LDB(B1, 0, 1); PG8_STAGE(PG8_SB(0, 0), b2, voffB);
;             PG8_BAR; PG8_WAIT_L(0); PG8_MMA(0, 1, At, B1); PG8_BAR;
;             PG8_LDA(At, 0, 1); PG8_STAGE(PG8_SA(0, 0), a2, voffA);
;             PG8_BAR; PG8_WAIT_L(0); PG8_MMA(1, 0, At, B0); PG8_BAR; PG8_SCHED;
;             PG8_STAGE(PG8_SB(0, 1), b2 + hstepB, voffB);
;             PG8_WAIT_V(6); PG8_BAR; PG8_MMA(1, 1, At, B1); PG8_BAR;
;             PG8_LDB(B0, 1, 0); PG8_SCHED; PG8_LDA(At, 1, 0); PG8_STAGE(PG8_SA(0, 1), a2 + hstepA, voffA);
;             PG8_WAIT_L(8); PG8_BAR; PG8_WAIT_L(0); PG8_MMA(0, 0, At, B0); PG8_BAR; PG8_SCHED;
;             PG8_LDB(B1, 1, 1); PG8_STAGE(PG8_SB(1, 0), b3, voffB);
;             PG8_BAR; PG8_WAIT_L(0); PG8_MMA(0, 1, At, B1); PG8_BAR;
;             PG8_LDA(At, 1, 1); PG8_STAGE(PG8_SA(1, 0), a3, voffA);
;             PG8_BAR; PG8_WAIT_L(0); PG8_MMA(1, 0, At, B0); PG8_BAR; PG8_SCHED;
;             PG8_STAGE(PG8_SB(1, 1), b3 + hstepB, voffB);
;             PG8_WAIT_V(6); PG8_BAR; PG8_MMA(1, 1, At, B1); PG8_BAR;
	v_mfma_f32_16x16x32_bf16 v[96:99], v[142:145], v[162:165], 0
	v_mfma_f32_16x16x32_bf16 v[92:95], v[150:153], v[162:165], 0
	v_mfma_f32_16x16x32_bf16 v[88:91], v[142:145], v[170:173], 0
	v_mfma_f32_16x16x32_bf16 v[84:87], v[150:153], v[170:173], 0
	v_mfma_f32_16x16x32_bf16 v[80:83], v[142:145], v[178:181], 0
	v_mfma_f32_16x16x32_bf16 v[76:79], v[150:153], v[178:181], 0
	v_mfma_f32_16x16x32_bf16 v[72:75], v[142:145], v[186:189], 0
	v_mfma_f32_16x16x32_bf16 v[68:71], v[150:153], v[186:189], 0
	v_mfma_f32_16x16x32_bf16 v[96:99], v[146:149], v[166:169], v[96:99]
	v_mfma_f32_16x16x32_bf16 v[92:95], v[158:161], v[166:169], v[92:95]
	v_mfma_f32_16x16x32_bf16 v[88:91], v[146:149], v[174:177], v[88:91]
	v_mfma_f32_16x16x32_bf16 v[84:87], v[158:161], v[174:177], v[84:87]
	v_mfma_f32_16x16x32_bf16 v[80:83], v[146:149], v[182:185], v[80:83]
	v_mfma_f32_16x16x32_bf16 v[76:79], v[158:161], v[182:185], v[76:79]
	v_mfma_f32_16x16x32_bf16 v[72:75], v[146:149], v[190:193], v[72:75]
	v_mfma_f32_16x16x32_bf16 v[68:71], v[158:161], v[190:193], v[68:71]
	v_mfma_f32_16x16x32_bf16 v[32:35], v[194:197], v[162:165], 0
	v_mfma_f32_16x16x32_bf16 v[28:31], v[202:205], v[162:165], 0
	v_mfma_f32_16x16x32_bf16 v[24:27], v[194:197], v[170:173], 0
	v_mfma_f32_16x16x32_bf16 v[20:23], v[202:205], v[170:173], 0
	v_mfma_f32_16x16x32_bf16 v[16:19], v[194:197], v[178:181], 0
	v_mfma_f32_16x16x32_bf16 v[12:15], v[202:205], v[178:181], 0
	v_mfma_f32_16x16x32_bf16 v[8:11], v[194:197], v[186:189], 0
	v_mfma_f32_16x16x32_bf16 v[4:7], v[202:205], v[186:189], 0
	v_mfma_f32_16x16x32_bf16 v[32:35], v[198:201], v[166:169], v[32:35]
	v_mfma_f32_16x16x32_bf16 v[28:31], v[206:209], v[166:169], v[28:31]
	v_mfma_f32_16x16x32_bf16 v[24:27], v[198:201], v[174:177], v[24:27]
	v_mfma_f32_16x16x32_bf16 v[20:23], v[206:209], v[174:177], v[20:23]
	v_mfma_f32_16x16x32_bf16 v[16:19], v[198:201], v[182:185], v[16:19]
	v_mfma_f32_16x16x32_bf16 v[12:15], v[206:209], v[182:185], v[12:15]
	v_mfma_f32_16x16x32_bf16 v[8:11], v[198:201], v[190:193], v[8:11]
	v_mfma_f32_16x16x32_bf16 v[4:7], v[206:209], v[190:193], v[4:7]
	s_barrier
	s_setprio 0
	s_add_i32 s68, 0, 0x18000
	v_add_u32_e32 v157, s68, v1
	ds_read_b128 v[142:145], v157
	ds_read_b128 v[146:149], v157 offset:1024
	ds_read_b128 v[150:153], v157 offset:2048
	ds_read_b128 v[158:161], v157 offset:3072
	s_add_u32 s14, s14, 0x80000
	s_addc_u32 s15, s15, 0
	ds_read_b128 v[162:165], v156 offset:32768
	ds_read_b128 v[166:169], v156 offset:33792
	ds_read_b128 v[170:173], v156 offset:34816
	ds_read_b128 v[174:177], v156 offset:35840
	ds_read_b128 v[178:181], v156 offset:36864
	ds_read_b128 v[182:185], v156 offset:37888
	ds_read_b128 v[186:189], v156 offset:38912
	ds_read_b128 v[190:193], v156 offset:39936
	s_mov_b32 m0, s38
	s_nop 0
	global_load_lds_dwordx4 v132, s[14:15]
	s_mov_b32 m0, s39
	s_nop 0
	global_load_lds_dwordx4 v134, s[14:15]
	s_add_i32 s14, 0, 0x1c000
	v_add_u32_e32 v157, s14, v1
	ds_read_b128 v[194:197], v157
	ds_read_b128 v[198:201], v157 offset:1024
	ds_read_b128 v[202:205], v157 offset:2048
	ds_read_b128 v[206:209], v157 offset:3072
	s_waitcnt lgkmcnt(0)
	s_setprio 1
	s_barrier
	v_mfma_f32_16x16x32_bf16 v[128:131], v[142:145], v[162:165], v[128:131]
	v_mfma_f32_16x16x32_bf16 v[124:127], v[150:153], v[162:165], v[124:127]
	v_mfma_f32_16x16x32_bf16 v[120:123], v[142:145], v[170:173], v[120:123]
	v_mfma_f32_16x16x32_bf16 v[116:119], v[150:153], v[170:173], v[116:119]
	v_mfma_f32_16x16x32_bf16 v[112:115], v[142:145], v[178:181], v[112:115]
	v_mfma_f32_16x16x32_bf16 v[108:111], v[150:153], v[178:181], v[108:111]
	v_mfma_f32_16x16x32_bf16 v[104:107], v[142:145], v[186:189], v[104:107]
	v_mfma_f32_16x16x32_bf16 v[100:103], v[150:153], v[186:189], v[100:103]
	v_mfma_f32_16x16x32_bf16 v[128:131], v[146:149], v[166:169], v[128:131]
	v_mfma_f32_16x16x32_bf16 v[124:127], v[158:161], v[166:169], v[124:127]
	v_mfma_f32_16x16x32_bf16 v[120:123], v[146:149], v[174:177], v[120:123]
	v_mfma_f32_16x16x32_bf16 v[116:119], v[158:161], v[174:177], v[116:119]
	v_mfma_f32_16x16x32_bf16 v[112:115], v[146:149], v[182:185], v[112:115]
	v_mfma_f32_16x16x32_bf16 v[108:111], v[158:161], v[182:185], v[108:111]
	v_mfma_f32_16x16x32_bf16 v[104:107], v[146:149], v[190:193], v[104:107]
	v_mfma_f32_16x16x32_bf16 v[100:103], v[158:161], v[190:193], v[100:103]
	v_mfma_f32_16x16x32_bf16 v[64:67], v[194:197], v[162:165], v[64:67]
	v_mfma_f32_16x16x32_bf16 v[60:63], v[202:205], v[162:165], v[60:63]
	v_mfma_f32_16x16x32_bf16 v[56:59], v[194:197], v[170:173], v[56:59]
	v_mfma_f32_16x16x32_bf16 v[52:55], v[202:205], v[170:173], v[52:55]
	v_mfma_f32_16x16x32_bf16 v[48:51], v[194:197], v[178:181], v[48:51]
	v_mfma_f32_16x16x32_bf16 v[44:47], v[202:205], v[178:181], v[44:47]
	v_mfma_f32_16x16x32_bf16 v[40:43], v[194:197], v[186:189], v[40:43]
	v_mfma_f32_16x16x32_bf16 v[36:39], v[202:205], v[186:189], v[36:39]
	v_mfma_f32_16x16x32_bf16 v[64:67], v[198:201], v[166:169], v[64:67]
	v_mfma_f32_16x16x32_bf16 v[60:63], v[206:209], v[166:169], v[60:63]
	v_mfma_f32_16x16x32_bf16 v[56:59], v[198:201], v[174:177], v[56:59]
	v_mfma_f32_16x16x32_bf16 v[52:55], v[206:209], v[174:177], v[52:55]
	v_mfma_f32_16x16x32_bf16 v[48:51], v[198:201], v[182:185], v[48:51]
	v_mfma_f32_16x16x32_bf16 v[44:47], v[206:209], v[182:185], v[44:47]
	v_mfma_f32_16x16x32_bf16 v[40:43], v[198:201], v[190:193], v[40:43]
	v_mfma_f32_16x16x32_bf16 v[36:39], v[206:209], v[190:193], v[36:39]
	s_barrier
; #define PG8_STAGE(bufoff, gbase, voff) do { _Pragma("unroll") for (int _i = 0; _i < 2; ++_i) \
;         __builtin_amdgcn_global_load_lds((const unsigned*)((const char*)(gbase) + (voff)[_i]), (LAS unsigned*)(lds + (bufoff) + ldsw + _i * 8192), 16, 0, 0); } while (0)
; #define PG8_LDA(dst, b, h) do { _Pragma("unroll") for (int m = 0; m < 4; ++m) _Pragma("unroll") for (int k = 0; k < 2; ++k) dst[m][k] = *(const LAS bf16x8*)(lds + PG8_SA(b, h) + aoff + m * 2048 + k * 1024); } while (0)
; #define PG8_LDB(dst, b, h) do { _Pragma("unroll") for (int n = 0; n < 2; ++n) _Pragma("unroll") for (int k = 0; k < 2; ++k) dst[n][k] = *(const LAS bf16x8*)(lds + PG8_SB(b, h) + boff + n * 2048 + k * 1024); } while (0)
; #define PG8_MMA(ai, bj, At, Bt) do { __builtin_amdgcn_s_setprio(1); _Pragma("unroll") for (int m = 0; m < 4; ++m) _Pragma("unroll") for (int n = 0; n < 2; ++n) _Pragma("unroll") for (int k = 0; k < 2; ++k) \
;         acc[ai][bj][m][n] = __builtin_amdgcn_mfma_f32_16x16x32_bf16(Bt[n][k], At[m][k], acc[ai][bj][m][n], 0, 0, 0); __builtin_amdgcn_s_setprio(0); } while (0)
; #define PG8_WAIT_V(n) asm volatile("s_waitcnt vmcnt(" #n ")" ::: "memory")
; #define PG8_WAIT_L(n) asm volatile("s_waitcnt lgkmcnt(" #n ")" ::: "memory")
; #define PG8_BAR __builtin_amdgcn_s_barrier()
; #define PG8_SCHED __builtin_amdgcn_sched_barrier(0)
; template <class Epi, class Sched>
; __device__ __forceinline__ void gemm_phase(LAS unsigned char* lds, const Gemm g, const Sched& S, const Epi& E) {
;     ...
;             PG8_STAGE(PG8_SB(0, 1), b2 + hstepB, voffB);
;             PG8_WAIT_V(6); PG8_BAR; PG8_MMA(1, 1, At, B1); PG8_BAR;
;             PG8_LDB(B0, 1, 0); PG8_SCHED; PG8_LDA(At, 1, 0); PG8_STAGE(PG8_SA(0, 1), a2 + hstepA, voffA);
;             PG8_WAIT_L(8); PG8_BAR; PG8_WAIT_L(0); PG8_MMA(0, 0, At, B0); PG8_BAR; PG8_SCHED;
;             PG8_LDB(B1, 1, 1); PG8_STAGE(PG8_SB(1, 0), b3, voffB);
;             PG8_BAR; PG8_WAIT_L(0); PG8_MMA(0, 1, At, B1); PG8_BAR;
;             PG8_LDA(At, 1, 1); PG8_STAGE(PG8_SA(1, 0), a3, voffA);
;             PG8_BAR; PG8_WAIT_L(0); PG8_MMA(1, 0, At, B0); PG8_BAR; PG8_SCHED;
;             PG8_STAGE(PG8_SB(1, 1), b3 + hstepB, voffB);
;             PG8_WAIT_V(6); PG8_BAR; PG8_MMA(1, 1, At, B1); PG8_BAR;
	s_setprio 0
	ds_read_b128 v[162:165], v156 offset:49152
	ds_read_b128 v[166:169], v156 offset:50176
	ds_read_b128 v[170:173], v156 offset:51200
	ds_read_b128 v[174:177], v156 offset:52224
	ds_read_b128 v[178:181], v156 offset:53248
	ds_read_b128 v[182:185], v156 offset:54272
	ds_read_b128 v[186:189], v156 offset:55296
	ds_read_b128 v[190:193], v156 offset:56320
	s_add_i32 s15, s68, s29
	v_lshl_add_u64 v[154:155], v[154:155], 0, s[8:9]
	s_mov_b32 m0, s15
	s_nop 0
	global_load_lds_dwordx4 v[154:155], off
	v_lshl_add_u64 v[154:155], v[210:211], 0, s[8:9]
	s_add_i32 m0, s15, 0x2000
	s_nop 0
	global_load_lds_dwordx4 v[154:155], off
	s_mov_b32 m0, s62
	v_lshl_add_u64 v[154:155], v[212:213], 0, s[8:9]
	global_load_lds_dwordx4 v[154:155], off
	v_lshl_add_u64 v[154:155], v[216:217], 0, s[8:9]
	s_mov_b32 m0, s63
	s_nop 0
	global_load_lds_dwordx4 v[154:155], off
	s_add_u32 s6, s6, 0x100080
	s_addc_u32 s7, s7, 0
	s_add_i32 s14, s14, s29
	s_mov_b32 m0, s14
	s_nop 0
	global_load_lds_dwordx4 v2, s[6:7]
	s_add_i32 m0, s14, 0x2000
	s_nop 0
	global_load_lds_dwordx4 v136, s[6:7]
	s_add_i32 s67, s67, 2
	s_add_u32 s4, s4, 0x100
	s_addc_u32 s5, s5, 0
	s_add_u32 s65, s65, 0x100
	s_addc_u32 s66, s66, 0
	s_cmp_gt_u32 s67, 61
	s_waitcnt lgkmcnt(0)
	s_waitcnt vmcnt(6)
	s_setprio 1
	s_barrier
	v_mfma_f32_16x16x32_bf16 v[96:99], v[142:145], v[162:165], v[96:99]
	v_mfma_f32_16x16x32_bf16 v[92:95], v[150:153], v[162:165], v[92:95]
	v_mfma_f32_16x16x32_bf16 v[88:91], v[142:145], v[170:173], v[88:91]
	v_mfma_f32_16x16x32_bf16 v[84:87], v[150:153], v[170:173], v[84:87]
	v_mfma_f32_16x16x32_bf16 v[80:83], v[142:145], v[178:181], v[80:83]
	v_mfma_f32_16x16x32_bf16 v[76:79], v[150:153], v[178:181], v[76:79]
	v_mfma_f32_16x16x32_bf16 v[72:75], v[142:145], v[186:189], v[72:75]
	v_mfma_f32_16x16x32_bf16 v[68:71], v[150:153], v[186:189], v[68:71]
	v_mfma_f32_16x16x32_bf16 v[96:99], v[146:149], v[166:169], v[96:99]
	v_mfma_f32_16x16x32_bf16 v[92:95], v[158:161], v[166:169], v[92:95]
	v_mfma_f32_16x16x32_bf16 v[88:91], v[146:149], v[174:177], v[88:91]
	v_mfma_f32_16x16x32_bf16 v[84:87], v[158:161], v[174:177], v[84:87]
	v_mfma_f32_16x16x32_bf16 v[80:83], v[146:149], v[182:185], v[80:83]
	v_mfma_f32_16x16x32_bf16 v[76:79], v[158:161], v[182:185], v[76:79]
	v_mfma_f32_16x16x32_bf16 v[72:75], v[146:149], v[190:193], v[72:75]
	v_mfma_f32_16x16x32_bf16 v[68:71], v[158:161], v[190:193], v[68:71]
	v_mfma_f32_16x16x32_bf16 v[32:35], v[194:197], v[162:165], v[32:35]
	v_mfma_f32_16x16x32_bf16 v[28:31], v[202:205], v[162:165], v[28:31]
	v_mfma_f32_16x16x32_bf16 v[24:27], v[194:197], v[170:173], v[24:27]
	v_mfma_f32_16x16x32_bf16 v[20:23], v[202:205], v[170:173], v[20:23]
	v_mfma_f32_16x16x32_bf16 v[16:19], v[194:197], v[178:181], v[16:19]
	v_mfma_f32_16x16x32_bf16 v[12:15], v[202:205], v[178:181], v[12:15]
	v_mfma_f32_16x16x32_bf16 v[8:11], v[194:197], v[186:189], v[8:11]
	v_mfma_f32_16x16x32_bf16 v[4:7], v[202:205], v[186:189], v[4:7]
	v_mfma_f32_16x16x32_bf16 v[32:35], v[198:201], v[166:169], v[32:35]
	v_mfma_f32_16x16x32_bf16 v[28:31], v[206:209], v[166:169], v[28:31]
	v_mfma_f32_16x16x32_bf16 v[24:27], v[198:201], v[174:177], v[24:27]
	v_mfma_f32_16x16x32_bf16 v[20:23], v[206:209], v[174:177], v[20:23]
	v_mfma_f32_16x16x32_bf16 v[16:19], v[198:201], v[182:185], v[16:19]
	v_mfma_f32_16x16x32_bf16 v[12:15], v[206:209], v[182:185], v[12:15]
	v_mfma_f32_16x16x32_bf16 v[8:11], v[198:201], v[190:193], v[8:11]
	v_mfma_f32_16x16x32_bf16 v[4:7], v[206:209], v[190:193], v[4:7]
	s_barrier
	s_setprio 0
	.p2align	6

; #define PG8_STAGE(bufoff, gbase, voff) do { _Pragma("unroll") for (int _i = 0; _i < 2; ++_i) \
;         __builtin_amdgcn_global_load_lds((const unsigned*)((const char*)(gbase) + (voff)[_i]), (LAS unsigned*)(lds + (bufoff) + ldsw + _i * 8192), 16, 0, 0); } while (0)
; #define PG8_LDA(dst, b, h) do { _Pragma("unroll") for (int m = 0; m < 4; ++m) _Pragma("unroll") for (int k = 0; k < 2; ++k) dst[m][k] = *(const LAS bf16x8*)(lds + PG8_SA(b, h) + aoff + m * 2048 + k * 1024); } while (0)
; #define PG8_LDB(dst, b, h) do { _Pragma("unroll") for (int n = 0; n < 2; ++n) _Pragma("unroll") for (int k = 0; k < 2; ++k) dst[n][k] = *(const LAS bf16x8*)(lds + PG8_SB(b, h) + boff + n * 2048 + k * 1024); } while (0)
; #define PG8_WAIT_V(n) asm volatile("s_waitcnt vmcnt(" #n ")" ::: "memory")
; template <class Epi, class Sched>
; __device__ __forceinline__ void gemm_phase(LAS unsigned char* lds, const Gemm g, const Sched& S, const Epi& E) {
;     ...
;         const bool has_next = S.next(ui + 1, nxt);
;         const char* nA = has_next ? (const char*)g.A + (size_t)nxt.pm * tstepA : cA; const char* nB = has_next ? (const char*)g.Bt + (size_t)nxt.pn * tstepB : cB;
;         for (int t = 0; t < nt; t += 2) {
;             const bool last = (t == nt - 2);
;             const char* a1 = cA + (size_t)(t + 1) * kstep;
;             const char* a2 = last ? nA : cA + (size_t)(t + 2) * kstep; const char* b2 = last ? nB : cB + (size_t)(t + 2) * kstep;
;             const char* a3 = a2 + kstep; const char* b3 = b2 + kstep;
;             if (last && has_next) S.a_ready(nxt);
;             PG8_LDB(B0, 0, 0); PG8_SCHED; PG8_LDA(At, 0, 0); PG8_STAGE(PG8_SA(1, 1), a1 + hstepA, voffA);
;             PG8_WAIT_L(8); PG8_BAR; PG8_WAIT_L(0); PG8_MMA(0, 0, At, B0); PG8_BAR; PG8_SCHED;
;             PG8_LDB(B1, 0, 1); PG8_STAGE(PG8_SB(0, 0), b2, voffB);
;             PG8_BAR; PG8_WAIT_L(0); PG8_MMA(0, 1, At, B1); PG8_BAR;
;             PG8_LDA(At, 0, 1); PG8_STAGE(PG8_SA(0, 0), a2, voffA);
;             PG8_BAR; PG8_WAIT_L(0); PG8_MMA(1, 0, At, B0); PG8_BAR; PG8_SCHED;
;             PG8_STAGE(PG8_SB(0, 1), b2 + hstepB, voffB);
;             PG8_WAIT_V(6); PG8_BAR; PG8_MMA(1, 1, At, B1); PG8_BAR;
;             PG8_LDB(B0, 1, 0); PG8_SCHED; PG8_LDA(At, 1, 0); PG8_STAGE(PG8_SA(0, 1), a2 + hstepA, voffA);
;             PG8_WAIT_L(8); PG8_BAR; PG8_WAIT_L(0); PG8_MMA(0, 0, At, B0); PG8_BAR; PG8_SCHED;
.LBB0_965:
	v_mov_b64_e32 v[4:5], 0x400
	s_ashr_i32 s15, s14, 31
	v_cmp_lt_i64_e32 vcc, s[4:5], v[4:5]
	s_lshl_b64 s[4:5], s[14:15], 20
	v_readlane_b32 s48, v252, 0
	v_readlane_b32 s49, v252, 1
	s_add_u32 s4, s48, s4
	s_addc_u32 s5, s49, s5
	s_and_b64 s[18:19], vcc, exec
	s_cselect_b32 s15, s5, s7
	s_cselect_b32 s47, s4, s6
	s_ashr_i32 s1, s0, 31
	s_lshl_b64 s[18:19], s[0:1], 20
	s_add_u32 s18, s28, s18
	s_addc_u32 s19, s29, s19
	s_and_b64 s[24:25], vcc, exec
	s_cselect_b32 s1, s19, s21
	s_cselect_b32 s48, s18, s20
	s_add_u32 s6, s6, 0x80080
	s_addc_u32 s7, s7, 0
	v_readlane_b32 s50, v252, 2
	v_readlane_b32 s51, v252, 3
	s_add_u32 s49, s20, 0x100
	s_addc_u32 s50, s21, 0
	s_mov_b32 s51, -2
	s_waitcnt lgkmcnt(0)
	s_setprio 0
	s_add_u32 s20, s6, 0xfff80080
	s_addc_u32 s21, s7, -1
	s_add_i32 s52, 0, 0x10000
	v_add_u32_e32 v144, s52, v1
	ds_read_b128 v[132:135], v144
	ds_read_b128 v[136:139], v144 offset:1024
	ds_read_b128 v[140:143], v144 offset:2048
	ds_read_b128 v[144:147], v144 offset:3072
	s_cmp_eq_u32 s51, 28
	s_cselect_b32 s25, s15, s21
	s_cselect_b32 s24, s47, s20
	s_cselect_b32 s21, s1, s50
	s_cselect_b32 s20, s48, s49
	ds_read_b128 v[148:151], v224
	ds_read_b128 v[152:155], v224 offset:1024
	ds_read_b128 v[156:159], v224 offset:2048
	ds_read_b128 v[160:163], v224 offset:3072
	ds_read_b128 v[164:167], v224 offset:4096
	ds_read_b128 v[168:171], v224 offset:5120
	ds_read_b128 v[172:175], v224 offset:6144
	ds_read_b128 v[176:179], v224 offset:7168
	s_add_i32 s54, 0, 0x14000
	v_add_u32_e32 v202, s54, v1
	ds_read_b128 v[180:183], v202
	ds_read_b128 v[184:187], v202 offset:1024
	ds_read_b128 v[188:191], v202 offset:2048
	ds_read_b128 v[202:205], v202 offset:3072
	s_add_i32 m0, s31, 0xc000
	s_nop 0
	global_load_lds_dwordx4 v198, s[6:7]
	s_add_i32 m0, s31, 0xe000
	s_nop 0
	global_load_lds_dwordx4 v200, s[6:7]
	s_waitcnt lgkmcnt(0)
	s_setprio 1
	s_barrier
	v_mfma_f32_16x16x32_bf16 v[128:131], v[132:135], v[148:151], 0
	v_mfma_f32_16x16x32_bf16 v[124:127], v[140:143], v[148:151], 0
	v_mfma_f32_16x16x32_bf16 v[112:115], v[132:135], v[156:159], 0
	v_mfma_f32_16x16x32_bf16 v[108:111], v[140:143], v[156:159], 0
	v_mfma_f32_16x16x32_bf16 v[100:103], v[132:135], v[164:167], 0
	v_mfma_f32_16x16x32_bf16 v[92:95], v[140:143], v[164:167], 0
	v_mfma_f32_16x16x32_bf16 v[84:87], v[132:135], v[172:175], 0
	v_mfma_f32_16x16x32_bf16 v[76:79], v[140:143], v[172:175], 0
	v_mfma_f32_16x16x32_bf16 v[128:131], v[136:139], v[152:155], v[128:131]
	v_mfma_f32_16x16x32_bf16 v[124:127], v[144:147], v[152:155], v[124:127]
	v_mfma_f32_16x16x32_bf16 v[112:115], v[136:139], v[160:163], v[112:115]
	v_mfma_f32_16x16x32_bf16 v[108:111], v[144:147], v[160:163], v[108:111]
	v_mfma_f32_16x16x32_bf16 v[100:103], v[136:139], v[168:171], v[100:103]
	v_mfma_f32_16x16x32_bf16 v[92:95], v[144:147], v[168:171], v[92:95]
	v_mfma_f32_16x16x32_bf16 v[84:87], v[136:139], v[176:179], v[84:87]
	v_mfma_f32_16x16x32_bf16 v[76:79], v[144:147], v[176:179], v[76:79]
	v_mfma_f32_16x16x32_bf16 v[120:123], v[180:183], v[148:151], 0
	v_mfma_f32_16x16x32_bf16 v[116:119], v[188:191], v[148:151], 0
	v_mfma_f32_16x16x32_bf16 v[104:107], v[180:183], v[156:159], 0
	v_mfma_f32_16x16x32_bf16 v[96:99], v[188:191], v[156:159], 0
	v_mfma_f32_16x16x32_bf16 v[88:91], v[180:183], v[164:167], 0
	v_mfma_f32_16x16x32_bf16 v[80:83], v[188:191], v[164:167], 0
	v_mfma_f32_16x16x32_bf16 v[72:75], v[180:183], v[172:175], 0
	v_mfma_f32_16x16x32_bf16 v[68:71], v[188:191], v[172:175], 0
	v_mfma_f32_16x16x32_bf16 v[120:123], v[184:187], v[152:155], v[120:123]
	v_mfma_f32_16x16x32_bf16 v[116:119], v[202:205], v[152:155], v[116:119]
	v_mfma_f32_16x16x32_bf16 v[104:107], v[184:187], v[160:163], v[104:107]
	v_mfma_f32_16x16x32_bf16 v[96:99], v[202:205], v[160:163], v[96:99]
	v_mfma_f32_16x16x32_bf16 v[88:91], v[184:187], v[168:171], v[88:91]
	v_mfma_f32_16x16x32_bf16 v[80:83], v[202:205], v[168:171], v[80:83]
	v_mfma_f32_16x16x32_bf16 v[72:75], v[184:187], v[176:179], v[72:75]
	v_mfma_f32_16x16x32_bf16 v[68:71], v[202:205], v[176:179], v[68:71]
	s_barrier
	s_setprio 0
	ds_read_b128 v[148:151], v224 offset:16384
	ds_read_b128 v[152:155], v224 offset:17408
	ds_read_b128 v[156:159], v224 offset:18432
	ds_read_b128 v[160:163], v224 offset:19456
	ds_read_b128 v[164:167], v224 offset:20480
	ds_read_b128 v[168:171], v224 offset:21504
	ds_read_b128 v[172:175], v224 offset:22528
	ds_read_b128 v[176:179], v224 offset:23552
	s_add_i32 s52, s52, s30
	v_lshl_add_u64 v[206:207], s[20:21], 0, v[2:3]
	s_mov_b32 m0, s52
	s_nop 0
	global_load_lds_dwordx4 v[206:207], off
	v_lshl_add_u64 v[208:209], s[20:21], 0, v[192:193]
	s_add_i32 m0, s52, 0x2000
	s_nop 0
	global_load_lds_dwordx4 v[208:209], off
	s_mov_b32 m0, s31
	v_lshl_add_u64 v[210:211], s[24:25], 0, v[196:197]
	global_load_lds_dwordx4 v[210:211], off
	v_lshl_add_u64 v[212:213], s[24:25], 0, v[194:195]
	s_mov_b32 m0, s35
	s_nop 0
	global_load_lds_dwordx4 v[212:213], off
	s_add_u32 s52, s20, 0x80000
	s_addc_u32 s53, s21, 0
	s_add_i32 s54, s54, s30
	s_mov_b32 m0, s54
	s_nop 0
	global_load_lds_dwordx4 v2, s[52:53]
	s_add_i32 m0, s54, 0x2000
	s_nop 0
	global_load_lds_dwordx4 v192, s[52:53]
	s_waitcnt lgkmcnt(0)
	s_waitcnt vmcnt(6)
	s_setprio 1
	s_barrier
; #define PG8_STAGE(bufoff, gbase, voff) do { _Pragma("unroll") for (int _i = 0; _i < 2; ++_i) \
;         __builtin_amdgcn_global_load_lds((const unsigned*)((const char*)(gbase) + (voff)[_i]), (LAS unsigned*)(lds + (bufoff) + ldsw + _i * 8192), 16, 0, 0); } while (0)
; #define PG8_LDA(dst, b, h) do { _Pragma("unroll") for (int m = 0; m < 4; ++m) _Pragma("unroll") for (int k = 0; k < 2; ++k) dst[m][k] = *(const LAS bf16x8*)(lds + PG8_SA(b, h) + aoff + m * 2048 + k * 1024); } while (0)
; #define PG8_LDB(dst, b, h) do { _Pragma("unroll") for (int n = 0; n < 2; ++n) _Pragma("unroll") for (int k = 0; k < 2; ++k) dst[n][k] = *(const LAS bf16x8*)(lds + PG8_SB(b, h) + boff + n * 2048 + k * 1024); } while (0)
; #define PG8_MMA(ai, bj, At, Bt) do { __builtin_amdgcn_s_setprio(1); _Pragma("unroll") for (int m = 0; m < 4; ++m) _Pragma("unroll") for (int n = 0; n < 2; ++n) _Pragma("unroll") for (int k = 0; k < 2; ++k) \
;         acc[ai][bj][m][n] = __builtin_amdgcn_mfma_f32_16x16x32_bf16(Bt[n][k], At[m][k], acc[ai][bj][m][n], 0, 0, 0); __builtin_amdgcn_s_setprio(0); } while (0)
; #define PG8_WAIT_V(n) asm volatile("s_waitcnt vmcnt(" #n ")" ::: "memory")
; #define PG8_WAIT_L(n) asm volatile("s_waitcnt lgkmcnt(" #n ")" ::: "memory")
; #define PG8_BAR __builtin_amdgcn_s_barrier()
; #define PG8_SCHED __builtin_amdgcn_sched_barrier(0)
; template <class Epi, class Sched>
; __device__ __forceinline__ void gemm_phase(LAS unsigned char* lds, const Gemm g, const Sched& S, const Epi& E) {
;     ...
;             PG8_BAR; PG8_WAIT_L(0); PG8_MMA(1, 0, At, B0); PG8_BAR; PG8_SCHED;
;             PG8_STAGE(PG8_SB(0, 1), b2 + hstepB, voffB);
;             PG8_WAIT_V(6); PG8_BAR; PG8_MMA(1, 1, At, B1); PG8_BAR;
;             PG8_LDB(B0, 1, 0); PG8_SCHED; PG8_LDA(At, 1, 0); PG8_STAGE(PG8_SA(0, 1), a2 + hstepA, voffA);
;             PG8_WAIT_L(8); PG8_BAR; PG8_WAIT_L(0); PG8_MMA(0, 0, At, B0); PG8_BAR; PG8_SCHED;
;             PG8_LDB(B1, 1, 1); PG8_STAGE(PG8_SB(1, 0), b3, voffB);
;             PG8_BAR; PG8_WAIT_L(0); PG8_MMA(0, 1, At, B1); PG8_BAR;
;             PG8_LDA(At, 1, 1); PG8_STAGE(PG8_SA(1, 0), a3, voffA);
;             PG8_BAR; PG8_WAIT_L(0); PG8_MMA(1, 0, At, B0); PG8_BAR; PG8_SCHED;
	v_mfma_f32_16x16x32_bf16 v[64:67], v[132:135], v[148:151], 0
	v_mfma_f32_16x16x32_bf16 v[60:63], v[140:143], v[148:151], 0
	v_mfma_f32_16x16x32_bf16 v[52:55], v[132:135], v[156:159], 0
	v_mfma_f32_16x16x32_bf16 v[44:47], v[140:143], v[156:159], 0
	v_mfma_f32_16x16x32_bf16 v[36:39], v[132:135], v[164:167], 0
	v_mfma_f32_16x16x32_bf16 v[28:31], v[140:143], v[164:167], 0
	v_mfma_f32_16x16x32_bf16 v[20:23], v[132:135], v[172:175], 0
	v_mfma_f32_16x16x32_bf16 v[12:15], v[140:143], v[172:175], 0
	v_mfma_f32_16x16x32_bf16 v[64:67], v[136:139], v[152:155], v[64:67]
	v_mfma_f32_16x16x32_bf16 v[60:63], v[144:147], v[152:155], v[60:63]
	v_mfma_f32_16x16x32_bf16 v[52:55], v[136:139], v[160:163], v[52:55]
	v_mfma_f32_16x16x32_bf16 v[44:47], v[144:147], v[160:163], v[44:47]
	v_mfma_f32_16x16x32_bf16 v[36:39], v[136:139], v[168:171], v[36:39]
	v_mfma_f32_16x16x32_bf16 v[28:31], v[144:147], v[168:171], v[28:31]
	v_mfma_f32_16x16x32_bf16 v[20:23], v[136:139], v[176:179], v[20:23]
	v_mfma_f32_16x16x32_bf16 v[12:15], v[144:147], v[176:179], v[12:15]
	v_mfma_f32_16x16x32_bf16 v[56:59], v[180:183], v[148:151], 0
	v_mfma_f32_16x16x32_bf16 v[48:51], v[188:191], v[148:151], 0
	v_mfma_f32_16x16x32_bf16 v[40:43], v[180:183], v[156:159], 0
	v_mfma_f32_16x16x32_bf16 v[32:35], v[188:191], v[156:159], 0
	v_mfma_f32_16x16x32_bf16 v[24:27], v[180:183], v[164:167], 0
	v_mfma_f32_16x16x32_bf16 v[16:19], v[188:191], v[164:167], 0
	v_mfma_f32_16x16x32_bf16 v[8:11], v[180:183], v[172:175], 0
	v_mfma_f32_16x16x32_bf16 v[4:7], v[188:191], v[172:175], 0
	v_mfma_f32_16x16x32_bf16 v[56:59], v[184:187], v[152:155], v[56:59]
	v_mfma_f32_16x16x32_bf16 v[48:51], v[202:205], v[152:155], v[48:51]
	v_mfma_f32_16x16x32_bf16 v[40:43], v[184:187], v[160:163], v[40:43]
	v_mfma_f32_16x16x32_bf16 v[32:35], v[202:205], v[160:163], v[32:35]
	v_mfma_f32_16x16x32_bf16 v[24:27], v[184:187], v[168:171], v[24:27]
	v_mfma_f32_16x16x32_bf16 v[16:19], v[202:205], v[168:171], v[16:19]
	v_mfma_f32_16x16x32_bf16 v[8:11], v[184:187], v[176:179], v[8:11]
	v_mfma_f32_16x16x32_bf16 v[4:7], v[202:205], v[176:179], v[4:7]
	s_barrier
	s_setprio 0
	s_add_i32 s52, 0, 0x18000
	v_add_u32_e32 v144, s52, v1
	ds_read_b128 v[132:135], v144
	ds_read_b128 v[136:139], v144 offset:1024
	ds_read_b128 v[140:143], v144 offset:2048
	ds_read_b128 v[144:147], v144 offset:3072
	s_add_u32 s24, s24, 0x80000
	s_addc_u32 s25, s25, 0
	ds_read_b128 v[148:151], v224 offset:32768
	ds_read_b128 v[152:155], v224 offset:33792
	ds_read_b128 v[156:159], v224 offset:34816
	ds_read_b128 v[160:163], v224 offset:35840
	ds_read_b128 v[164:167], v224 offset:36864
	ds_read_b128 v[168:171], v224 offset:37888
	ds_read_b128 v[172:175], v224 offset:38912
	ds_read_b128 v[176:179], v224 offset:39936
	s_mov_b32 m0, s36
	s_nop 0
	global_load_lds_dwordx4 v196, s[24:25]
	s_mov_b32 m0, s37
	s_nop 0
	global_load_lds_dwordx4 v194, s[24:25]
	s_add_i32 s24, 0, 0x1c000
	v_add_u32_e32 v202, s24, v1
	ds_read_b128 v[180:183], v202
	ds_read_b128 v[184:187], v202 offset:1024
	ds_read_b128 v[188:191], v202 offset:2048
	ds_read_b128 v[202:205], v202 offset:3072
	s_waitcnt lgkmcnt(0)
	s_setprio 1
	s_barrier
	v_mfma_f32_16x16x32_bf16 v[128:131], v[132:135], v[148:151], v[128:131]
	v_mfma_f32_16x16x32_bf16 v[124:127], v[140:143], v[148:151], v[124:127]
	v_mfma_f32_16x16x32_bf16 v[112:115], v[132:135], v[156:159], v[112:115]
	v_mfma_f32_16x16x32_bf16 v[108:111], v[140:143], v[156:159], v[108:111]
	v_mfma_f32_16x16x32_bf16 v[100:103], v[132:135], v[164:167], v[100:103]
	v_mfma_f32_16x16x32_bf16 v[92:95], v[140:143], v[164:167], v[92:95]
	v_mfma_f32_16x16x32_bf16 v[84:87], v[132:135], v[172:175], v[84:87]
	v_mfma_f32_16x16x32_bf16 v[76:79], v[140:143], v[172:175], v[76:79]
	v_mfma_f32_16x16x32_bf16 v[128:131], v[136:139], v[152:155], v[128:131]
	v_mfma_f32_16x16x32_bf16 v[124:127], v[144:147], v[152:155], v[124:127]
	v_mfma_f32_16x16x32_bf16 v[112:115], v[136:139], v[160:163], v[112:115]
	v_mfma_f32_16x16x32_bf16 v[108:111], v[144:147], v[160:163], v[108:111]
	v_mfma_f32_16x16x32_bf16 v[100:103], v[136:139], v[168:171], v[100:103]
	v_mfma_f32_16x16x32_bf16 v[92:95], v[144:147], v[168:171], v[92:95]
	v_mfma_f32_16x16x32_bf16 v[84:87], v[136:139], v[176:179], v[84:87]
	v_mfma_f32_16x16x32_bf16 v[76:79], v[144:147], v[176:179], v[76:79]
	v_mfma_f32_16x16x32_bf16 v[120:123], v[180:183], v[148:151], v[120:123]
	v_mfma_f32_16x16x32_bf16 v[116:119], v[188:191], v[148:151], v[116:119]
	v_mfma_f32_16x16x32_bf16 v[104:107], v[180:183], v[156:159], v[104:107]
	v_mfma_f32_16x16x32_bf16 v[96:99], v[188:191], v[156:159], v[96:99]
	v_mfma_f32_16x16x32_bf16 v[88:91], v[180:183], v[164:167], v[88:91]
	v_mfma_f32_16x16x32_bf16 v[80:83], v[188:191], v[164:167], v[80:83]
	v_mfma_f32_16x16x32_bf16 v[72:75], v[180:183], v[172:175], v[72:75]
	v_mfma_f32_16x16x32_bf16 v[68:71], v[188:191], v[172:175], v[68:71]
	v_mfma_f32_16x16x32_bf16 v[120:123], v[184:187], v[152:155], v[120:123]
	v_mfma_f32_16x16x32_bf16 v[116:119], v[202:205], v[152:155], v[116:119]
	v_mfma_f32_16x16x32_bf16 v[104:107], v[184:187], v[160:163], v[104:107]
	v_mfma_f32_16x16x32_bf16 v[96:99], v[202:205], v[160:163], v[96:99]
	v_mfma_f32_16x16x32_bf16 v[88:91], v[184:187], v[168:171], v[88:91]
	v_mfma_f32_16x16x32_bf16 v[80:83], v[202:205], v[168:171], v[80:83]
	v_mfma_f32_16x16x32_bf16 v[72:75], v[184:187], v[176:179], v[72:75]
	v_mfma_f32_16x16x32_bf16 v[68:71], v[202:205], v[176:179], v[68:71]
	s_barrier
; #define PG8_STAGE(bufoff, gbase, voff) do { _Pragma("unroll") for (int _i = 0; _i < 2; ++_i) \
;         __builtin_amdgcn_global_load_lds((const unsigned*)((const char*)(gbase) + (voff)[_i]), (LAS unsigned*)(lds + (bufoff) + ldsw + _i * 8192), 16, 0, 0); } while (0)
; #define PG8_LDA(dst, b, h) do { _Pragma("unroll") for (int m = 0; m < 4; ++m) _Pragma("unroll") for (int k = 0; k < 2; ++k) dst[m][k] = *(const LAS bf16x8*)(lds + PG8_SA(b, h) + aoff + m * 2048 + k * 1024); } while (0)
; #define PG8_MMA(ai, bj, At, Bt) do { __builtin_amdgcn_s_setprio(1); _Pragma("unroll") for (int m = 0; m < 4; ++m) _Pragma("unroll") for (int n = 0; n < 2; ++n) _Pragma("unroll") for (int k = 0; k < 2; ++k) \
;         acc[ai][bj][m][n] = __builtin_amdgcn_mfma_f32_16x16x32_bf16(Bt[n][k], At[m][k], acc[ai][bj][m][n], 0, 0, 0); __builtin_amdgcn_s_setprio(0); } while (0)
; #define PG8_WAIT_V(n) asm volatile("s_waitcnt vmcnt(" #n ")" ::: "memory")
; #define PG8_WAIT_L(n) asm volatile("s_waitcnt lgkmcnt(" #n ")" ::: "memory")
; #define PG8_BAR __builtin_amdgcn_s_barrier()
; #define PG8_SCHED __builtin_amdgcn_sched_barrier(0)
; template <class Epi, class Sched>
; __device__ __forceinline__ void gemm_phase(LAS unsigned char* lds, const Gemm g, const Sched& S, const Epi& E) {
;     ...
;             PG8_LDA(At, 1, 1); PG8_STAGE(PG8_SA(1, 0), a3, voffA);
;             PG8_BAR; PG8_WAIT_L(0); PG8_MMA(1, 0, At, B0); PG8_BAR; PG8_SCHED;
;             PG8_STAGE(PG8_SB(1, 1), b3 + hstepB, voffB);
;             PG8_WAIT_V(6); PG8_BAR; PG8_MMA(1, 1, At, B1); PG8_BAR;
	s_setprio 0
	ds_read_b128 v[148:151], v224 offset:49152
	ds_read_b128 v[152:155], v224 offset:50176
	ds_read_b128 v[156:159], v224 offset:51200
	ds_read_b128 v[160:163], v224 offset:52224
	ds_read_b128 v[164:167], v224 offset:53248
	ds_read_b128 v[168:171], v224 offset:54272
	ds_read_b128 v[172:175], v224 offset:55296
	ds_read_b128 v[176:179], v224 offset:56320
	s_add_i32 s25, s52, s30
	v_lshl_add_u64 v[206:207], v[206:207], 0, s[8:9]
	s_mov_b32 m0, s25
	s_nop 0
	global_load_lds_dwordx4 v[206:207], off
	v_lshl_add_u64 v[206:207], v[208:209], 0, s[8:9]
	s_add_i32 m0, s25, 0x2000
	s_nop 0
	global_load_lds_dwordx4 v[206:207], off
	s_mov_b32 m0, s40
	v_lshl_add_u64 v[206:207], v[210:211], 0, s[8:9]
	global_load_lds_dwordx4 v[206:207], off
	v_lshl_add_u64 v[206:207], v[212:213], 0, s[8:9]
	s_mov_b32 m0, s41
	s_nop 0
	global_load_lds_dwordx4 v[206:207], off
	s_add_u32 s20, s20, 0x80080
	s_addc_u32 s21, s21, 0
	s_add_i32 s24, s24, s30
	s_mov_b32 m0, s24
	s_nop 0
	global_load_lds_dwordx4 v2, s[20:21]
	s_add_i32 m0, s24, 0x2000
	s_nop 0
	global_load_lds_dwordx4 v192, s[20:21]
	s_add_i32 s51, s51, 2
	s_add_u32 s6, s6, 0x100
	s_addc_u32 s7, s7, 0
	s_add_u32 s49, s49, 0x100
	s_addc_u32 s50, s50, 0
	s_cmp_gt_u32 s51, 29
	s_waitcnt lgkmcnt(0)
	s_waitcnt vmcnt(6)
	s_setprio 1
	s_barrier
	v_mfma_f32_16x16x32_bf16 v[64:67], v[132:135], v[148:151], v[64:67]
	v_mfma_f32_16x16x32_bf16 v[60:63], v[140:143], v[148:151], v[60:63]
	v_mfma_f32_16x16x32_bf16 v[52:55], v[132:135], v[156:159], v[52:55]
	v_mfma_f32_16x16x32_bf16 v[44:47], v[140:143], v[156:159], v[44:47]
	v_mfma_f32_16x16x32_bf16 v[36:39], v[132:135], v[164:167], v[36:39]
	v_mfma_f32_16x16x32_bf16 v[28:31], v[140:143], v[164:167], v[28:31]
	v_mfma_f32_16x16x32_bf16 v[20:23], v[132:135], v[172:175], v[20:23]
	v_mfma_f32_16x16x32_bf16 v[12:15], v[140:143], v[172:175], v[12:15]
	v_mfma_f32_16x16x32_bf16 v[64:67], v[136:139], v[152:155], v[64:67]
	v_mfma_f32_16x16x32_bf16 v[60:63], v[144:147], v[152:155], v[60:63]
	v_mfma_f32_16x16x32_bf16 v[52:55], v[136:139], v[160:163], v[52:55]
	v_mfma_f32_16x16x32_bf16 v[44:47], v[144:147], v[160:163], v[44:47]
	v_mfma_f32_16x16x32_bf16 v[36:39], v[136:139], v[168:171], v[36:39]
	v_mfma_f32_16x16x32_bf16 v[28:31], v[144:147], v[168:171], v[28:31]
	v_mfma_f32_16x16x32_bf16 v[20:23], v[136:139], v[176:179], v[20:23]
	v_mfma_f32_16x16x32_bf16 v[12:15], v[144:147], v[176:179], v[12:15]
	v_mfma_f32_16x16x32_bf16 v[56:59], v[180:183], v[148:151], v[56:59]
	v_mfma_f32_16x16x32_bf16 v[48:51], v[188:191], v[148:151], v[48:51]
	v_mfma_f32_16x16x32_bf16 v[40:43], v[180:183], v[156:159], v[40:43]
	v_mfma_f32_16x16x32_bf16 v[32:35], v[188:191], v[156:159], v[32:35]
	v_mfma_f32_16x16x32_bf16 v[24:27], v[180:183], v[164:167], v[24:27]
	v_mfma_f32_16x16x32_bf16 v[16:19], v[188:191], v[164:167], v[16:19]
	v_mfma_f32_16x16x32_bf16 v[8:11], v[180:183], v[172:175], v[8:11]
	v_mfma_f32_16x16x32_bf16 v[4:7], v[188:191], v[172:175], v[4:7]
	v_mfma_f32_16x16x32_bf16 v[56:59], v[184:187], v[152:155], v[56:59]
	v_mfma_f32_16x16x32_bf16 v[48:51], v[202:205], v[152:155], v[48:51]
	v_mfma_f32_16x16x32_bf16 v[40:43], v[184:187], v[160:163], v[40:43]
	v_mfma_f32_16x16x32_bf16 v[32:35], v[202:205], v[160:163], v[32:35]
	v_mfma_f32_16x16x32_bf16 v[24:27], v[184:187], v[168:171], v[24:27]
	v_mfma_f32_16x16x32_bf16 v[16:19], v[202:205], v[168:171], v[16:19]
	v_mfma_f32_16x16x32_bf16 v[8:11], v[184:187], v[176:179], v[8:11]
	v_mfma_f32_16x16x32_bf16 v[4:7], v[202:205], v[176:179], v[4:7]
	s_barrier
	s_setprio 0
	.p2align	6

; #define PG8_STAGE(bufoff, gbase, voff) do { _Pragma("unroll") for (int _i = 0; _i < 2; ++_i) \
;         __builtin_amdgcn_global_load_lds((const unsigned*)((const char*)(gbase) + (voff)[_i]), (LAS unsigned*)(lds + (bufoff) + ldsw + _i * 8192), 16, 0, 0); } while (0)
; #define PG8_LDA(dst, b, h) do { _Pragma("unroll") for (int m = 0; m < 4; ++m) _Pragma("unroll") for (int k = 0; k < 2; ++k) dst[m][k] = *(const LAS bf16x8*)(lds + PG8_SA(b, h) + aoff + m * 2048 + k * 1024); } while (0)
; #define PG8_LDB(dst, b, h) do { _Pragma("unroll") for (int n = 0; n < 2; ++n) _Pragma("unroll") for (int k = 0; k < 2; ++k) dst[n][k] = *(const LAS bf16x8*)(lds + PG8_SB(b, h) + boff + n * 2048 + k * 1024); } while (0)
; #define PG8_WAIT_V(n) asm volatile("s_waitcnt vmcnt(" #n ")" ::: "memory")
; template <class Epi, class Sched>
; __device__ __forceinline__ void gemm_phase(LAS unsigned char* lds, const Gemm g, const Sched& S, const Epi& E) {
;     ...
;         const bool has_next = S.next(ui + 1, nxt);
;         const char* nA = has_next ? (const char*)g.A + (size_t)nxt.pm * tstepA : cA; const char* nB = has_next ? (const char*)g.Bt + (size_t)nxt.pn * tstepB : cB;
;         for (int t = 0; t < nt; t += 2) {
;             const bool last = (t == nt - 2);
;             const char* a1 = cA + (size_t)(t + 1) * kstep;
;             const char* a2 = last ? nA : cA + (size_t)(t + 2) * kstep; const char* b2 = last ? nB : cB + (size_t)(t + 2) * kstep;
;             const char* a3 = a2 + kstep; const char* b3 = b2 + kstep;
;             if (last && has_next) S.a_ready(nxt);
;             PG8_LDB(B0, 0, 0); PG8_SCHED; PG8_LDA(At, 0, 0); PG8_STAGE(PG8_SA(1, 1), a1 + hstepA, voffA);
;             PG8_WAIT_L(8); PG8_BAR; PG8_WAIT_L(0); PG8_MMA(0, 0, At, B0); PG8_BAR; PG8_SCHED;
;             PG8_LDB(B1, 0, 1); PG8_STAGE(PG8_SB(0, 0), b2, voffB);
;             PG8_BAR; PG8_WAIT_L(0); PG8_MMA(0, 1, At, B1); PG8_BAR;
;             PG8_LDA(At, 0, 1); PG8_STAGE(PG8_SA(0, 0), a2, voffA);
;             PG8_BAR; PG8_WAIT_L(0); PG8_MMA(1, 0, At, B0); PG8_BAR; PG8_SCHED;
;             PG8_STAGE(PG8_SB(0, 1), b2 + hstepB, voffB);
;             PG8_WAIT_V(6); PG8_BAR; PG8_MMA(1, 1, At, B1); PG8_BAR;
;             PG8_LDB(B0, 1, 0); PG8_SCHED; PG8_LDA(At, 1, 0); PG8_STAGE(PG8_SA(0, 1), a2 + hstepA, voffA);
;             PG8_WAIT_L(8); PG8_BAR; PG8_WAIT_L(0); PG8_MMA(0, 0, At, B0); PG8_BAR; PG8_SCHED;
.LBB0_1093:
	v_mov_b64_e32 v[4:5], 0x900
	s_ashr_i32 s5, s4, 31
	v_cmp_lt_i64_e32 vcc, s[6:7], v[4:5]
	s_lshl_b64 s[6:7], s[4:5], 20
	s_add_u32 s6, s88, s6
	s_addc_u32 s7, s89, s7
	s_and_b64 s[14:15], vcc, exec
	s_cselect_b32 s5, s7, s19
	s_cselect_b32 s49, s6, s18
	s_ashr_i32 s1, s0, 31
	s_lshl_b64 s[14:15], s[0:1], 20
	s_add_u32 s14, s28, s14
	s_addc_u32 s15, s29, s15
	s_and_b64 s[24:25], vcc, exec
	s_cselect_b32 s1, s15, s21
	s_cselect_b32 s50, s14, s20
	s_add_u32 s18, s18, 0x80080
	s_addc_u32 s19, s19, 0
	s_add_u32 s51, s20, 0x100
	s_addc_u32 s52, s21, 0
	s_mov_b32 s53, -2
	s_setprio 0
	s_add_u32 s20, s18, 0xfff80080
	s_addc_u32 s21, s19, -1
	s_add_i32 s54, 0, 0x10000
	v_add_u32_e32 v146, s54, v1
	ds_read_b128 v[142:145], v146
	ds_read_b128 v[150:153], v146 offset:1024
	ds_read_b128 v[154:157], v146 offset:2048
	ds_read_b128 v[158:161], v146 offset:3072
	s_cmp_eq_u32 s53, 28
	s_cselect_b32 s25, s5, s21
	s_cselect_b32 s24, s49, s20
	s_cselect_b32 s21, s1, s52
	s_cselect_b32 s20, s50, s51
	ds_read_b128 v[162:165], v148
	ds_read_b128 v[166:169], v148 offset:1024
	ds_read_b128 v[170:173], v148 offset:2048
	ds_read_b128 v[174:177], v148 offset:3072
	ds_read_b128 v[178:181], v148 offset:4096
	ds_read_b128 v[182:185], v148 offset:5120
	ds_read_b128 v[186:189], v148 offset:6144
	ds_read_b128 v[190:193], v148 offset:7168
	s_add_i32 s56, 0, 0x14000
	v_add_u32_e32 v146, s56, v1
	ds_read_b128 v[194:197], v146
	ds_read_b128 v[198:201], v146 offset:1024
	ds_read_b128 v[202:205], v146 offset:2048
	ds_read_b128 v[206:209], v146 offset:3072
	s_add_i32 m0, s31, 0xc000
	s_nop 0
	global_load_lds_dwordx4 v138, s[18:19]
	s_add_i32 m0, s31, 0xe000
	s_nop 0
	global_load_lds_dwordx4 v140, s[18:19]
	s_waitcnt lgkmcnt(0)
	s_setprio 1
	s_barrier
	v_mfma_f32_16x16x32_bf16 v[128:131], v[142:145], v[162:165], 0
	v_mfma_f32_16x16x32_bf16 v[124:127], v[154:157], v[162:165], 0
	v_mfma_f32_16x16x32_bf16 v[120:123], v[142:145], v[170:173], 0
	v_mfma_f32_16x16x32_bf16 v[112:115], v[154:157], v[170:173], 0
	v_mfma_f32_16x16x32_bf16 v[104:107], v[142:145], v[178:181], 0
	v_mfma_f32_16x16x32_bf16 v[96:99], v[154:157], v[178:181], 0
	v_mfma_f32_16x16x32_bf16 v[88:91], v[142:145], v[186:189], 0
	v_mfma_f32_16x16x32_bf16 v[80:83], v[154:157], v[186:189], 0
	v_mfma_f32_16x16x32_bf16 v[128:131], v[150:153], v[166:169], v[128:131]
	v_mfma_f32_16x16x32_bf16 v[124:127], v[158:161], v[166:169], v[124:127]
	v_mfma_f32_16x16x32_bf16 v[120:123], v[150:153], v[174:177], v[120:123]
	v_mfma_f32_16x16x32_bf16 v[112:115], v[158:161], v[174:177], v[112:115]
	v_mfma_f32_16x16x32_bf16 v[104:107], v[150:153], v[182:185], v[104:107]
	v_mfma_f32_16x16x32_bf16 v[96:99], v[158:161], v[182:185], v[96:99]
	v_mfma_f32_16x16x32_bf16 v[88:91], v[150:153], v[190:193], v[88:91]
	v_mfma_f32_16x16x32_bf16 v[80:83], v[158:161], v[190:193], v[80:83]
	v_mfma_f32_16x16x32_bf16 v[116:119], v[194:197], v[162:165], 0
	v_mfma_f32_16x16x32_bf16 v[108:111], v[202:205], v[162:165], 0
	v_mfma_f32_16x16x32_bf16 v[100:103], v[194:197], v[170:173], 0
	v_mfma_f32_16x16x32_bf16 v[92:95], v[202:205], v[170:173], 0
	v_mfma_f32_16x16x32_bf16 v[84:87], v[194:197], v[178:181], 0
	v_mfma_f32_16x16x32_bf16 v[76:79], v[202:205], v[178:181], 0
	v_mfma_f32_16x16x32_bf16 v[72:75], v[194:197], v[186:189], 0
	v_mfma_f32_16x16x32_bf16 v[68:71], v[202:205], v[186:189], 0
	v_mfma_f32_16x16x32_bf16 v[116:119], v[198:201], v[166:169], v[116:119]
	v_mfma_f32_16x16x32_bf16 v[108:111], v[206:209], v[166:169], v[108:111]
	v_mfma_f32_16x16x32_bf16 v[100:103], v[198:201], v[174:177], v[100:103]
	v_mfma_f32_16x16x32_bf16 v[92:95], v[206:209], v[174:177], v[92:95]
	v_mfma_f32_16x16x32_bf16 v[84:87], v[198:201], v[182:185], v[84:87]
	v_mfma_f32_16x16x32_bf16 v[76:79], v[206:209], v[182:185], v[76:79]
	v_mfma_f32_16x16x32_bf16 v[72:75], v[198:201], v[190:193], v[72:75]
	v_mfma_f32_16x16x32_bf16 v[68:71], v[206:209], v[190:193], v[68:71]
	s_barrier
	s_setprio 0
	ds_read_b128 v[162:165], v148 offset:16384
	ds_read_b128 v[166:169], v148 offset:17408
	ds_read_b128 v[170:173], v148 offset:18432
	ds_read_b128 v[174:177], v148 offset:19456
	ds_read_b128 v[178:181], v148 offset:20480
	ds_read_b128 v[182:185], v148 offset:21504
	ds_read_b128 v[186:189], v148 offset:22528
	ds_read_b128 v[190:193], v148 offset:23552
	s_add_i32 s54, s54, s30
	v_lshl_add_u64 v[146:147], s[20:21], 0, v[2:3]
	s_mov_b32 m0, s54
	v_lshl_add_u64 v[210:211], s[20:21], 0, v[132:133]
	global_load_lds_dwordx4 v[146:147], off
	s_add_i32 m0, s54, 0x2000
	s_nop 0
	global_load_lds_dwordx4 v[210:211], off
	s_mov_b32 m0, s31
	v_lshl_add_u64 v[212:213], s[24:25], 0, v[136:137]
	global_load_lds_dwordx4 v[212:213], off
	v_lshl_add_u64 v[216:217], s[24:25], 0, v[134:135]
	s_mov_b32 m0, s35
	s_nop 0
	global_load_lds_dwordx4 v[216:217], off
	s_add_u32 s54, s20, 0x80000
	s_addc_u32 s55, s21, 0
	s_add_i32 s56, s56, s30
	s_mov_b32 m0, s56
	s_nop 0
	global_load_lds_dwordx4 v2, s[54:55]
	s_add_i32 m0, s56, 0x2000
	s_nop 0
	global_load_lds_dwordx4 v132, s[54:55]
	s_waitcnt lgkmcnt(0)
	s_waitcnt vmcnt(6)
	s_setprio 1
	s_barrier
; #define PG8_STAGE(bufoff, gbase, voff) do { _Pragma("unroll") for (int _i = 0; _i < 2; ++_i) \
;         __builtin_amdgcn_global_load_lds((const unsigned*)((const char*)(gbase) + (voff)[_i]), (LAS unsigned*)(lds + (bufoff) + ldsw + _i * 8192), 16, 0, 0); } while (0)
; #define PG8_LDA(dst, b, h) do { _Pragma("unroll") for (int m = 0; m < 4; ++m) _Pragma("unroll") for (int k = 0; k < 2; ++k) dst[m][k] = *(const LAS bf16x8*)(lds + PG8_SA(b, h) + aoff + m * 2048 + k * 1024); } while (0)
; #define PG8_LDB(dst, b, h) do { _Pragma("unroll") for (int n = 0; n < 2; ++n) _Pragma("unroll") for (int k = 0; k < 2; ++k) dst[n][k] = *(const LAS bf16x8*)(lds + PG8_SB(b, h) + boff + n * 2048 + k * 1024); } while (0)
; #define PG8_MMA(ai, bj, At, Bt) do { __builtin_amdgcn_s_setprio(1); _Pragma("unroll") for (int m = 0; m < 4; ++m) _Pragma("unroll") for (int n = 0; n < 2; ++n) _Pragma("unroll") for (int k = 0; k < 2; ++k) \
;         acc[ai][bj][m][n] = __builtin_amdgcn_mfma_f32_16x16x32_bf16(Bt[n][k], At[m][k], acc[ai][bj][m][n], 0, 0, 0); __builtin_amdgcn_s_setprio(0); } while (0)
; #define PG8_WAIT_V(n) asm volatile("s_waitcnt vmcnt(" #n ")" ::: "memory")
; #define PG8_WAIT_L(n) asm volatile("s_waitcnt lgkmcnt(" #n ")" ::: "memory")
; #define PG8_BAR __builtin_amdgcn_s_barrier()
; #define PG8_SCHED __builtin_amdgcn_sched_barrier(0)
; template <class Epi, class Sched>
; __device__ __forceinline__ void gemm_phase(LAS unsigned char* lds, const Gemm g, const Sched& S, const Epi& E) {
;     ...
;             PG8_BAR; PG8_WAIT_L(0); PG8_MMA(1, 0, At, B0); PG8_BAR; PG8_SCHED;
;             PG8_STAGE(PG8_SB(0, 1), b2 + hstepB, voffB);
;             PG8_WAIT_V(6); PG8_BAR; PG8_MMA(1, 1, At, B1); PG8_BAR;
;             PG8_LDB(B0, 1, 0); PG8_SCHED; PG8_LDA(At, 1, 0); PG8_STAGE(PG8_SA(0, 1), a2 + hstepA, voffA);
;             PG8_WAIT_L(8); PG8_BAR; PG8_WAIT_L(0); PG8_MMA(0, 0, At, B0); PG8_BAR; PG8_SCHED;
;             PG8_LDB(B1, 1, 1); PG8_STAGE(PG8_SB(1, 0), b3, voffB);
;             PG8_BAR; PG8_WAIT_L(0); PG8_MMA(0, 1, At, B1); PG8_BAR;
;             PG8_LDA(At, 1, 1); PG8_STAGE(PG8_SA(1, 0), a3, voffA);
;             PG8_BAR; PG8_WAIT_L(0); PG8_MMA(1, 0, At, B0); PG8_BAR; PG8_SCHED;
	v_mfma_f32_16x16x32_bf16 v[64:67], v[142:145], v[162:165], 0
	v_mfma_f32_16x16x32_bf16 v[60:63], v[154:157], v[162:165], 0
	v_mfma_f32_16x16x32_bf16 v[56:59], v[142:145], v[170:173], 0
	v_mfma_f32_16x16x32_bf16 v[48:51], v[154:157], v[170:173], 0
	v_mfma_f32_16x16x32_bf16 v[40:43], v[142:145], v[178:181], 0
	v_mfma_f32_16x16x32_bf16 v[32:35], v[154:157], v[178:181], 0
	v_mfma_f32_16x16x32_bf16 v[24:27], v[142:145], v[186:189], 0
	v_mfma_f32_16x16x32_bf16 v[16:19], v[154:157], v[186:189], 0
	v_mfma_f32_16x16x32_bf16 v[64:67], v[150:153], v[166:169], v[64:67]
	v_mfma_f32_16x16x32_bf16 v[60:63], v[158:161], v[166:169], v[60:63]
	v_mfma_f32_16x16x32_bf16 v[56:59], v[150:153], v[174:177], v[56:59]
	v_mfma_f32_16x16x32_bf16 v[48:51], v[158:161], v[174:177], v[48:51]
	v_mfma_f32_16x16x32_bf16 v[40:43], v[150:153], v[182:185], v[40:43]
	v_mfma_f32_16x16x32_bf16 v[32:35], v[158:161], v[182:185], v[32:35]
	v_mfma_f32_16x16x32_bf16 v[24:27], v[150:153], v[190:193], v[24:27]
	v_mfma_f32_16x16x32_bf16 v[16:19], v[158:161], v[190:193], v[16:19]
	v_mfma_f32_16x16x32_bf16 v[52:55], v[194:197], v[162:165], 0
	v_mfma_f32_16x16x32_bf16 v[44:47], v[202:205], v[162:165], 0
	v_mfma_f32_16x16x32_bf16 v[36:39], v[194:197], v[170:173], 0
	v_mfma_f32_16x16x32_bf16 v[28:31], v[202:205], v[170:173], 0
	v_mfma_f32_16x16x32_bf16 v[20:23], v[194:197], v[178:181], 0
	v_mfma_f32_16x16x32_bf16 v[12:15], v[202:205], v[178:181], 0
	v_mfma_f32_16x16x32_bf16 v[8:11], v[194:197], v[186:189], 0
	v_mfma_f32_16x16x32_bf16 v[4:7], v[202:205], v[186:189], 0
	v_mfma_f32_16x16x32_bf16 v[52:55], v[198:201], v[166:169], v[52:55]
	v_mfma_f32_16x16x32_bf16 v[44:47], v[206:209], v[166:169], v[44:47]
	v_mfma_f32_16x16x32_bf16 v[36:39], v[198:201], v[174:177], v[36:39]
	v_mfma_f32_16x16x32_bf16 v[28:31], v[206:209], v[174:177], v[28:31]
	v_mfma_f32_16x16x32_bf16 v[20:23], v[198:201], v[182:185], v[20:23]
	v_mfma_f32_16x16x32_bf16 v[12:15], v[206:209], v[182:185], v[12:15]
	v_mfma_f32_16x16x32_bf16 v[8:11], v[198:201], v[190:193], v[8:11]
	v_mfma_f32_16x16x32_bf16 v[4:7], v[206:209], v[190:193], v[4:7]
	s_barrier
	s_setprio 0
	s_add_i32 s54, 0, 0x18000
	v_add_u32_e32 v149, s54, v1
	ds_read_b128 v[142:145], v149
	ds_read_b128 v[150:153], v149 offset:1024
	ds_read_b128 v[154:157], v149 offset:2048
	ds_read_b128 v[158:161], v149 offset:3072
	s_add_u32 s24, s24, 0x80000
	s_addc_u32 s25, s25, 0
	ds_read_b128 v[162:165], v148 offset:32768
	ds_read_b128 v[166:169], v148 offset:33792
	ds_read_b128 v[170:173], v148 offset:34816
	ds_read_b128 v[174:177], v148 offset:35840
	ds_read_b128 v[178:181], v148 offset:36864
	ds_read_b128 v[182:185], v148 offset:37888
	ds_read_b128 v[186:189], v148 offset:38912
	ds_read_b128 v[190:193], v148 offset:39936
	s_mov_b32 m0, s36
	s_nop 0
	global_load_lds_dwordx4 v136, s[24:25]
	s_mov_b32 m0, s37
	s_nop 0
	global_load_lds_dwordx4 v134, s[24:25]
	s_add_i32 s24, 0, 0x1c000
	v_add_u32_e32 v149, s24, v1
	ds_read_b128 v[194:197], v149
	ds_read_b128 v[198:201], v149 offset:1024
	ds_read_b128 v[202:205], v149 offset:2048
	ds_read_b128 v[206:209], v149 offset:3072
	s_waitcnt lgkmcnt(0)
	s_setprio 1
	s_barrier
	v_mfma_f32_16x16x32_bf16 v[128:131], v[142:145], v[162:165], v[128:131]
	v_mfma_f32_16x16x32_bf16 v[124:127], v[154:157], v[162:165], v[124:127]
	v_mfma_f32_16x16x32_bf16 v[120:123], v[142:145], v[170:173], v[120:123]
	v_mfma_f32_16x16x32_bf16 v[112:115], v[154:157], v[170:173], v[112:115]
	v_mfma_f32_16x16x32_bf16 v[104:107], v[142:145], v[178:181], v[104:107]
	v_mfma_f32_16x16x32_bf16 v[96:99], v[154:157], v[178:181], v[96:99]
	v_mfma_f32_16x16x32_bf16 v[88:91], v[142:145], v[186:189], v[88:91]
	v_mfma_f32_16x16x32_bf16 v[80:83], v[154:157], v[186:189], v[80:83]
	v_mfma_f32_16x16x32_bf16 v[128:131], v[150:153], v[166:169], v[128:131]
	v_mfma_f32_16x16x32_bf16 v[124:127], v[158:161], v[166:169], v[124:127]
	v_mfma_f32_16x16x32_bf16 v[120:123], v[150:153], v[174:177], v[120:123]
	v_mfma_f32_16x16x32_bf16 v[112:115], v[158:161], v[174:177], v[112:115]
	v_mfma_f32_16x16x32_bf16 v[104:107], v[150:153], v[182:185], v[104:107]
	v_mfma_f32_16x16x32_bf16 v[96:99], v[158:161], v[182:185], v[96:99]
	v_mfma_f32_16x16x32_bf16 v[88:91], v[150:153], v[190:193], v[88:91]
	v_mfma_f32_16x16x32_bf16 v[80:83], v[158:161], v[190:193], v[80:83]
	v_mfma_f32_16x16x32_bf16 v[116:119], v[194:197], v[162:165], v[116:119]
	v_mfma_f32_16x16x32_bf16 v[108:111], v[202:205], v[162:165], v[108:111]
	v_mfma_f32_16x16x32_bf16 v[100:103], v[194:197], v[170:173], v[100:103]
	v_mfma_f32_16x16x32_bf16 v[92:95], v[202:205], v[170:173], v[92:95]
	v_mfma_f32_16x16x32_bf16 v[84:87], v[194:197], v[178:181], v[84:87]
	v_mfma_f32_16x16x32_bf16 v[76:79], v[202:205], v[178:181], v[76:79]
	v_mfma_f32_16x16x32_bf16 v[72:75], v[194:197], v[186:189], v[72:75]
	v_mfma_f32_16x16x32_bf16 v[68:71], v[202:205], v[186:189], v[68:71]
	v_mfma_f32_16x16x32_bf16 v[116:119], v[198:201], v[166:169], v[116:119]
	v_mfma_f32_16x16x32_bf16 v[108:111], v[206:209], v[166:169], v[108:111]
	v_mfma_f32_16x16x32_bf16 v[100:103], v[198:201], v[174:177], v[100:103]
	v_mfma_f32_16x16x32_bf16 v[92:95], v[206:209], v[174:177], v[92:95]
	v_mfma_f32_16x16x32_bf16 v[84:87], v[198:201], v[182:185], v[84:87]
	v_mfma_f32_16x16x32_bf16 v[76:79], v[206:209], v[182:185], v[76:79]
	v_mfma_f32_16x16x32_bf16 v[72:75], v[198:201], v[190:193], v[72:75]
	v_mfma_f32_16x16x32_bf16 v[68:71], v[206:209], v[190:193], v[68:71]
	s_barrier
; #define PG8_STAGE(bufoff, gbase, voff) do { _Pragma("unroll") for (int _i = 0; _i < 2; ++_i) \
;         __builtin_amdgcn_global_load_lds((const unsigned*)((const char*)(gbase) + (voff)[_i]), (LAS unsigned*)(lds + (bufoff) + ldsw + _i * 8192), 16, 0, 0); } while (0)
; #define PG8_LDA(dst, b, h) do { _Pragma("unroll") for (int m = 0; m < 4; ++m) _Pragma("unroll") for (int k = 0; k < 2; ++k) dst[m][k] = *(const LAS bf16x8*)(lds + PG8_SA(b, h) + aoff + m * 2048 + k * 1024); } while (0)
; #define PG8_MMA(ai, bj, At, Bt) do { __builtin_amdgcn_s_setprio(1); _Pragma("unroll") for (int m = 0; m < 4; ++m) _Pragma("unroll") for (int n = 0; n < 2; ++n) _Pragma("unroll") for (int k = 0; k < 2; ++k) \
;         acc[ai][bj][m][n] = __builtin_amdgcn_mfma_f32_16x16x32_bf16(Bt[n][k], At[m][k], acc[ai][bj][m][n], 0, 0, 0); __builtin_amdgcn_s_setprio(0); } while (0)
; #define PG8_WAIT_V(n) asm volatile("s_waitcnt vmcnt(" #n ")" ::: "memory")
; #define PG8_WAIT_L(n) asm volatile("s_waitcnt lgkmcnt(" #n ")" ::: "memory")
; #define PG8_BAR __builtin_amdgcn_s_barrier()
; #define PG8_SCHED __builtin_amdgcn_sched_barrier(0)
; template <class Epi, class Sched>
; __device__ __forceinline__ void gemm_phase(LAS unsigned char* lds, const Gemm g, const Sched& S, const Epi& E) {
;     ...
;             PG8_LDA(At, 1, 1); PG8_STAGE(PG8_SA(1, 0), a3, voffA);
;             PG8_BAR; PG8_WAIT_L(0); PG8_MMA(1, 0, At, B0); PG8_BAR; PG8_SCHED;
;             PG8_STAGE(PG8_SB(1, 1), b3 + hstepB, voffB);
;             PG8_WAIT_V(6); PG8_BAR; PG8_MMA(1, 1, At, B1); PG8_BAR;
	s_setprio 0
	ds_read_b128 v[162:165], v148 offset:49152
	ds_read_b128 v[166:169], v148 offset:50176
	ds_read_b128 v[170:173], v148 offset:51200
	ds_read_b128 v[174:177], v148 offset:52224
	ds_read_b128 v[178:181], v148 offset:53248
	ds_read_b128 v[182:185], v148 offset:54272
	ds_read_b128 v[186:189], v148 offset:55296
	ds_read_b128 v[190:193], v148 offset:56320
	s_add_i32 s25, s54, s30
	v_lshl_add_u64 v[146:147], v[146:147], 0, s[8:9]
	s_mov_b32 m0, s25
	s_nop 0
	global_load_lds_dwordx4 v[146:147], off
	v_lshl_add_u64 v[146:147], v[210:211], 0, s[8:9]
	s_add_i32 m0, s25, 0x2000
	s_nop 0
	global_load_lds_dwordx4 v[146:147], off
	s_mov_b32 m0, s42
	v_lshl_add_u64 v[146:147], v[212:213], 0, s[8:9]
	global_load_lds_dwordx4 v[146:147], off
	v_lshl_add_u64 v[146:147], v[216:217], 0, s[8:9]
	s_mov_b32 m0, s43
	s_nop 0
	global_load_lds_dwordx4 v[146:147], off
	s_add_u32 s20, s20, 0x80080
	s_addc_u32 s21, s21, 0
	s_add_i32 s24, s24, s30
	s_mov_b32 m0, s24
	s_nop 0
	global_load_lds_dwordx4 v2, s[20:21]
	s_add_i32 m0, s24, 0x2000
	s_nop 0
	global_load_lds_dwordx4 v132, s[20:21]
	s_add_i32 s53, s53, 2
	s_add_u32 s18, s18, 0x100
	s_addc_u32 s19, s19, 0
	s_add_u32 s51, s51, 0x100
	s_addc_u32 s52, s52, 0
	s_cmp_gt_u32 s53, 29
	s_waitcnt lgkmcnt(0)
	s_waitcnt vmcnt(6)
	s_setprio 1
	s_barrier
	v_mfma_f32_16x16x32_bf16 v[64:67], v[142:145], v[162:165], v[64:67]
	v_mfma_f32_16x16x32_bf16 v[60:63], v[154:157], v[162:165], v[60:63]
	v_mfma_f32_16x16x32_bf16 v[56:59], v[142:145], v[170:173], v[56:59]
	v_mfma_f32_16x16x32_bf16 v[48:51], v[154:157], v[170:173], v[48:51]
	v_mfma_f32_16x16x32_bf16 v[40:43], v[142:145], v[178:181], v[40:43]
	v_mfma_f32_16x16x32_bf16 v[32:35], v[154:157], v[178:181], v[32:35]
	v_mfma_f32_16x16x32_bf16 v[24:27], v[142:145], v[186:189], v[24:27]
	v_mfma_f32_16x16x32_bf16 v[16:19], v[154:157], v[186:189], v[16:19]
	v_mfma_f32_16x16x32_bf16 v[64:67], v[150:153], v[166:169], v[64:67]
	v_mfma_f32_16x16x32_bf16 v[60:63], v[158:161], v[166:169], v[60:63]
	v_mfma_f32_16x16x32_bf16 v[56:59], v[150:153], v[174:177], v[56:59]
	v_mfma_f32_16x16x32_bf16 v[48:51], v[158:161], v[174:177], v[48:51]
	v_mfma_f32_16x16x32_bf16 v[40:43], v[150:153], v[182:185], v[40:43]
	v_mfma_f32_16x16x32_bf16 v[32:35], v[158:161], v[182:185], v[32:35]
	v_mfma_f32_16x16x32_bf16 v[24:27], v[150:153], v[190:193], v[24:27]
	v_mfma_f32_16x16x32_bf16 v[16:19], v[158:161], v[190:193], v[16:19]
	v_mfma_f32_16x16x32_bf16 v[52:55], v[194:197], v[162:165], v[52:55]
	v_mfma_f32_16x16x32_bf16 v[44:47], v[202:205], v[162:165], v[44:47]
	v_mfma_f32_16x16x32_bf16 v[36:39], v[194:197], v[170:173], v[36:39]
	v_mfma_f32_16x16x32_bf16 v[28:31], v[202:205], v[170:173], v[28:31]
	v_mfma_f32_16x16x32_bf16 v[20:23], v[194:197], v[178:181], v[20:23]
	v_mfma_f32_16x16x32_bf16 v[12:15], v[202:205], v[178:181], v[12:15]
	v_mfma_f32_16x16x32_bf16 v[8:11], v[194:197], v[186:189], v[8:11]
	v_mfma_f32_16x16x32_bf16 v[4:7], v[202:205], v[186:189], v[4:7]
	v_mfma_f32_16x16x32_bf16 v[52:55], v[198:201], v[166:169], v[52:55]
	v_mfma_f32_16x16x32_bf16 v[44:47], v[206:209], v[166:169], v[44:47]
	v_mfma_f32_16x16x32_bf16 v[36:39], v[198:201], v[174:177], v[36:39]
	v_mfma_f32_16x16x32_bf16 v[28:31], v[206:209], v[174:177], v[28:31]
	v_mfma_f32_16x16x32_bf16 v[20:23], v[198:201], v[182:185], v[20:23]
	v_mfma_f32_16x16x32_bf16 v[12:15], v[206:209], v[182:185], v[12:15]
	v_mfma_f32_16x16x32_bf16 v[8:11], v[198:201], v[190:193], v[8:11]
	v_mfma_f32_16x16x32_bf16 v[4:7], v[206:209], v[190:193], v[4:7]
	s_barrier
	s_setprio 0
	.p2align	6

; #define PG8_STAGE(bufoff, gbase, voff) do { _Pragma("unroll") for (int _i = 0; _i < 2; ++_i) \
;         __builtin_amdgcn_global_load_lds((const unsigned*)((const char*)(gbase) + (voff)[_i]), (LAS unsigned*)(lds + (bufoff) + ldsw + _i * 8192), 16, 0, 0); } while (0)
; #define PG8_LDA(dst, b, h) do { _Pragma("unroll") for (int m = 0; m < 4; ++m) _Pragma("unroll") for (int k = 0; k < 2; ++k) dst[m][k] = *(const LAS bf16x8*)(lds + PG8_SA(b, h) + aoff + m * 2048 + k * 1024); } while (0)
; #define PG8_LDB(dst, b, h) do { _Pragma("unroll") for (int n = 0; n < 2; ++n) _Pragma("unroll") for (int k = 0; k < 2; ++k) dst[n][k] = *(const LAS bf16x8*)(lds + PG8_SB(b, h) + boff + n * 2048 + k * 1024); } while (0)
; #define PG8_WAIT_V(n) asm volatile("s_waitcnt vmcnt(" #n ")" ::: "memory")
; template <class Epi, class Sched>
; __device__ __forceinline__ void gemm_phase(LAS unsigned char* lds, const Gemm g, const Sched& S, const Epi& E) {
;     ...
;         const bool has_next = S.next(ui + 1, nxt);
;         const char* nA = has_next ? (const char*)g.A + (size_t)nxt.pm * tstepA : cA; const char* nB = has_next ? (const char*)g.Bt + (size_t)nxt.pn * tstepB : cB;
;         for (int t = 0; t < nt; t += 2) {
;             const bool last = (t == nt - 2);
;             const char* a1 = cA + (size_t)(t + 1) * kstep;
;             const char* a2 = last ? nA : cA + (size_t)(t + 2) * kstep; const char* b2 = last ? nB : cB + (size_t)(t + 2) * kstep;
;             const char* a3 = a2 + kstep; const char* b3 = b2 + kstep;
;             if (last && has_next) S.a_ready(nxt);
;             PG8_LDB(B0, 0, 0); PG8_SCHED; PG8_LDA(At, 0, 0); PG8_STAGE(PG8_SA(1, 1), a1 + hstepA, voffA);
;             PG8_WAIT_L(8); PG8_BAR; PG8_WAIT_L(0); PG8_MMA(0, 0, At, B0); PG8_BAR; PG8_SCHED;
;             PG8_LDB(B1, 0, 1); PG8_STAGE(PG8_SB(0, 0), b2, voffB);
;             PG8_BAR; PG8_WAIT_L(0); PG8_MMA(0, 1, At, B1); PG8_BAR;
;             PG8_LDA(At, 0, 1); PG8_STAGE(PG8_SA(0, 0), a2, voffA);
;             PG8_BAR; PG8_WAIT_L(0); PG8_MMA(1, 0, At, B0); PG8_BAR; PG8_SCHED;
;             PG8_STAGE(PG8_SB(0, 1), b2 + hstepB, voffB);
;             PG8_WAIT_V(6); PG8_BAR; PG8_MMA(1, 1, At, B1); PG8_BAR;
;             PG8_LDB(B0, 1, 0); PG8_SCHED; PG8_LDA(At, 1, 0); PG8_STAGE(PG8_SA(0, 1), a2 + hstepA, voffA);
;             PG8_WAIT_L(8); PG8_BAR; PG8_WAIT_L(0); PG8_MMA(0, 0, At, B0); PG8_BAR; PG8_SCHED;
.LBB0_1395:
	v_mov_b64_e32 v[4:5], 0x400
	s_ashr_i32 s15, s14, 31
	v_cmp_lt_i64_e32 vcc, s[4:5], v[4:5]
	s_lshl_b64 s[4:5], s[14:15], 20
	v_readlane_b32 s48, v252, 0
	v_readlane_b32 s49, v252, 1
	s_add_u32 s4, s48, s4
	s_addc_u32 s5, s49, s5
	s_and_b64 s[18:19], vcc, exec
	s_cselect_b32 s15, s5, s7
	s_cselect_b32 s47, s4, s6
	s_ashr_i32 s1, s0, 31
	s_lshl_b64 s[18:19], s[0:1], 20
	s_add_u32 s18, s28, s18
	s_addc_u32 s19, s29, s19
	s_and_b64 s[24:25], vcc, exec
	s_cselect_b32 s1, s19, s21
	s_cselect_b32 s48, s18, s20
	s_add_u32 s6, s6, 0x80080
	s_addc_u32 s7, s7, 0
	v_readlane_b32 s50, v252, 2
	v_readlane_b32 s51, v252, 3
	s_add_u32 s49, s20, 0x100
	s_addc_u32 s50, s21, 0
	s_mov_b32 s51, -2
	s_setprio 0
	s_add_u32 s20, s6, 0xfff80080
	s_addc_u32 s21, s7, -1
	s_add_i32 s52, 0, 0x10000
	v_add_u32_e32 v144, s52, v1
	ds_read_b128 v[132:135], v144
	ds_read_b128 v[136:139], v144 offset:1024
	ds_read_b128 v[140:143], v144 offset:2048
	ds_read_b128 v[144:147], v144 offset:3072
	s_cmp_eq_u32 s51, 28
	s_cselect_b32 s25, s15, s21
	s_cselect_b32 s24, s47, s20
	s_cselect_b32 s21, s1, s50
	s_cselect_b32 s20, s48, s49
	ds_read_b128 v[148:151], v224
	ds_read_b128 v[152:155], v224 offset:1024
	ds_read_b128 v[156:159], v224 offset:2048
	ds_read_b128 v[160:163], v224 offset:3072
	ds_read_b128 v[164:167], v224 offset:4096
	ds_read_b128 v[168:171], v224 offset:5120
	ds_read_b128 v[172:175], v224 offset:6144
	ds_read_b128 v[176:179], v224 offset:7168
	s_add_i32 s54, 0, 0x14000
	v_add_u32_e32 v202, s54, v1
	ds_read_b128 v[180:183], v202
	ds_read_b128 v[184:187], v202 offset:1024
	ds_read_b128 v[188:191], v202 offset:2048
	ds_read_b128 v[202:205], v202 offset:3072
	s_add_i32 m0, s31, 0xc000
	s_nop 0
	global_load_lds_dwordx4 v198, s[6:7]
	s_add_i32 m0, s31, 0xe000
	s_nop 0
	global_load_lds_dwordx4 v200, s[6:7]
	s_waitcnt lgkmcnt(0)
	s_setprio 1
	s_barrier
	v_mfma_f32_16x16x32_bf16 v[128:131], v[132:135], v[148:151], 0
	v_mfma_f32_16x16x32_bf16 v[124:127], v[140:143], v[148:151], 0
	v_mfma_f32_16x16x32_bf16 v[112:115], v[132:135], v[156:159], 0
	v_mfma_f32_16x16x32_bf16 v[108:111], v[140:143], v[156:159], 0
	v_mfma_f32_16x16x32_bf16 v[100:103], v[132:135], v[164:167], 0
	v_mfma_f32_16x16x32_bf16 v[92:95], v[140:143], v[164:167], 0
	v_mfma_f32_16x16x32_bf16 v[84:87], v[132:135], v[172:175], 0
	v_mfma_f32_16x16x32_bf16 v[76:79], v[140:143], v[172:175], 0
	v_mfma_f32_16x16x32_bf16 v[128:131], v[136:139], v[152:155], v[128:131]
	v_mfma_f32_16x16x32_bf16 v[124:127], v[144:147], v[152:155], v[124:127]
	v_mfma_f32_16x16x32_bf16 v[112:115], v[136:139], v[160:163], v[112:115]
	v_mfma_f32_16x16x32_bf16 v[108:111], v[144:147], v[160:163], v[108:111]
	v_mfma_f32_16x16x32_bf16 v[100:103], v[136:139], v[168:171], v[100:103]
	v_mfma_f32_16x16x32_bf16 v[92:95], v[144:147], v[168:171], v[92:95]
	v_mfma_f32_16x16x32_bf16 v[84:87], v[136:139], v[176:179], v[84:87]
	v_mfma_f32_16x16x32_bf16 v[76:79], v[144:147], v[176:179], v[76:79]
	v_mfma_f32_16x16x32_bf16 v[120:123], v[180:183], v[148:151], 0
	v_mfma_f32_16x16x32_bf16 v[116:119], v[188:191], v[148:151], 0
	v_mfma_f32_16x16x32_bf16 v[104:107], v[180:183], v[156:159], 0
	v_mfma_f32_16x16x32_bf16 v[96:99], v[188:191], v[156:159], 0
	v_mfma_f32_16x16x32_bf16 v[88:91], v[180:183], v[164:167], 0
	v_mfma_f32_16x16x32_bf16 v[80:83], v[188:191], v[164:167], 0
	v_mfma_f32_16x16x32_bf16 v[72:75], v[180:183], v[172:175], 0
	v_mfma_f32_16x16x32_bf16 v[68:71], v[188:191], v[172:175], 0
	v_mfma_f32_16x16x32_bf16 v[120:123], v[184:187], v[152:155], v[120:123]
	v_mfma_f32_16x16x32_bf16 v[116:119], v[202:205], v[152:155], v[116:119]
	v_mfma_f32_16x16x32_bf16 v[104:107], v[184:187], v[160:163], v[104:107]
	v_mfma_f32_16x16x32_bf16 v[96:99], v[202:205], v[160:163], v[96:99]
	v_mfma_f32_16x16x32_bf16 v[88:91], v[184:187], v[168:171], v[88:91]
	v_mfma_f32_16x16x32_bf16 v[80:83], v[202:205], v[168:171], v[80:83]
	v_mfma_f32_16x16x32_bf16 v[72:75], v[184:187], v[176:179], v[72:75]
	v_mfma_f32_16x16x32_bf16 v[68:71], v[202:205], v[176:179], v[68:71]
	s_barrier
	s_setprio 0
	ds_read_b128 v[148:151], v224 offset:16384
	ds_read_b128 v[152:155], v224 offset:17408
	ds_read_b128 v[156:159], v224 offset:18432
	ds_read_b128 v[160:163], v224 offset:19456
	ds_read_b128 v[164:167], v224 offset:20480
	ds_read_b128 v[168:171], v224 offset:21504
	ds_read_b128 v[172:175], v224 offset:22528
	ds_read_b128 v[176:179], v224 offset:23552
	s_add_i32 s52, s52, s30
	v_lshl_add_u64 v[206:207], s[20:21], 0, v[2:3]
	s_mov_b32 m0, s52
	s_nop 0
	global_load_lds_dwordx4 v[206:207], off
	v_lshl_add_u64 v[208:209], s[20:21], 0, v[192:193]
	s_add_i32 m0, s52, 0x2000
	s_nop 0
	global_load_lds_dwordx4 v[208:209], off
	s_mov_b32 m0, s31
	v_lshl_add_u64 v[210:211], s[24:25], 0, v[196:197]
	global_load_lds_dwordx4 v[210:211], off
	v_lshl_add_u64 v[212:213], s[24:25], 0, v[194:195]
	s_mov_b32 m0, s35
	s_nop 0
	global_load_lds_dwordx4 v[212:213], off
	s_add_u32 s52, s20, 0x80000
	s_addc_u32 s53, s21, 0
	s_add_i32 s54, s54, s30
	s_mov_b32 m0, s54
	s_nop 0
	global_load_lds_dwordx4 v2, s[52:53]
	s_add_i32 m0, s54, 0x2000
	s_nop 0
	global_load_lds_dwordx4 v192, s[52:53]
	s_waitcnt lgkmcnt(0)
	s_waitcnt vmcnt(6)
	s_setprio 1
	s_barrier
; #define PG8_STAGE(bufoff, gbase, voff) do { _Pragma("unroll") for (int _i = 0; _i < 2; ++_i) \
;         __builtin_amdgcn_global_load_lds((const unsigned*)((const char*)(gbase) + (voff)[_i]), (LAS unsigned*)(lds + (bufoff) + ldsw + _i * 8192), 16, 0, 0); } while (0)
; #define PG8_LDA(dst, b, h) do { _Pragma("unroll") for (int m = 0; m < 4; ++m) _Pragma("unroll") for (int k = 0; k < 2; ++k) dst[m][k] = *(const LAS bf16x8*)(lds + PG8_SA(b, h) + aoff + m * 2048 + k * 1024); } while (0)
; #define PG8_LDB(dst, b, h) do { _Pragma("unroll") for (int n = 0; n < 2; ++n) _Pragma("unroll") for (int k = 0; k < 2; ++k) dst[n][k] = *(const LAS bf16x8*)(lds + PG8_SB(b, h) + boff + n * 2048 + k * 1024); } while (0)
; #define PG8_MMA(ai, bj, At, Bt) do { __builtin_amdgcn_s_setprio(1); _Pragma("unroll") for (int m = 0; m < 4; ++m) _Pragma("unroll") for (int n = 0; n < 2; ++n) _Pragma("unroll") for (int k = 0; k < 2; ++k) \
;         acc[ai][bj][m][n] = __builtin_amdgcn_mfma_f32_16x16x32_bf16(Bt[n][k], At[m][k], acc[ai][bj][m][n], 0, 0, 0); __builtin_amdgcn_s_setprio(0); } while (0)
; #define PG8_WAIT_V(n) asm volatile("s_waitcnt vmcnt(" #n ")" ::: "memory")
; #define PG8_WAIT_L(n) asm volatile("s_waitcnt lgkmcnt(" #n ")" ::: "memory")
; #define PG8_BAR __builtin_amdgcn_s_barrier()
; #define PG8_SCHED __builtin_amdgcn_sched_barrier(0)
; template <class Epi, class Sched>
; __device__ __forceinline__ void gemm_phase(LAS unsigned char* lds, const Gemm g, const Sched& S, const Epi& E) {
;     ...
;             PG8_BAR; PG8_WAIT_L(0); PG8_MMA(1, 0, At, B0); PG8_BAR; PG8_SCHED;
;             PG8_STAGE(PG8_SB(0, 1), b2 + hstepB, voffB);
;             PG8_WAIT_V(6); PG8_BAR; PG8_MMA(1, 1, At, B1); PG8_BAR;
;             PG8_LDB(B0, 1, 0); PG8_SCHED; PG8_LDA(At, 1, 0); PG8_STAGE(PG8_SA(0, 1), a2 + hstepA, voffA);
;             PG8_WAIT_L(8); PG8_BAR; PG8_WAIT_L(0); PG8_MMA(0, 0, At, B0); PG8_BAR; PG8_SCHED;
;             PG8_LDB(B1, 1, 1); PG8_STAGE(PG8_SB(1, 0), b3, voffB);
;             PG8_BAR; PG8_WAIT_L(0); PG8_MMA(0, 1, At, B1); PG8_BAR;
;             PG8_LDA(At, 1, 1); PG8_STAGE(PG8_SA(1, 0), a3, voffA);
;             PG8_BAR; PG8_WAIT_L(0); PG8_MMA(1, 0, At, B0); PG8_BAR; PG8_SCHED;
	v_mfma_f32_16x16x32_bf16 v[64:67], v[132:135], v[148:151], 0
	v_mfma_f32_16x16x32_bf16 v[60:63], v[140:143], v[148:151], 0
	v_mfma_f32_16x16x32_bf16 v[52:55], v[132:135], v[156:159], 0
	v_mfma_f32_16x16x32_bf16 v[44:47], v[140:143], v[156:159], 0
	v_mfma_f32_16x16x32_bf16 v[36:39], v[132:135], v[164:167], 0
	v_mfma_f32_16x16x32_bf16 v[28:31], v[140:143], v[164:167], 0
	v_mfma_f32_16x16x32_bf16 v[20:23], v[132:135], v[172:175], 0
	v_mfma_f32_16x16x32_bf16 v[12:15], v[140:143], v[172:175], 0
	v_mfma_f32_16x16x32_bf16 v[64:67], v[136:139], v[152:155], v[64:67]
	v_mfma_f32_16x16x32_bf16 v[60:63], v[144:147], v[152:155], v[60:63]
	v_mfma_f32_16x16x32_bf16 v[52:55], v[136:139], v[160:163], v[52:55]
	v_mfma_f32_16x16x32_bf16 v[44:47], v[144:147], v[160:163], v[44:47]
	v_mfma_f32_16x16x32_bf16 v[36:39], v[136:139], v[168:171], v[36:39]
	v_mfma_f32_16x16x32_bf16 v[28:31], v[144:147], v[168:171], v[28:31]
	v_mfma_f32_16x16x32_bf16 v[20:23], v[136:139], v[176:179], v[20:23]
	v_mfma_f32_16x16x32_bf16 v[12:15], v[144:147], v[176:179], v[12:15]
	v_mfma_f32_16x16x32_bf16 v[56:59], v[180:183], v[148:151], 0
	v_mfma_f32_16x16x32_bf16 v[48:51], v[188:191], v[148:151], 0
	v_mfma_f32_16x16x32_bf16 v[40:43], v[180:183], v[156:159], 0
	v_mfma_f32_16x16x32_bf16 v[32:35], v[188:191], v[156:159], 0
	v_mfma_f32_16x16x32_bf16 v[24:27], v[180:183], v[164:167], 0
	v_mfma_f32_16x16x32_bf16 v[16:19], v[188:191], v[164:167], 0
	v_mfma_f32_16x16x32_bf16 v[8:11], v[180:183], v[172:175], 0
	v_mfma_f32_16x16x32_bf16 v[4:7], v[188:191], v[172:175], 0
	v_mfma_f32_16x16x32_bf16 v[56:59], v[184:187], v[152:155], v[56:59]
	v_mfma_f32_16x16x32_bf16 v[48:51], v[202:205], v[152:155], v[48:51]
	v_mfma_f32_16x16x32_bf16 v[40:43], v[184:187], v[160:163], v[40:43]
	v_mfma_f32_16x16x32_bf16 v[32:35], v[202:205], v[160:163], v[32:35]
	v_mfma_f32_16x16x32_bf16 v[24:27], v[184:187], v[168:171], v[24:27]
	v_mfma_f32_16x16x32_bf16 v[16:19], v[202:205], v[168:171], v[16:19]
	v_mfma_f32_16x16x32_bf16 v[8:11], v[184:187], v[176:179], v[8:11]
	v_mfma_f32_16x16x32_bf16 v[4:7], v[202:205], v[176:179], v[4:7]
	s_barrier
	s_setprio 0
	s_add_i32 s52, 0, 0x18000
	v_add_u32_e32 v144, s52, v1
	ds_read_b128 v[132:135], v144
	ds_read_b128 v[136:139], v144 offset:1024
	ds_read_b128 v[140:143], v144 offset:2048
	ds_read_b128 v[144:147], v144 offset:3072
	s_add_u32 s24, s24, 0x80000
	s_addc_u32 s25, s25, 0
	ds_read_b128 v[148:151], v224 offset:32768
	ds_read_b128 v[152:155], v224 offset:33792
	ds_read_b128 v[156:159], v224 offset:34816
	ds_read_b128 v[160:163], v224 offset:35840
	ds_read_b128 v[164:167], v224 offset:36864
	ds_read_b128 v[168:171], v224 offset:37888
	ds_read_b128 v[172:175], v224 offset:38912
	ds_read_b128 v[176:179], v224 offset:39936
	s_mov_b32 m0, s36
	s_nop 0
	global_load_lds_dwordx4 v196, s[24:25]
	s_mov_b32 m0, s37
	s_nop 0
	global_load_lds_dwordx4 v194, s[24:25]
	s_add_i32 s24, 0, 0x1c000
	v_add_u32_e32 v202, s24, v1
	ds_read_b128 v[180:183], v202
	ds_read_b128 v[184:187], v202 offset:1024
	ds_read_b128 v[188:191], v202 offset:2048
	ds_read_b128 v[202:205], v202 offset:3072
	s_waitcnt lgkmcnt(0)
	s_setprio 1
	s_barrier
	v_mfma_f32_16x16x32_bf16 v[128:131], v[132:135], v[148:151], v[128:131]
	v_mfma_f32_16x16x32_bf16 v[124:127], v[140:143], v[148:151], v[124:127]
	v_mfma_f32_16x16x32_bf16 v[112:115], v[132:135], v[156:159], v[112:115]
	v_mfma_f32_16x16x32_bf16 v[108:111], v[140:143], v[156:159], v[108:111]
	v_mfma_f32_16x16x32_bf16 v[100:103], v[132:135], v[164:167], v[100:103]
	v_mfma_f32_16x16x32_bf16 v[92:95], v[140:143], v[164:167], v[92:95]
	v_mfma_f32_16x16x32_bf16 v[84:87], v[132:135], v[172:175], v[84:87]
	v_mfma_f32_16x16x32_bf16 v[76:79], v[140:143], v[172:175], v[76:79]
	v_mfma_f32_16x16x32_bf16 v[128:131], v[136:139], v[152:155], v[128:131]
	v_mfma_f32_16x16x32_bf16 v[124:127], v[144:147], v[152:155], v[124:127]
	v_mfma_f32_16x16x32_bf16 v[112:115], v[136:139], v[160:163], v[112:115]
	v_mfma_f32_16x16x32_bf16 v[108:111], v[144:147], v[160:163], v[108:111]
	v_mfma_f32_16x16x32_bf16 v[100:103], v[136:139], v[168:171], v[100:103]
	v_mfma_f32_16x16x32_bf16 v[92:95], v[144:147], v[168:171], v[92:95]
	v_mfma_f32_16x16x32_bf16 v[84:87], v[136:139], v[176:179], v[84:87]
	v_mfma_f32_16x16x32_bf16 v[76:79], v[144:147], v[176:179], v[76:79]
	v_mfma_f32_16x16x32_bf16 v[120:123], v[180:183], v[148:151], v[120:123]
	v_mfma_f32_16x16x32_bf16 v[116:119], v[188:191], v[148:151], v[116:119]
	v_mfma_f32_16x16x32_bf16 v[104:107], v[180:183], v[156:159], v[104:107]
	v_mfma_f32_16x16x32_bf16 v[96:99], v[188:191], v[156:159], v[96:99]
	v_mfma_f32_16x16x32_bf16 v[88:91], v[180:183], v[164:167], v[88:91]
	v_mfma_f32_16x16x32_bf16 v[80:83], v[188:191], v[164:167], v[80:83]
	v_mfma_f32_16x16x32_bf16 v[72:75], v[180:183], v[172:175], v[72:75]
	v_mfma_f32_16x16x32_bf16 v[68:71], v[188:191], v[172:175], v[68:71]
	v_mfma_f32_16x16x32_bf16 v[120:123], v[184:187], v[152:155], v[120:123]
	v_mfma_f32_16x16x32_bf16 v[116:119], v[202:205], v[152:155], v[116:119]
	v_mfma_f32_16x16x32_bf16 v[104:107], v[184:187], v[160:163], v[104:107]
	v_mfma_f32_16x16x32_bf16 v[96:99], v[202:205], v[160:163], v[96:99]
	v_mfma_f32_16x16x32_bf16 v[88:91], v[184:187], v[168:171], v[88:91]
	v_mfma_f32_16x16x32_bf16 v[80:83], v[202:205], v[168:171], v[80:83]
	v_mfma_f32_16x16x32_bf16 v[72:75], v[184:187], v[176:179], v[72:75]
	v_mfma_f32_16x16x32_bf16 v[68:71], v[202:205], v[176:179], v[68:71]
	s_barrier
; #define PG8_STAGE(bufoff, gbase, voff) do { _Pragma("unroll") for (int _i = 0; _i < 2; ++_i) \
;         __builtin_amdgcn_global_load_lds((const unsigned*)((const char*)(gbase) + (voff)[_i]), (LAS unsigned*)(lds + (bufoff) + ldsw + _i * 8192), 16, 0, 0); } while (0)
; #define PG8_LDA(dst, b, h) do { _Pragma("unroll") for (int m = 0; m < 4; ++m) _Pragma("unroll") for (int k = 0; k < 2; ++k) dst[m][k] = *(const LAS bf16x8*)(lds + PG8_SA(b, h) + aoff + m * 2048 + k * 1024); } while (0)
; #define PG8_MMA(ai, bj, At, Bt) do { __builtin_amdgcn_s_setprio(1); _Pragma("unroll") for (int m = 0; m < 4; ++m) _Pragma("unroll") for (int n = 0; n < 2; ++n) _Pragma("unroll") for (int k = 0; k < 2; ++k) \
;         acc[ai][bj][m][n] = __builtin_amdgcn_mfma_f32_16x16x32_bf16(Bt[n][k], At[m][k], acc[ai][bj][m][n], 0, 0, 0); __builtin_amdgcn_s_setprio(0); } while (0)
; #define PG8_WAIT_V(n) asm volatile("s_waitcnt vmcnt(" #n ")" ::: "memory")
; #define PG8_WAIT_L(n) asm volatile("s_waitcnt lgkmcnt(" #n ")" ::: "memory")
; #define PG8_BAR __builtin_amdgcn_s_barrier()
; #define PG8_SCHED __builtin_amdgcn_sched_barrier(0)
; template <class Epi, class Sched>
; __device__ __forceinline__ void gemm_phase(LAS unsigned char* lds, const Gemm g, const Sched& S, const Epi& E) {
;     ...
;             PG8_LDA(At, 1, 1); PG8_STAGE(PG8_SA(1, 0), a3, voffA);
;             PG8_BAR; PG8_WAIT_L(0); PG8_MMA(1, 0, At, B0); PG8_BAR; PG8_SCHED;
;             PG8_STAGE(PG8_SB(1, 1), b3 + hstepB, voffB);
;             PG8_WAIT_V(6); PG8_BAR; PG8_MMA(1, 1, At, B1); PG8_BAR;
	s_setprio 0
	ds_read_b128 v[148:151], v224 offset:49152
	ds_read_b128 v[152:155], v224 offset:50176
	ds_read_b128 v[156:159], v224 offset:51200
	ds_read_b128 v[160:163], v224 offset:52224
	ds_read_b128 v[164:167], v224 offset:53248
	ds_read_b128 v[168:171], v224 offset:54272
	ds_read_b128 v[172:175], v224 offset:55296
	ds_read_b128 v[176:179], v224 offset:56320
	s_add_i32 s25, s52, s30
	v_lshl_add_u64 v[206:207], v[206:207], 0, s[8:9]
	s_mov_b32 m0, s25
	s_nop 0
	global_load_lds_dwordx4 v[206:207], off
	v_lshl_add_u64 v[206:207], v[208:209], 0, s[8:9]
	s_add_i32 m0, s25, 0x2000
	s_nop 0
	global_load_lds_dwordx4 v[206:207], off
	s_mov_b32 m0, s42
	v_lshl_add_u64 v[206:207], v[210:211], 0, s[8:9]
	global_load_lds_dwordx4 v[206:207], off
	v_lshl_add_u64 v[206:207], v[212:213], 0, s[8:9]
	s_mov_b32 m0, s43
	s_nop 0
	global_load_lds_dwordx4 v[206:207], off
	s_add_u32 s20, s20, 0x80080
	s_addc_u32 s21, s21, 0
	s_add_i32 s24, s24, s30
	s_mov_b32 m0, s24
	s_nop 0
	global_load_lds_dwordx4 v2, s[20:21]
	s_add_i32 m0, s24, 0x2000
	s_nop 0
	global_load_lds_dwordx4 v192, s[20:21]
	s_add_i32 s51, s51, 2
	s_add_u32 s6, s6, 0x100
	s_addc_u32 s7, s7, 0
	s_add_u32 s49, s49, 0x100
	s_addc_u32 s50, s50, 0
	s_cmp_gt_u32 s51, 29
	s_waitcnt lgkmcnt(0)
	s_waitcnt vmcnt(6)
	s_setprio 1
	s_barrier
	v_mfma_f32_16x16x32_bf16 v[64:67], v[132:135], v[148:151], v[64:67]
	v_mfma_f32_16x16x32_bf16 v[60:63], v[140:143], v[148:151], v[60:63]
	v_mfma_f32_16x16x32_bf16 v[52:55], v[132:135], v[156:159], v[52:55]
	v_mfma_f32_16x16x32_bf16 v[44:47], v[140:143], v[156:159], v[44:47]
	v_mfma_f32_16x16x32_bf16 v[36:39], v[132:135], v[164:167], v[36:39]
	v_mfma_f32_16x16x32_bf16 v[28:31], v[140:143], v[164:167], v[28:31]
	v_mfma_f32_16x16x32_bf16 v[20:23], v[132:135], v[172:175], v[20:23]
	v_mfma_f32_16x16x32_bf16 v[12:15], v[140:143], v[172:175], v[12:15]
	v_mfma_f32_16x16x32_bf16 v[64:67], v[136:139], v[152:155], v[64:67]
	v_mfma_f32_16x16x32_bf16 v[60:63], v[144:147], v[152:155], v[60:63]
	v_mfma_f32_16x16x32_bf16 v[52:55], v[136:139], v[160:163], v[52:55]
	v_mfma_f32_16x16x32_bf16 v[44:47], v[144:147], v[160:163], v[44:47]
	v_mfma_f32_16x16x32_bf16 v[36:39], v[136:139], v[168:171], v[36:39]
	v_mfma_f32_16x16x32_bf16 v[28:31], v[144:147], v[168:171], v[28:31]
	v_mfma_f32_16x16x32_bf16 v[20:23], v[136:139], v[176:179], v[20:23]
	v_mfma_f32_16x16x32_bf16 v[12:15], v[144:147], v[176:179], v[12:15]
	v_mfma_f32_16x16x32_bf16 v[56:59], v[180:183], v[148:151], v[56:59]
	v_mfma_f32_16x16x32_bf16 v[48:51], v[188:191], v[148:151], v[48:51]
	v_mfma_f32_16x16x32_bf16 v[40:43], v[180:183], v[156:159], v[40:43]
	v_mfma_f32_16x16x32_bf16 v[32:35], v[188:191], v[156:159], v[32:35]
	v_mfma_f32_16x16x32_bf16 v[24:27], v[180:183], v[164:167], v[24:27]
	v_mfma_f32_16x16x32_bf16 v[16:19], v[188:191], v[164:167], v[16:19]
	v_mfma_f32_16x16x32_bf16 v[8:11], v[180:183], v[172:175], v[8:11]
	v_mfma_f32_16x16x32_bf16 v[4:7], v[188:191], v[172:175], v[4:7]
	v_mfma_f32_16x16x32_bf16 v[56:59], v[184:187], v[152:155], v[56:59]
	v_mfma_f32_16x16x32_bf16 v[48:51], v[202:205], v[152:155], v[48:51]
	v_mfma_f32_16x16x32_bf16 v[40:43], v[184:187], v[160:163], v[40:43]
	v_mfma_f32_16x16x32_bf16 v[32:35], v[202:205], v[160:163], v[32:35]
	v_mfma_f32_16x16x32_bf16 v[24:27], v[184:187], v[168:171], v[24:27]
	v_mfma_f32_16x16x32_bf16 v[16:19], v[202:205], v[168:171], v[16:19]
	v_mfma_f32_16x16x32_bf16 v[8:11], v[184:187], v[176:179], v[8:11]
	v_mfma_f32_16x16x32_bf16 v[4:7], v[202:205], v[176:179], v[4:7]
	s_barrier
	s_setprio 0
	.p2align	6

; #define PG8_STAGE(bufoff, gbase, voff) do { _Pragma("unroll") for (int _i = 0; _i < 2; ++_i) \
;         __builtin_amdgcn_global_load_lds((const unsigned*)((const char*)(gbase) + (voff)[_i]), (LAS unsigned*)(lds + (bufoff) + ldsw + _i * 8192), 16, 0, 0); } while (0)
; #define PG8_LDA(dst, b, h) do { _Pragma("unroll") for (int m = 0; m < 4; ++m) _Pragma("unroll") for (int k = 0; k < 2; ++k) dst[m][k] = *(const LAS bf16x8*)(lds + PG8_SA(b, h) + aoff + m * 2048 + k * 1024); } while (0)
; #define PG8_LDB(dst, b, h) do { _Pragma("unroll") for (int n = 0; n < 2; ++n) _Pragma("unroll") for (int k = 0; k < 2; ++k) dst[n][k] = *(const LAS bf16x8*)(lds + PG8_SB(b, h) + boff + n * 2048 + k * 1024); } while (0)
; #define PG8_WAIT_V(n) asm volatile("s_waitcnt vmcnt(" #n ")" ::: "memory")
; template <class Epi, class Sched>
; __device__ __forceinline__ void gemm_phase(LAS unsigned char* lds, const Gemm g, const Sched& S, const Epi& E) {
;     ...
;         const bool has_next = S.next(ui + 1, nxt);
;         const char* nA = has_next ? (const char*)g.A + (size_t)nxt.pm * tstepA : cA; const char* nB = has_next ? (const char*)g.Bt + (size_t)nxt.pn * tstepB : cB;
;         for (int t = 0; t < nt; t += 2) {
;             const bool last = (t == nt - 2);
;             const char* a1 = cA + (size_t)(t + 1) * kstep;
;             const char* a2 = last ? nA : cA + (size_t)(t + 2) * kstep; const char* b2 = last ? nB : cB + (size_t)(t + 2) * kstep;
;             const char* a3 = a2 + kstep; const char* b3 = b2 + kstep;
;             if (last && has_next) S.a_ready(nxt);
;             PG8_LDB(B0, 0, 0); PG8_SCHED; PG8_LDA(At, 0, 0); PG8_STAGE(PG8_SA(1, 1), a1 + hstepA, voffA);
;             PG8_WAIT_L(8); PG8_BAR; PG8_WAIT_L(0); PG8_MMA(0, 0, At, B0); PG8_BAR; PG8_SCHED;
;             PG8_LDB(B1, 0, 1); PG8_STAGE(PG8_SB(0, 0), b2, voffB);
;             PG8_BAR; PG8_WAIT_L(0); PG8_MMA(0, 1, At, B1); PG8_BAR;
;             PG8_LDA(At, 0, 1); PG8_STAGE(PG8_SA(0, 0), a2, voffA);
;             PG8_BAR; PG8_WAIT_L(0); PG8_MMA(1, 0, At, B0); PG8_BAR; PG8_SCHED;
;             PG8_STAGE(PG8_SB(0, 1), b2 + hstepB, voffB);
;             PG8_WAIT_V(6); PG8_BAR; PG8_MMA(1, 1, At, B1); PG8_BAR;
;             PG8_LDB(B0, 1, 0); PG8_SCHED; PG8_LDA(At, 1, 0); PG8_STAGE(PG8_SA(0, 1), a2 + hstepA, voffA);
;             PG8_WAIT_L(8); PG8_BAR; PG8_WAIT_L(0); PG8_MMA(0, 0, At, B0); PG8_BAR; PG8_SCHED;
.LBB0_1525:
	v_mov_b64_e32 v[4:5], 0x1600
	s_ashr_i32 s57, s56, 31
	v_cmp_lt_i64_e32 vcc, s[14:15], v[4:5]
	s_lshl_b64 s[14:15], s[56:57], 20
	s_add_u32 s58, s88, s14
	s_addc_u32 s59, s89, s15
	s_and_b64 s[14:15], vcc, exec
	s_cselect_b32 s57, s59, s5
	s_cselect_b32 s67, s58, s4
	s_ashr_i32 s55, s54, 31
	s_lshl_b64 s[14:15], s[54:55], 20
	s_add_u32 s60, s2, s14
	s_addc_u32 s61, s18, s15
	s_and_b64 s[14:15], vcc, exec
	s_cselect_b32 s55, s61, s7
	s_cselect_b32 s68, s60, s6
	s_add_u32 s4, s4, 0x80080
	s_addc_u32 s5, s5, 0
	s_add_u32 s69, s6, 0x100
	s_addc_u32 s70, s7, 0
	s_mov_b32 s71, -2
	s_setprio 0
	s_add_u32 s6, s4, 0xfff80080
	s_addc_u32 s7, s5, -1
	s_add_i32 s72, 0, 0x10000
	v_add_u32_e32 v2, s72, v1
	ds_read_b128 v[132:135], v2
	ds_read_b128 v[136:139], v2 offset:1024
	ds_read_b128 v[140:143], v2 offset:2048
	ds_read_b128 v[144:147], v2 offset:3072
	s_cmp_eq_u32 s71, 28
	s_cselect_b32 s15, s57, s7
	s_cselect_b32 s14, s67, s6
	s_cselect_b32 s7, s55, s70
	s_cselect_b32 s6, s68, s69
	ds_read_b128 v[148:151], v207
	ds_read_b128 v[152:155], v207 offset:1024
	ds_read_b128 v[156:159], v207 offset:2048
	ds_read_b128 v[160:163], v207 offset:3072
	ds_read_b128 v[164:167], v207 offset:4096
	ds_read_b128 v[168:171], v207 offset:5120
	ds_read_b128 v[186:189], v207 offset:6144
	ds_read_b128 v[190:193], v207 offset:7168
	s_add_i32 s74, 0, 0x14000
	v_add_u32_e32 v2, s74, v1
	ds_read_b128 v[194:197], v2
	ds_read_b128 v[198:201], v2 offset:1024
	ds_read_b128 v[202:205], v2 offset:2048
	ds_read_b128 v[208:211], v2 offset:3072
	s_add_i32 m0, s20, 0xc000
	s_nop 0
	global_load_lds_dwordx4 v182, s[4:5]
	s_add_i32 m0, s20, 0xe000
	s_nop 0
	global_load_lds_dwordx4 v184, s[4:5]
	s_waitcnt lgkmcnt(0)
	s_setprio 1
	s_barrier
	v_mfma_f32_16x16x32_bf16 v[68:71], v[132:135], v[148:151], 0
	v_mfma_f32_16x16x32_bf16 v[72:75], v[140:143], v[148:151], 0
	v_mfma_f32_16x16x32_bf16 v[120:123], v[132:135], v[156:159], 0
	v_mfma_f32_16x16x32_bf16 v[116:119], v[140:143], v[156:159], 0
	v_mfma_f32_16x16x32_bf16 v[112:115], v[132:135], v[164:167], 0
	v_mfma_f32_16x16x32_bf16 v[108:111], v[140:143], v[164:167], 0
	v_mfma_f32_16x16x32_bf16 v[104:107], v[132:135], v[186:189], 0
	v_mfma_f32_16x16x32_bf16 v[100:103], v[140:143], v[186:189], 0
	v_mfma_f32_16x16x32_bf16 v[68:71], v[136:139], v[152:155], v[68:71]
	v_mfma_f32_16x16x32_bf16 v[72:75], v[144:147], v[152:155], v[72:75]
	v_mfma_f32_16x16x32_bf16 v[120:123], v[136:139], v[160:163], v[120:123]
	v_mfma_f32_16x16x32_bf16 v[116:119], v[144:147], v[160:163], v[116:119]
	v_mfma_f32_16x16x32_bf16 v[112:115], v[136:139], v[168:171], v[112:115]
	v_mfma_f32_16x16x32_bf16 v[108:111], v[144:147], v[168:171], v[108:111]
	v_mfma_f32_16x16x32_bf16 v[104:107], v[136:139], v[190:193], v[104:107]
	v_mfma_f32_16x16x32_bf16 v[100:103], v[144:147], v[190:193], v[100:103]
	v_mfma_f32_16x16x32_bf16 v[76:79], v[194:197], v[148:151], 0
	v_mfma_f32_16x16x32_bf16 v[80:83], v[202:205], v[148:151], 0
	v_mfma_f32_16x16x32_bf16 v[96:99], v[194:197], v[156:159], 0
	v_mfma_f32_16x16x32_bf16 v[92:95], v[202:205], v[156:159], 0
	v_mfma_f32_16x16x32_bf16 v[88:91], v[194:197], v[164:167], 0
	v_mfma_f32_16x16x32_bf16 v[84:87], v[202:205], v[164:167], 0
	v_mfma_f32_16x16x32_bf16 v[128:131], v[194:197], v[186:189], 0
	v_mfma_f32_16x16x32_bf16 v[124:127], v[202:205], v[186:189], 0
	v_mfma_f32_16x16x32_bf16 v[76:79], v[198:201], v[152:155], v[76:79]
	v_mfma_f32_16x16x32_bf16 v[80:83], v[208:211], v[152:155], v[80:83]
	v_mfma_f32_16x16x32_bf16 v[96:99], v[198:201], v[160:163], v[96:99]
	v_mfma_f32_16x16x32_bf16 v[92:95], v[208:211], v[160:163], v[92:95]
	v_mfma_f32_16x16x32_bf16 v[88:91], v[198:201], v[168:171], v[88:91]
	v_mfma_f32_16x16x32_bf16 v[84:87], v[208:211], v[168:171], v[84:87]
	v_mfma_f32_16x16x32_bf16 v[128:131], v[198:201], v[190:193], v[128:131]
	v_mfma_f32_16x16x32_bf16 v[124:127], v[208:211], v[190:193], v[124:127]
	s_barrier
	s_setprio 0
	ds_read_b128 v[148:151], v207 offset:16384
	ds_read_b128 v[152:155], v207 offset:17408
	ds_read_b128 v[156:159], v207 offset:18432
	ds_read_b128 v[160:163], v207 offset:19456
	ds_read_b128 v[164:167], v207 offset:20480
	ds_read_b128 v[168:171], v207 offset:21504
	ds_read_b128 v[186:189], v207 offset:22528
	ds_read_b128 v[190:193], v207 offset:23552
	s_add_i32 s72, s72, s19
	v_lshl_add_u64 v[172:173], s[6:7], 0, v[178:179]
	s_mov_b32 m0, s72
	s_nop 0
	global_load_lds_dwordx4 v[172:173], off
	v_lshl_add_u64 v[212:213], s[6:7], 0, v[174:175]
	s_add_i32 m0, s72, 0x2000
	s_nop 0
	global_load_lds_dwordx4 v[212:213], off
	s_mov_b32 m0, s20
	v_lshl_add_u64 v[216:217], s[14:15], 0, v[180:181]
	global_load_lds_dwordx4 v[216:217], off
	v_lshl_add_u64 v[218:219], s[14:15], 0, v[176:177]
	s_mov_b32 m0, s21
	s_nop 0
	global_load_lds_dwordx4 v[218:219], off
	s_add_u32 s72, s6, 0x80000
	s_addc_u32 s73, s7, 0
	s_add_i32 s74, s74, s19
	s_mov_b32 m0, s74
	s_nop 0
	global_load_lds_dwordx4 v178, s[72:73]
	s_add_i32 m0, s74, 0x2000
	s_nop 0
	global_load_lds_dwordx4 v174, s[72:73]
	s_waitcnt lgkmcnt(0)
	s_waitcnt vmcnt(6)
	s_setprio 1
	s_barrier
; #define PG8_STAGE(bufoff, gbase, voff) do { _Pragma("unroll") for (int _i = 0; _i < 2; ++_i) \
;         __builtin_amdgcn_global_load_lds((const unsigned*)((const char*)(gbase) + (voff)[_i]), (LAS unsigned*)(lds + (bufoff) + ldsw + _i * 8192), 16, 0, 0); } while (0)
; #define PG8_LDA(dst, b, h) do { _Pragma("unroll") for (int m = 0; m < 4; ++m) _Pragma("unroll") for (int k = 0; k < 2; ++k) dst[m][k] = *(const LAS bf16x8*)(lds + PG8_SA(b, h) + aoff + m * 2048 + k * 1024); } while (0)
; #define PG8_LDB(dst, b, h) do { _Pragma("unroll") for (int n = 0; n < 2; ++n) _Pragma("unroll") for (int k = 0; k < 2; ++k) dst[n][k] = *(const LAS bf16x8*)(lds + PG8_SB(b, h) + boff + n * 2048 + k * 1024); } while (0)
; #define PG8_MMA(ai, bj, At, Bt) do { __builtin_amdgcn_s_setprio(1); _Pragma("unroll") for (int m = 0; m < 4; ++m) _Pragma("unroll") for (int n = 0; n < 2; ++n) _Pragma("unroll") for (int k = 0; k < 2; ++k) \
;         acc[ai][bj][m][n] = __builtin_amdgcn_mfma_f32_16x16x32_bf16(Bt[n][k], At[m][k], acc[ai][bj][m][n], 0, 0, 0); __builtin_amdgcn_s_setprio(0); } while (0)
; #define PG8_WAIT_V(n) asm volatile("s_waitcnt vmcnt(" #n ")" ::: "memory")
; #define PG8_WAIT_L(n) asm volatile("s_waitcnt lgkmcnt(" #n ")" ::: "memory")
; #define PG8_BAR __builtin_amdgcn_s_barrier()
; #define PG8_SCHED __builtin_amdgcn_sched_barrier(0)
; template <class Epi, class Sched>
; __device__ __forceinline__ void gemm_phase(LAS unsigned char* lds, const Gemm g, const Sched& S, const Epi& E) {
;     ...
;             PG8_BAR; PG8_WAIT_L(0); PG8_MMA(1, 0, At, B0); PG8_BAR; PG8_SCHED;
;             PG8_STAGE(PG8_SB(0, 1), b2 + hstepB, voffB);
;             PG8_WAIT_V(6); PG8_BAR; PG8_MMA(1, 1, At, B1); PG8_BAR;
;             PG8_LDB(B0, 1, 0); PG8_SCHED; PG8_LDA(At, 1, 0); PG8_STAGE(PG8_SA(0, 1), a2 + hstepA, voffA);
;             PG8_WAIT_L(8); PG8_BAR; PG8_WAIT_L(0); PG8_MMA(0, 0, At, B0); PG8_BAR; PG8_SCHED;
;             PG8_LDB(B1, 1, 1); PG8_STAGE(PG8_SB(1, 0), b3, voffB);
;             PG8_BAR; PG8_WAIT_L(0); PG8_MMA(0, 1, At, B1); PG8_BAR;
;             PG8_LDA(At, 1, 1); PG8_STAGE(PG8_SA(1, 0), a3, voffA);
;             PG8_BAR; PG8_WAIT_L(0); PG8_MMA(1, 0, At, B0); PG8_BAR; PG8_SCHED;
	v_mfma_f32_16x16x32_bf16 v[56:59], v[132:135], v[148:151], 0
	v_mfma_f32_16x16x32_bf16 v[52:55], v[140:143], v[148:151], 0
	v_mfma_f32_16x16x32_bf16 v[48:51], v[132:135], v[156:159], 0
	v_mfma_f32_16x16x32_bf16 v[44:47], v[140:143], v[156:159], 0
	v_mfma_f32_16x16x32_bf16 v[40:43], v[132:135], v[164:167], 0
	v_mfma_f32_16x16x32_bf16 v[36:39], v[140:143], v[164:167], 0
	v_mfma_f32_16x16x32_bf16 v[32:35], v[132:135], v[186:189], 0
	v_mfma_f32_16x16x32_bf16 v[28:31], v[140:143], v[186:189], 0
	v_mfma_f32_16x16x32_bf16 v[56:59], v[136:139], v[152:155], v[56:59]
	v_mfma_f32_16x16x32_bf16 v[52:55], v[144:147], v[152:155], v[52:55]
	v_mfma_f32_16x16x32_bf16 v[48:51], v[136:139], v[160:163], v[48:51]
	v_mfma_f32_16x16x32_bf16 v[44:47], v[144:147], v[160:163], v[44:47]
	v_mfma_f32_16x16x32_bf16 v[40:43], v[136:139], v[168:171], v[40:43]
	v_mfma_f32_16x16x32_bf16 v[36:39], v[144:147], v[168:171], v[36:39]
	v_mfma_f32_16x16x32_bf16 v[32:35], v[136:139], v[190:193], v[32:35]
	v_mfma_f32_16x16x32_bf16 v[28:31], v[144:147], v[190:193], v[28:31]
	v_mfma_f32_16x16x32_bf16 v[24:27], v[194:197], v[148:151], 0
	v_mfma_f32_16x16x32_bf16 v[20:23], v[202:205], v[148:151], 0
	v_mfma_f32_16x16x32_bf16 v[16:19], v[194:197], v[156:159], 0
	v_mfma_f32_16x16x32_bf16 v[12:15], v[202:205], v[156:159], 0
	v_mfma_f32_16x16x32_bf16 v[8:11], v[194:197], v[164:167], 0
	v_mfma_f32_16x16x32_bf16 v[4:7], v[202:205], v[164:167], 0
	v_mfma_f32_16x16x32_bf16 v[60:63], v[194:197], v[186:189], 0
	v_mfma_f32_16x16x32_bf16 v[64:67], v[202:205], v[186:189], 0
	v_mfma_f32_16x16x32_bf16 v[24:27], v[198:201], v[152:155], v[24:27]
	v_mfma_f32_16x16x32_bf16 v[20:23], v[208:211], v[152:155], v[20:23]
	v_mfma_f32_16x16x32_bf16 v[16:19], v[198:201], v[160:163], v[16:19]
	v_mfma_f32_16x16x32_bf16 v[12:15], v[208:211], v[160:163], v[12:15]
	v_mfma_f32_16x16x32_bf16 v[8:11], v[198:201], v[168:171], v[8:11]
	v_mfma_f32_16x16x32_bf16 v[4:7], v[208:211], v[168:171], v[4:7]
	v_mfma_f32_16x16x32_bf16 v[60:63], v[198:201], v[190:193], v[60:63]
	v_mfma_f32_16x16x32_bf16 v[64:67], v[208:211], v[190:193], v[64:67]
	s_barrier
	s_setprio 0
	s_add_i32 s72, 0, 0x18000
	v_add_u32_e32 v2, s72, v1
	ds_read_b128 v[132:135], v2
	ds_read_b128 v[136:139], v2 offset:1024
	ds_read_b128 v[140:143], v2 offset:2048
	ds_read_b128 v[144:147], v2 offset:3072
	s_add_u32 s14, s14, 0x80000
	s_addc_u32 s15, s15, 0
	ds_read_b128 v[148:151], v207 offset:32768
	ds_read_b128 v[152:155], v207 offset:33792
	ds_read_b128 v[156:159], v207 offset:34816
	ds_read_b128 v[160:163], v207 offset:35840
	ds_read_b128 v[164:167], v207 offset:36864
	ds_read_b128 v[168:171], v207 offset:37888
	ds_read_b128 v[186:189], v207 offset:38912
	ds_read_b128 v[190:193], v207 offset:39936
	s_mov_b32 m0, s24
	s_nop 0
	global_load_lds_dwordx4 v180, s[14:15]
	s_mov_b32 m0, s25
	s_nop 0
	global_load_lds_dwordx4 v176, s[14:15]
	s_add_i32 s14, 0, 0x1c000
	v_add_u32_e32 v2, s14, v1
	ds_read_b128 v[194:197], v2
	ds_read_b128 v[198:201], v2 offset:1024
	ds_read_b128 v[202:205], v2 offset:2048
	ds_read_b128 v[208:211], v2 offset:3072
	s_waitcnt lgkmcnt(0)
	s_setprio 1
	s_barrier
	v_mfma_f32_16x16x32_bf16 v[68:71], v[132:135], v[148:151], v[68:71]
	v_mfma_f32_16x16x32_bf16 v[72:75], v[140:143], v[148:151], v[72:75]
	v_mfma_f32_16x16x32_bf16 v[120:123], v[132:135], v[156:159], v[120:123]
	v_mfma_f32_16x16x32_bf16 v[116:119], v[140:143], v[156:159], v[116:119]
	v_mfma_f32_16x16x32_bf16 v[112:115], v[132:135], v[164:167], v[112:115]
	v_mfma_f32_16x16x32_bf16 v[108:111], v[140:143], v[164:167], v[108:111]
	v_mfma_f32_16x16x32_bf16 v[104:107], v[132:135], v[186:189], v[104:107]
	v_mfma_f32_16x16x32_bf16 v[100:103], v[140:143], v[186:189], v[100:103]
	v_mfma_f32_16x16x32_bf16 v[68:71], v[136:139], v[152:155], v[68:71]
	v_mfma_f32_16x16x32_bf16 v[72:75], v[144:147], v[152:155], v[72:75]
	v_mfma_f32_16x16x32_bf16 v[120:123], v[136:139], v[160:163], v[120:123]
	v_mfma_f32_16x16x32_bf16 v[116:119], v[144:147], v[160:163], v[116:119]
	v_mfma_f32_16x16x32_bf16 v[112:115], v[136:139], v[168:171], v[112:115]
	v_mfma_f32_16x16x32_bf16 v[108:111], v[144:147], v[168:171], v[108:111]
	v_mfma_f32_16x16x32_bf16 v[104:107], v[136:139], v[190:193], v[104:107]
	v_mfma_f32_16x16x32_bf16 v[100:103], v[144:147], v[190:193], v[100:103]
	v_mfma_f32_16x16x32_bf16 v[76:79], v[194:197], v[148:151], v[76:79]
	v_mfma_f32_16x16x32_bf16 v[80:83], v[202:205], v[148:151], v[80:83]
	v_mfma_f32_16x16x32_bf16 v[96:99], v[194:197], v[156:159], v[96:99]
	v_mfma_f32_16x16x32_bf16 v[92:95], v[202:205], v[156:159], v[92:95]
	v_mfma_f32_16x16x32_bf16 v[88:91], v[194:197], v[164:167], v[88:91]
	v_mfma_f32_16x16x32_bf16 v[84:87], v[202:205], v[164:167], v[84:87]
	v_mfma_f32_16x16x32_bf16 v[128:131], v[194:197], v[186:189], v[128:131]
	v_mfma_f32_16x16x32_bf16 v[124:127], v[202:205], v[186:189], v[124:127]
	v_mfma_f32_16x16x32_bf16 v[76:79], v[198:201], v[152:155], v[76:79]
	v_mfma_f32_16x16x32_bf16 v[80:83], v[208:211], v[152:155], v[80:83]
	v_mfma_f32_16x16x32_bf16 v[96:99], v[198:201], v[160:163], v[96:99]
	v_mfma_f32_16x16x32_bf16 v[92:95], v[208:211], v[160:163], v[92:95]
	v_mfma_f32_16x16x32_bf16 v[88:91], v[198:201], v[168:171], v[88:91]
	v_mfma_f32_16x16x32_bf16 v[84:87], v[208:211], v[168:171], v[84:87]
	v_mfma_f32_16x16x32_bf16 v[128:131], v[198:201], v[190:193], v[128:131]
	v_mfma_f32_16x16x32_bf16 v[124:127], v[208:211], v[190:193], v[124:127]
	s_barrier
; #define PG8_STAGE(bufoff, gbase, voff) do { _Pragma("unroll") for (int _i = 0; _i < 2; ++_i) \
;         __builtin_amdgcn_global_load_lds((const unsigned*)((const char*)(gbase) + (voff)[_i]), (LAS unsigned*)(lds + (bufoff) + ldsw + _i * 8192), 16, 0, 0); } while (0)
; #define PG8_LDA(dst, b, h) do { _Pragma("unroll") for (int m = 0; m < 4; ++m) _Pragma("unroll") for (int k = 0; k < 2; ++k) dst[m][k] = *(const LAS bf16x8*)(lds + PG8_SA(b, h) + aoff + m * 2048 + k * 1024); } while (0)
; #define PG8_MMA(ai, bj, At, Bt) do { __builtin_amdgcn_s_setprio(1); _Pragma("unroll") for (int m = 0; m < 4; ++m) _Pragma("unroll") for (int n = 0; n < 2; ++n) _Pragma("unroll") for (int k = 0; k < 2; ++k) \
;         acc[ai][bj][m][n] = __builtin_amdgcn_mfma_f32_16x16x32_bf16(Bt[n][k], At[m][k], acc[ai][bj][m][n], 0, 0, 0); __builtin_amdgcn_s_setprio(0); } while (0)
; #define PG8_WAIT_V(n) asm volatile("s_waitcnt vmcnt(" #n ")" ::: "memory")
; #define PG8_WAIT_L(n) asm volatile("s_waitcnt lgkmcnt(" #n ")" ::: "memory")
; #define PG8_BAR __builtin_amdgcn_s_barrier()
; #define PG8_SCHED __builtin_amdgcn_sched_barrier(0)
; template <class Epi, class Sched>
; __device__ __forceinline__ void gemm_phase(LAS unsigned char* lds, const Gemm g, const Sched& S, const Epi& E) {
;     ...
;             PG8_LDA(At, 1, 1); PG8_STAGE(PG8_SA(1, 0), a3, voffA);
;             PG8_BAR; PG8_WAIT_L(0); PG8_MMA(1, 0, At, B0); PG8_BAR; PG8_SCHED;
;             PG8_STAGE(PG8_SB(1, 1), b3 + hstepB, voffB);
;             PG8_WAIT_V(6); PG8_BAR; PG8_MMA(1, 1, At, B1); PG8_BAR;
	s_setprio 0
	ds_read_b128 v[148:151], v207 offset:49152
	ds_read_b128 v[152:155], v207 offset:50176
	ds_read_b128 v[156:159], v207 offset:51200
	ds_read_b128 v[160:163], v207 offset:52224
	ds_read_b128 v[164:167], v207 offset:53248
	ds_read_b128 v[168:171], v207 offset:54272
	ds_read_b128 v[186:189], v207 offset:55296
	ds_read_b128 v[190:193], v207 offset:56320
	s_add_i32 s15, s72, s19
	v_lshl_add_u64 v[172:173], v[172:173], 0, s[8:9]
	s_mov_b32 m0, s15
	s_nop 0
	global_load_lds_dwordx4 v[172:173], off
	v_lshl_add_u64 v[172:173], v[212:213], 0, s[8:9]
	s_add_i32 m0, s15, 0x2000
	s_nop 0
	global_load_lds_dwordx4 v[172:173], off
	s_mov_b32 m0, s30
	v_lshl_add_u64 v[172:173], v[216:217], 0, s[8:9]
	global_load_lds_dwordx4 v[172:173], off
	v_lshl_add_u64 v[172:173], v[218:219], 0, s[8:9]
	s_mov_b32 m0, s31
	s_nop 0
	global_load_lds_dwordx4 v[172:173], off
	s_add_u32 s6, s6, 0x80080
	s_addc_u32 s7, s7, 0
	s_add_i32 s14, s14, s19
	s_mov_b32 m0, s14
	s_nop 0
	global_load_lds_dwordx4 v178, s[6:7]
	s_add_i32 m0, s14, 0x2000
	s_nop 0
	global_load_lds_dwordx4 v174, s[6:7]
	s_add_i32 s71, s71, 2
	s_add_u32 s4, s4, 0x100
	s_addc_u32 s5, s5, 0
	s_add_u32 s69, s69, 0x100
	s_addc_u32 s70, s70, 0
	s_cmp_gt_u32 s71, 29
	s_waitcnt lgkmcnt(0)
	s_waitcnt vmcnt(6)
	s_setprio 1
	s_barrier
	v_mfma_f32_16x16x32_bf16 v[56:59], v[132:135], v[148:151], v[56:59]
	v_mfma_f32_16x16x32_bf16 v[52:55], v[140:143], v[148:151], v[52:55]
	v_mfma_f32_16x16x32_bf16 v[48:51], v[132:135], v[156:159], v[48:51]
	v_mfma_f32_16x16x32_bf16 v[44:47], v[140:143], v[156:159], v[44:47]
	v_mfma_f32_16x16x32_bf16 v[40:43], v[132:135], v[164:167], v[40:43]
	v_mfma_f32_16x16x32_bf16 v[36:39], v[140:143], v[164:167], v[36:39]
	v_mfma_f32_16x16x32_bf16 v[32:35], v[132:135], v[186:189], v[32:35]
	v_mfma_f32_16x16x32_bf16 v[28:31], v[140:143], v[186:189], v[28:31]
	v_mfma_f32_16x16x32_bf16 v[56:59], v[136:139], v[152:155], v[56:59]
	v_mfma_f32_16x16x32_bf16 v[52:55], v[144:147], v[152:155], v[52:55]
	v_mfma_f32_16x16x32_bf16 v[48:51], v[136:139], v[160:163], v[48:51]
	v_mfma_f32_16x16x32_bf16 v[44:47], v[144:147], v[160:163], v[44:47]
	v_mfma_f32_16x16x32_bf16 v[40:43], v[136:139], v[168:171], v[40:43]
	v_mfma_f32_16x16x32_bf16 v[36:39], v[144:147], v[168:171], v[36:39]
	v_mfma_f32_16x16x32_bf16 v[32:35], v[136:139], v[190:193], v[32:35]
	v_mfma_f32_16x16x32_bf16 v[28:31], v[144:147], v[190:193], v[28:31]
	v_mfma_f32_16x16x32_bf16 v[24:27], v[194:197], v[148:151], v[24:27]
	v_mfma_f32_16x16x32_bf16 v[20:23], v[202:205], v[148:151], v[20:23]
	v_mfma_f32_16x16x32_bf16 v[16:19], v[194:197], v[156:159], v[16:19]
	v_mfma_f32_16x16x32_bf16 v[12:15], v[202:205], v[156:159], v[12:15]
	v_mfma_f32_16x16x32_bf16 v[8:11], v[194:197], v[164:167], v[8:11]
	v_mfma_f32_16x16x32_bf16 v[4:7], v[202:205], v[164:167], v[4:7]
	v_mfma_f32_16x16x32_bf16 v[60:63], v[194:197], v[186:189], v[60:63]
	v_mfma_f32_16x16x32_bf16 v[64:67], v[202:205], v[186:189], v[64:67]
	v_mfma_f32_16x16x32_bf16 v[24:27], v[198:201], v[152:155], v[24:27]
	v_mfma_f32_16x16x32_bf16 v[20:23], v[208:211], v[152:155], v[20:23]
	v_mfma_f32_16x16x32_bf16 v[16:19], v[198:201], v[160:163], v[16:19]
	v_mfma_f32_16x16x32_bf16 v[12:15], v[208:211], v[160:163], v[12:15]
	v_mfma_f32_16x16x32_bf16 v[8:11], v[198:201], v[168:171], v[8:11]
	v_mfma_f32_16x16x32_bf16 v[4:7], v[208:211], v[168:171], v[4:7]
	v_mfma_f32_16x16x32_bf16 v[60:63], v[198:201], v[190:193], v[60:63]
	v_mfma_f32_16x16x32_bf16 v[64:67], v[208:211], v[190:193], v[64:67]
	s_barrier
	s_setprio 0
	.p2align	6

; #define PG8_STAGE(bufoff, gbase, voff) do { _Pragma("unroll") for (int _i = 0; _i < 2; ++_i) \
;         __builtin_amdgcn_global_load_lds((const unsigned*)((const char*)(gbase) + (voff)[_i]), (LAS unsigned*)(lds + (bufoff) + ldsw + _i * 8192), 16, 0, 0); } while (0)
; #define PG8_LDA(dst, b, h) do { _Pragma("unroll") for (int m = 0; m < 4; ++m) _Pragma("unroll") for (int k = 0; k < 2; ++k) dst[m][k] = *(const LAS bf16x8*)(lds + PG8_SA(b, h) + aoff + m * 2048 + k * 1024); } while (0)
; #define PG8_LDB(dst, b, h) do { _Pragma("unroll") for (int n = 0; n < 2; ++n) _Pragma("unroll") for (int k = 0; k < 2; ++k) dst[n][k] = *(const LAS bf16x8*)(lds + PG8_SB(b, h) + boff + n * 2048 + k * 1024); } while (0)
; #define PG8_WAIT_V(n) asm volatile("s_waitcnt vmcnt(" #n ")" ::: "memory")
; #define PG8_WAIT_L(n) asm volatile("s_waitcnt lgkmcnt(" #n ")" ::: "memory")
; #define PG8_BAR __builtin_amdgcn_s_barrier()
; #define PG8_SCHED __builtin_amdgcn_sched_barrier(0)
; template <class Epi, class Sched>
; __device__ __forceinline__ void gemm_phase(LAS unsigned char* lds, const Gemm g, const Sched& S, const Epi& E) {
;     ...
;         const char* nA = has_next ? (const char*)g.A + (size_t)nxt.pm * tstepA : cA; const char* nB = has_next ? (const char*)g.Bt + (size_t)nxt.pn * tstepB : cB;
;         for (int t = 0; t < nt; t += 2) {
;             const bool last = (t == nt - 2);
;             const char* a1 = cA + (size_t)(t + 1) * kstep;
;             const char* a2 = last ? nA : cA + (size_t)(t + 2) * kstep; const char* b2 = last ? nB : cB + (size_t)(t + 2) * kstep;
;             const char* a3 = a2 + kstep; const char* b3 = b2 + kstep;
;             if (last && has_next) S.a_ready(nxt);
;             PG8_LDB(B0, 0, 0); PG8_SCHED; PG8_LDA(At, 0, 0); PG8_STAGE(PG8_SA(1, 1), a1 + hstepA, voffA);
;             PG8_WAIT_L(8); PG8_BAR; PG8_WAIT_L(0); PG8_MMA(0, 0, At, B0); PG8_BAR; PG8_SCHED;
;             PG8_LDB(B1, 0, 1); PG8_STAGE(PG8_SB(0, 0), b2, voffB);
;             PG8_BAR; PG8_WAIT_L(0); PG8_MMA(0, 1, At, B1); PG8_BAR;
;             PG8_LDA(At, 0, 1); PG8_STAGE(PG8_SA(0, 0), a2, voffA);
;             PG8_BAR; PG8_WAIT_L(0); PG8_MMA(1, 0, At, B0); PG8_BAR; PG8_SCHED;
;             PG8_STAGE(PG8_SB(0, 1), b2 + hstepB, voffB);
;             PG8_WAIT_V(6); PG8_BAR; PG8_MMA(1, 1, At, B1); PG8_BAR;
.LBB0_1665:
	s_add_u32 s42, s14, 0x100
	s_addc_u32 s43, s15, 0
	s_mov_b32 s44, -2
	s_setprio 0
	s_add_u32 s14, s6, 0x100
	s_addc_u32 s15, s7, 0
	s_add_i32 s45, 0, 0x10000
	v_add_u32_e32 v144, s45, v1
	ds_read_b128 v[132:135], v144
	ds_read_b128 v[136:139], v144 offset:1024
	ds_read_b128 v[140:143], v144 offset:2048
	ds_read_b128 v[144:147], v144 offset:3072
	s_cmpk_eq_i32 s44, 0x54
	s_cselect_b32 s21, s1, s15
	s_cselect_b32 s20, s0, s14
	s_cselect_b32 s19, s5, s43
	s_cselect_b32 s18, s4, s42
	ds_read_b128 v[148:151], v224
	ds_read_b128 v[152:155], v224 offset:1024
	ds_read_b128 v[156:159], v224 offset:2048
	ds_read_b128 v[160:163], v224 offset:3072
	ds_read_b128 v[164:167], v224 offset:4096
	ds_read_b128 v[168:171], v224 offset:5120
	ds_read_b128 v[172:175], v224 offset:6144
	ds_read_b128 v[176:179], v224 offset:7168
	s_add_i32 s51, 0, 0x14000
	v_add_u32_e32 v202, s51, v1
	ds_read_b128 v[180:183], v202
	ds_read_b128 v[184:187], v202 offset:1024
	ds_read_b128 v[188:191], v202 offset:2048
	ds_read_b128 v[202:205], v202 offset:3072
	s_add_i32 m0, s29, 0xc000
	s_nop 0
	global_load_lds_dwordx4 v198, s[6:7]
	s_add_i32 m0, s29, 0xe000
	s_nop 0
	global_load_lds_dwordx4 v200, s[6:7]
	s_waitcnt lgkmcnt(0)
	s_setprio 1
	s_barrier
	v_mfma_f32_16x16x32_bf16 v[128:131], v[132:135], v[148:151], 0
	v_mfma_f32_16x16x32_bf16 v[124:127], v[140:143], v[148:151], 0
	v_mfma_f32_16x16x32_bf16 v[112:115], v[132:135], v[156:159], 0
	v_mfma_f32_16x16x32_bf16 v[108:111], v[140:143], v[156:159], 0
	v_mfma_f32_16x16x32_bf16 v[100:103], v[132:135], v[164:167], 0
	v_mfma_f32_16x16x32_bf16 v[92:95], v[140:143], v[164:167], 0
	v_mfma_f32_16x16x32_bf16 v[84:87], v[132:135], v[172:175], 0
	v_mfma_f32_16x16x32_bf16 v[76:79], v[140:143], v[172:175], 0
	v_mfma_f32_16x16x32_bf16 v[128:131], v[136:139], v[152:155], v[128:131]
	v_mfma_f32_16x16x32_bf16 v[124:127], v[144:147], v[152:155], v[124:127]
	v_mfma_f32_16x16x32_bf16 v[112:115], v[136:139], v[160:163], v[112:115]
	v_mfma_f32_16x16x32_bf16 v[108:111], v[144:147], v[160:163], v[108:111]
	v_mfma_f32_16x16x32_bf16 v[100:103], v[136:139], v[168:171], v[100:103]
	v_mfma_f32_16x16x32_bf16 v[92:95], v[144:147], v[168:171], v[92:95]
	v_mfma_f32_16x16x32_bf16 v[84:87], v[136:139], v[176:179], v[84:87]
	v_mfma_f32_16x16x32_bf16 v[76:79], v[144:147], v[176:179], v[76:79]
	v_mfma_f32_16x16x32_bf16 v[120:123], v[180:183], v[148:151], 0
	v_mfma_f32_16x16x32_bf16 v[116:119], v[188:191], v[148:151], 0
	v_mfma_f32_16x16x32_bf16 v[104:107], v[180:183], v[156:159], 0
	v_mfma_f32_16x16x32_bf16 v[96:99], v[188:191], v[156:159], 0
	v_mfma_f32_16x16x32_bf16 v[88:91], v[180:183], v[164:167], 0
	v_mfma_f32_16x16x32_bf16 v[80:83], v[188:191], v[164:167], 0
	v_mfma_f32_16x16x32_bf16 v[72:75], v[180:183], v[172:175], 0
	v_mfma_f32_16x16x32_bf16 v[68:71], v[188:191], v[172:175], 0
	v_mfma_f32_16x16x32_bf16 v[120:123], v[184:187], v[152:155], v[120:123]
	v_mfma_f32_16x16x32_bf16 v[116:119], v[202:205], v[152:155], v[116:119]
	v_mfma_f32_16x16x32_bf16 v[104:107], v[184:187], v[160:163], v[104:107]
	v_mfma_f32_16x16x32_bf16 v[96:99], v[202:205], v[160:163], v[96:99]
	v_mfma_f32_16x16x32_bf16 v[88:91], v[184:187], v[168:171], v[88:91]
	v_mfma_f32_16x16x32_bf16 v[80:83], v[202:205], v[168:171], v[80:83]
	v_mfma_f32_16x16x32_bf16 v[72:75], v[184:187], v[176:179], v[72:75]
	v_mfma_f32_16x16x32_bf16 v[68:71], v[202:205], v[176:179], v[68:71]
	s_barrier
	s_setprio 0
	ds_read_b128 v[148:151], v224 offset:16384
	ds_read_b128 v[152:155], v224 offset:17408
	ds_read_b128 v[156:159], v224 offset:18432
	ds_read_b128 v[160:163], v224 offset:19456
	ds_read_b128 v[164:167], v224 offset:20480
	ds_read_b128 v[168:171], v224 offset:21504
	ds_read_b128 v[172:175], v224 offset:22528
	ds_read_b128 v[176:179], v224 offset:23552
	s_add_i32 s6, s45, s28
	v_lshl_add_u64 v[206:207], s[18:19], 0, v[2:3]
	s_mov_b32 m0, s6
	s_nop 0
	global_load_lds_dwordx4 v[206:207], off
	v_lshl_add_u64 v[208:209], s[18:19], 0, v[192:193]
	s_add_i32 m0, s6, 0x2000
	s_nop 0
	global_load_lds_dwordx4 v[208:209], off
	s_mov_b32 m0, s29
	v_lshl_add_u64 v[210:211], s[20:21], 0, v[196:197]
	global_load_lds_dwordx4 v[210:211], off
	v_lshl_add_u64 v[212:213], s[20:21], 0, v[194:195]
	s_mov_b32 m0, s30
	s_nop 0
	global_load_lds_dwordx4 v[212:213], off
	s_add_u32 s6, s18, 0x160000
	s_addc_u32 s7, s19, 0
	s_add_i32 s45, s51, s28
	s_mov_b32 m0, s45
	s_nop 0
	global_load_lds_dwordx4 v2, s[6:7]
	s_add_i32 m0, s45, 0x2000
	s_nop 0
	global_load_lds_dwordx4 v192, s[6:7]
	s_waitcnt lgkmcnt(0)
	s_waitcnt vmcnt(6)
	s_setprio 1
	s_barrier
	v_mfma_f32_16x16x32_bf16 v[64:67], v[132:135], v[148:151], 0
	v_mfma_f32_16x16x32_bf16 v[60:63], v[140:143], v[148:151], 0
	v_mfma_f32_16x16x32_bf16 v[52:55], v[132:135], v[156:159], 0
	v_mfma_f32_16x16x32_bf16 v[44:47], v[140:143], v[156:159], 0
	v_mfma_f32_16x16x32_bf16 v[36:39], v[132:135], v[164:167], 0
	v_mfma_f32_16x16x32_bf16 v[28:31], v[140:143], v[164:167], 0
	v_mfma_f32_16x16x32_bf16 v[20:23], v[132:135], v[172:175], 0
	v_mfma_f32_16x16x32_bf16 v[12:15], v[140:143], v[172:175], 0
	v_mfma_f32_16x16x32_bf16 v[64:67], v[136:139], v[152:155], v[64:67]
	v_mfma_f32_16x16x32_bf16 v[60:63], v[144:147], v[152:155], v[60:63]
	v_mfma_f32_16x16x32_bf16 v[52:55], v[136:139], v[160:163], v[52:55]
	v_mfma_f32_16x16x32_bf16 v[44:47], v[144:147], v[160:163], v[44:47]
	v_mfma_f32_16x16x32_bf16 v[36:39], v[136:139], v[168:171], v[36:39]
	v_mfma_f32_16x16x32_bf16 v[28:31], v[144:147], v[168:171], v[28:31]
	v_mfma_f32_16x16x32_bf16 v[20:23], v[136:139], v[176:179], v[20:23]
	v_mfma_f32_16x16x32_bf16 v[12:15], v[144:147], v[176:179], v[12:15]
	v_mfma_f32_16x16x32_bf16 v[56:59], v[180:183], v[148:151], 0
	v_mfma_f32_16x16x32_bf16 v[48:51], v[188:191], v[148:151], 0
	v_mfma_f32_16x16x32_bf16 v[40:43], v[180:183], v[156:159], 0
	v_mfma_f32_16x16x32_bf16 v[32:35], v[188:191], v[156:159], 0
	v_mfma_f32_16x16x32_bf16 v[24:27], v[180:183], v[164:167], 0
	v_mfma_f32_16x16x32_bf16 v[16:19], v[188:191], v[164:167], 0
	v_mfma_f32_16x16x32_bf16 v[8:11], v[180:183], v[172:175], 0
	v_mfma_f32_16x16x32_bf16 v[4:7], v[188:191], v[172:175], 0
	v_mfma_f32_16x16x32_bf16 v[56:59], v[184:187], v[152:155], v[56:59]
	v_mfma_f32_16x16x32_bf16 v[48:51], v[202:205], v[152:155], v[48:51]
	v_mfma_f32_16x16x32_bf16 v[40:43], v[184:187], v[160:163], v[40:43]
	v_mfma_f32_16x16x32_bf16 v[32:35], v[202:205], v[160:163], v[32:35]
	v_mfma_f32_16x16x32_bf16 v[24:27], v[184:187], v[168:171], v[24:27]
	v_mfma_f32_16x16x32_bf16 v[16:19], v[202:205], v[168:171], v[16:19]
	v_mfma_f32_16x16x32_bf16 v[8:11], v[184:187], v[176:179], v[8:11]
	v_mfma_f32_16x16x32_bf16 v[4:7], v[202:205], v[176:179], v[4:7]
	s_barrier
; #define PG8_STAGE(bufoff, gbase, voff) do { _Pragma("unroll") for (int _i = 0; _i < 2; ++_i) \
;         __builtin_amdgcn_global_load_lds((const unsigned*)((const char*)(gbase) + (voff)[_i]), (LAS unsigned*)(lds + (bufoff) + ldsw + _i * 8192), 16, 0, 0); } while (0)
; #define PG8_LDA(dst, b, h) do { _Pragma("unroll") for (int m = 0; m < 4; ++m) _Pragma("unroll") for (int k = 0; k < 2; ++k) dst[m][k] = *(const LAS bf16x8*)(lds + PG8_SA(b, h) + aoff + m * 2048 + k * 1024); } while (0)
; #define PG8_LDB(dst, b, h) do { _Pragma("unroll") for (int n = 0; n < 2; ++n) _Pragma("unroll") for (int k = 0; k < 2; ++k) dst[n][k] = *(const LAS bf16x8*)(lds + PG8_SB(b, h) + boff + n * 2048 + k * 1024); } while (0)
; #define PG8_MMA(ai, bj, At, Bt) do { __builtin_amdgcn_s_setprio(1); _Pragma("unroll") for (int m = 0; m < 4; ++m) _Pragma("unroll") for (int n = 0; n < 2; ++n) _Pragma("unroll") for (int k = 0; k < 2; ++k) \
;         acc[ai][bj][m][n] = __builtin_amdgcn_mfma_f32_16x16x32_bf16(Bt[n][k], At[m][k], acc[ai][bj][m][n], 0, 0, 0); __builtin_amdgcn_s_setprio(0); } while (0)
; #define PG8_WAIT_V(n) asm volatile("s_waitcnt vmcnt(" #n ")" ::: "memory")
; #define PG8_WAIT_L(n) asm volatile("s_waitcnt lgkmcnt(" #n ")" ::: "memory")
; #define PG8_BAR __builtin_amdgcn_s_barrier()
; #define PG8_SCHED __builtin_amdgcn_sched_barrier(0)
; template <class Epi, class Sched>
; __device__ __forceinline__ void gemm_phase(LAS unsigned char* lds, const Gemm g, const Sched& S, const Epi& E) {
;     ...
;             PG8_WAIT_V(6); PG8_BAR; PG8_MMA(1, 1, At, B1); PG8_BAR;
;             PG8_LDB(B0, 1, 0); PG8_SCHED; PG8_LDA(At, 1, 0); PG8_STAGE(PG8_SA(0, 1), a2 + hstepA, voffA);
;             PG8_WAIT_L(8); PG8_BAR; PG8_WAIT_L(0); PG8_MMA(0, 0, At, B0); PG8_BAR; PG8_SCHED;
;             PG8_LDB(B1, 1, 1); PG8_STAGE(PG8_SB(1, 0), b3, voffB);
;             PG8_BAR; PG8_WAIT_L(0); PG8_MMA(0, 1, At, B1); PG8_BAR;
;             PG8_LDA(At, 1, 1); PG8_STAGE(PG8_SA(1, 0), a3, voffA);
;             PG8_BAR; PG8_WAIT_L(0); PG8_MMA(1, 0, At, B0); PG8_BAR; PG8_SCHED;
;             PG8_STAGE(PG8_SB(1, 1), b3 + hstepB, voffB);
;             PG8_WAIT_V(6); PG8_BAR; PG8_MMA(1, 1, At, B1); PG8_BAR;
	s_setprio 0
	s_add_i32 s45, 0, 0x18000
	v_add_u32_e32 v144, s45, v1
	ds_read_b128 v[132:135], v144
	ds_read_b128 v[136:139], v144 offset:1024
	ds_read_b128 v[140:143], v144 offset:2048
	ds_read_b128 v[144:147], v144 offset:3072
	s_add_u32 s6, s20, 0x160000
	s_addc_u32 s7, s21, 0
	ds_read_b128 v[148:151], v224 offset:32768
	ds_read_b128 v[152:155], v224 offset:33792
	ds_read_b128 v[156:159], v224 offset:34816
	ds_read_b128 v[160:163], v224 offset:35840
	ds_read_b128 v[164:167], v224 offset:36864
	ds_read_b128 v[168:171], v224 offset:37888
	ds_read_b128 v[172:175], v224 offset:38912
	ds_read_b128 v[176:179], v224 offset:39936
	s_mov_b32 m0, s31
	s_nop 0
	global_load_lds_dwordx4 v196, s[6:7]
	s_mov_b32 m0, s35
	s_nop 0
	global_load_lds_dwordx4 v194, s[6:7]
	s_add_i32 s20, 0, 0x1c000
	v_add_u32_e32 v202, s20, v1
	ds_read_b128 v[180:183], v202
	ds_read_b128 v[184:187], v202 offset:1024
	ds_read_b128 v[188:191], v202 offset:2048
	ds_read_b128 v[202:205], v202 offset:3072
	s_waitcnt lgkmcnt(0)
	s_setprio 1
	s_barrier
	v_mfma_f32_16x16x32_bf16 v[128:131], v[132:135], v[148:151], v[128:131]
	v_mfma_f32_16x16x32_bf16 v[124:127], v[140:143], v[148:151], v[124:127]
	v_mfma_f32_16x16x32_bf16 v[112:115], v[132:135], v[156:159], v[112:115]
	v_mfma_f32_16x16x32_bf16 v[108:111], v[140:143], v[156:159], v[108:111]
	v_mfma_f32_16x16x32_bf16 v[100:103], v[132:135], v[164:167], v[100:103]
	v_mfma_f32_16x16x32_bf16 v[92:95], v[140:143], v[164:167], v[92:95]
	v_mfma_f32_16x16x32_bf16 v[84:87], v[132:135], v[172:175], v[84:87]
	v_mfma_f32_16x16x32_bf16 v[76:79], v[140:143], v[172:175], v[76:79]
	v_mfma_f32_16x16x32_bf16 v[128:131], v[136:139], v[152:155], v[128:131]
	v_mfma_f32_16x16x32_bf16 v[124:127], v[144:147], v[152:155], v[124:127]
	v_mfma_f32_16x16x32_bf16 v[112:115], v[136:139], v[160:163], v[112:115]
	v_mfma_f32_16x16x32_bf16 v[108:111], v[144:147], v[160:163], v[108:111]
	v_mfma_f32_16x16x32_bf16 v[100:103], v[136:139], v[168:171], v[100:103]
	v_mfma_f32_16x16x32_bf16 v[92:95], v[144:147], v[168:171], v[92:95]
	v_mfma_f32_16x16x32_bf16 v[84:87], v[136:139], v[176:179], v[84:87]
	v_mfma_f32_16x16x32_bf16 v[76:79], v[144:147], v[176:179], v[76:79]
	v_mfma_f32_16x16x32_bf16 v[120:123], v[180:183], v[148:151], v[120:123]
	v_mfma_f32_16x16x32_bf16 v[116:119], v[188:191], v[148:151], v[116:119]
	v_mfma_f32_16x16x32_bf16 v[104:107], v[180:183], v[156:159], v[104:107]
	v_mfma_f32_16x16x32_bf16 v[96:99], v[188:191], v[156:159], v[96:99]
	v_mfma_f32_16x16x32_bf16 v[88:91], v[180:183], v[164:167], v[88:91]
	v_mfma_f32_16x16x32_bf16 v[80:83], v[188:191], v[164:167], v[80:83]
	v_mfma_f32_16x16x32_bf16 v[72:75], v[180:183], v[172:175], v[72:75]
	v_mfma_f32_16x16x32_bf16 v[68:71], v[188:191], v[172:175], v[68:71]
	v_mfma_f32_16x16x32_bf16 v[120:123], v[184:187], v[152:155], v[120:123]
	v_mfma_f32_16x16x32_bf16 v[116:119], v[202:205], v[152:155], v[116:119]
	v_mfma_f32_16x16x32_bf16 v[104:107], v[184:187], v[160:163], v[104:107]
	v_mfma_f32_16x16x32_bf16 v[96:99], v[202:205], v[160:163], v[96:99]
	v_mfma_f32_16x16x32_bf16 v[88:91], v[184:187], v[168:171], v[88:91]
	v_mfma_f32_16x16x32_bf16 v[80:83], v[202:205], v[168:171], v[80:83]
	v_mfma_f32_16x16x32_bf16 v[72:75], v[184:187], v[176:179], v[72:75]
	v_mfma_f32_16x16x32_bf16 v[68:71], v[202:205], v[176:179], v[68:71]
	s_barrier
	s_setprio 0
	ds_read_b128 v[148:151], v224 offset:49152
	ds_read_b128 v[152:155], v224 offset:50176
	ds_read_b128 v[156:159], v224 offset:51200
	ds_read_b128 v[160:163], v224 offset:52224
	ds_read_b128 v[164:167], v224 offset:53248
	ds_read_b128 v[168:171], v224 offset:54272
	ds_read_b128 v[172:175], v224 offset:55296
	ds_read_b128 v[176:179], v224 offset:56320
	s_add_i32 s6, s45, s28
	v_lshl_add_u64 v[206:207], v[206:207], 0, s[8:9]
	s_mov_b32 m0, s6
	s_nop 0
	global_load_lds_dwordx4 v[206:207], off
	v_lshl_add_u64 v[206:207], v[208:209], 0, s[8:9]
	s_add_i32 m0, s6, 0x2000
	s_nop 0
	global_load_lds_dwordx4 v[206:207], off
	s_mov_b32 m0, s38
	v_lshl_add_u64 v[206:207], v[210:211], 0, s[8:9]
	global_load_lds_dwordx4 v[206:207], off
	v_lshl_add_u64 v[206:207], v[212:213], 0, s[8:9]
	s_mov_b32 m0, s39
	s_nop 0
	global_load_lds_dwordx4 v[206:207], off
	s_add_u32 s6, s18, 0x160080
	s_addc_u32 s7, s19, 0
	s_add_i32 s18, s20, s28
	s_mov_b32 m0, s18
	s_nop 0
	global_load_lds_dwordx4 v2, s[6:7]
	s_add_i32 m0, s18, 0x2000
	s_nop 0
	global_load_lds_dwordx4 v192, s[6:7]
	s_add_i32 s44, s44, 2
	s_add_u32 s42, s42, 0x100
	s_addc_u32 s43, s43, 0
	s_cmpk_gt_u32 s44, 0x55
	s_mov_b64 s[6:7], s[14:15]
	s_waitcnt lgkmcnt(0)
	s_waitcnt vmcnt(6)
	s_setprio 1
	s_barrier
	v_mfma_f32_16x16x32_bf16 v[64:67], v[132:135], v[148:151], v[64:67]
	v_mfma_f32_16x16x32_bf16 v[60:63], v[140:143], v[148:151], v[60:63]
	v_mfma_f32_16x16x32_bf16 v[52:55], v[132:135], v[156:159], v[52:55]
	v_mfma_f32_16x16x32_bf16 v[44:47], v[140:143], v[156:159], v[44:47]
	v_mfma_f32_16x16x32_bf16 v[36:39], v[132:135], v[164:167], v[36:39]
	v_mfma_f32_16x16x32_bf16 v[28:31], v[140:143], v[164:167], v[28:31]
	v_mfma_f32_16x16x32_bf16 v[20:23], v[132:135], v[172:175], v[20:23]
	v_mfma_f32_16x16x32_bf16 v[12:15], v[140:143], v[172:175], v[12:15]
	v_mfma_f32_16x16x32_bf16 v[64:67], v[136:139], v[152:155], v[64:67]
	v_mfma_f32_16x16x32_bf16 v[60:63], v[144:147], v[152:155], v[60:63]
	v_mfma_f32_16x16x32_bf16 v[52:55], v[136:139], v[160:163], v[52:55]
	v_mfma_f32_16x16x32_bf16 v[44:47], v[144:147], v[160:163], v[44:47]
	v_mfma_f32_16x16x32_bf16 v[36:39], v[136:139], v[168:171], v[36:39]
	v_mfma_f32_16x16x32_bf16 v[28:31], v[144:147], v[168:171], v[28:31]
	v_mfma_f32_16x16x32_bf16 v[20:23], v[136:139], v[176:179], v[20:23]
	v_mfma_f32_16x16x32_bf16 v[12:15], v[144:147], v[176:179], v[12:15]
	v_mfma_f32_16x16x32_bf16 v[56:59], v[180:183], v[148:151], v[56:59]
	v_mfma_f32_16x16x32_bf16 v[48:51], v[188:191], v[148:151], v[48:51]
	v_mfma_f32_16x16x32_bf16 v[40:43], v[180:183], v[156:159], v[40:43]
	v_mfma_f32_16x16x32_bf16 v[32:35], v[188:191], v[156:159], v[32:35]
	v_mfma_f32_16x16x32_bf16 v[24:27], v[180:183], v[164:167], v[24:27]
	v_mfma_f32_16x16x32_bf16 v[16:19], v[188:191], v[164:167], v[16:19]
	v_mfma_f32_16x16x32_bf16 v[8:11], v[180:183], v[172:175], v[8:11]
	v_mfma_f32_16x16x32_bf16 v[4:7], v[188:191], v[172:175], v[4:7]
	v_mfma_f32_16x16x32_bf16 v[56:59], v[184:187], v[152:155], v[56:59]
	v_mfma_f32_16x16x32_bf16 v[48:51], v[202:205], v[152:155], v[48:51]
	v_mfma_f32_16x16x32_bf16 v[40:43], v[184:187], v[160:163], v[40:43]
	v_mfma_f32_16x16x32_bf16 v[32:35], v[202:205], v[160:163], v[32:35]
	v_mfma_f32_16x16x32_bf16 v[24:27], v[184:187], v[168:171], v[24:27]
	v_mfma_f32_16x16x32_bf16 v[16:19], v[202:205], v[168:171], v[16:19]
	v_mfma_f32_16x16x32_bf16 v[8:11], v[184:187], v[176:179], v[8:11]
	v_mfma_f32_16x16x32_bf16 v[4:7], v[202:205], v[176:179], v[4:7]
	s_barrier
	s_setprio 0
	.p2align	6
